# speedup vs baseline: 1.0023x; 1.0023x over previous
; #define LDA(dst, b, h)                                                                                     \
;   _Pragma("unroll") for (int m = 0; m < 4; ++m) _Pragma("unroll") for (int k = 0; k < 2; ++k) dst[m][k] = \
;       *reinterpret_cast<const bf16x8*>(shmc + aL + (((b) * 2 + (h)) * 16384 + (m * 2 + k) * 1024))
; #define LDB(dst, b, h)                                                                                     \
;   _Pragma("unroll") for (int n = 0; n < 2; ++n) _Pragma("unroll") for (int k = 0; k < 2; ++k) dst[n][k] = \
;       *reinterpret_cast<const bf16x8*>(shmc + bL + (((b) * 2 + (h)) * 16384 + (n * 2 + k) * 1024))
; #define OPAQ asm volatile("" : "+v"(aL), "+v"(bL))
; #define WAIT_V(n) asm volatile("s_waitcnt vmcnt(" #n ")" ::: "memory")
; #define WAIT_L(n) asm volatile("s_waitcnt lgkmcnt(" #n ")" ::: "memory")
; #define BAR __builtin_amdgcn_s_barrier()
; #define SCHED __builtin_amdgcn_sched_barrier(0)
; template <int EPI>
; __device__ __forceinline__ void phase_gemm(const Params& p, const GemmDesc& d, char* shmc) {
;     ...
;     for (int t = 0; t < nt - 2; t += 2) {
;       OPAQ;
;       LDB(B0, 0, 0); SCHED; LDA(At, 0, 0); STAGE_A(SA(1, 1), 1, t + 1);
;       WAIT_L(8); BAR; WAIT_L(0); MMA(0, 0, At, B0); BAR; SCHED;
;       LDB(B1, 0, 1); STAGE_B(SB(0, 0), 0, t + 2);
;       BAR; WAIT_L(0); MMA(0, 1, At, B1); BAR;
;       LDA(At, 0, 1); STAGE_A(SA(0, 0), 0, t + 2);
;       BAR; WAIT_L(0); MMA(1, 0, At, B0); BAR; SCHED;
;       STAGE_B(SB(0, 1), 1, t + 2);
;       WAIT_V(6); BAR; MMA(1, 1, At, B1); BAR;
.LBB0_296:
	s_nop 0
	s_setprio 0
	ds_read_b128 v[138:141], v205
	ds_read_b128 v[142:145], v205 offset:1024
	ds_read_b128 v[146:149], v205 offset:2048
	ds_read_b128 v[150:153], v205 offset:3072
	ds_read_b128 v[208:211], v205 offset:16384
	ds_read_b128 v[212:215], v205 offset:17408
	ds_read_b128 v[216:219], v205 offset:18432
	ds_read_b128 v[220:223], v205 offset:19456
	ds_read_b128 v[154:157], v204
	ds_read_b128 v[158:161], v204 offset:1024
	ds_read_b128 v[178:181], v204 offset:2048
	ds_read_b128 v[182:185], v204 offset:3072
	ds_read_b128 v[186:189], v204 offset:4096
	ds_read_b128 v[190:193], v204 offset:5120
	ds_read_b128 v[194:197], v204 offset:6144
	ds_read_b128 v[198:201], v204 offset:7168
	s_mov_b32 m0, s93
	s_nop 0
	global_load_lds_dwordx4 v202, s[98:99]
	s_mov_b32 m0, s94
	s_nop 0
	global_load_lds_dwordx4 v203, s[98:99]
	s_waitcnt vmcnt(8)
	s_waitcnt lgkmcnt(0)
	s_setprio 1
	s_barrier
	v_mfma_f32_16x16x32_bf16 v[2:5], v[154:157], v[138:141], v[2:5]
	v_mfma_f32_16x16x32_bf16 v[6:9], v[154:157], v[146:149], v[6:9]
	v_mfma_f32_16x16x32_bf16 v[10:13], v[178:181], v[138:141], v[10:13]
	v_mfma_f32_16x16x32_bf16 v[18:21], v[178:181], v[146:149], v[18:21]
	v_mfma_f32_16x16x32_bf16 v[30:33], v[186:189], v[138:141], v[30:33]
	v_mfma_f32_16x16x32_bf16 v[42:45], v[186:189], v[146:149], v[42:45]
	v_mfma_f32_16x16x32_bf16 v[54:57], v[194:197], v[138:141], v[54:57]
	v_mfma_f32_16x16x32_bf16 v[66:69], v[194:197], v[146:149], v[66:69]
	v_mfma_f32_16x16x32_bf16 v[2:5], v[158:161], v[142:145], v[2:5]
	v_mfma_f32_16x16x32_bf16 v[6:9], v[158:161], v[150:153], v[6:9]
	v_mfma_f32_16x16x32_bf16 v[10:13], v[182:185], v[142:145], v[10:13]
	v_mfma_f32_16x16x32_bf16 v[18:21], v[182:185], v[150:153], v[18:21]
	v_mfma_f32_16x16x32_bf16 v[30:33], v[190:193], v[142:145], v[30:33]
	v_mfma_f32_16x16x32_bf16 v[42:45], v[190:193], v[150:153], v[42:45]
	v_mfma_f32_16x16x32_bf16 v[54:57], v[198:201], v[142:145], v[54:57]
	v_mfma_f32_16x16x32_bf16 v[66:69], v[198:201], v[150:153], v[66:69]
	v_mfma_f32_16x16x32_bf16 v[14:17], v[154:157], v[208:211], v[14:17]
	v_mfma_f32_16x16x32_bf16 v[22:25], v[154:157], v[216:219], v[22:25]
	v_mfma_f32_16x16x32_bf16 v[34:37], v[178:181], v[208:211], v[34:37]
	v_mfma_f32_16x16x32_bf16 v[46:49], v[178:181], v[216:219], v[46:49]
	v_mfma_f32_16x16x32_bf16 v[58:61], v[186:189], v[208:211], v[58:61]
	v_mfma_f32_16x16x32_bf16 v[70:73], v[186:189], v[216:219], v[70:73]
	v_mfma_f32_16x16x32_bf16 v[78:81], v[194:197], v[208:211], v[78:81]
	v_mfma_f32_16x16x32_bf16 v[86:89], v[194:197], v[216:219], v[86:89]
	v_mfma_f32_16x16x32_bf16 v[14:17], v[158:161], v[212:215], v[14:17]
	v_mfma_f32_16x16x32_bf16 v[22:25], v[158:161], v[220:223], v[22:25]
	v_mfma_f32_16x16x32_bf16 v[34:37], v[182:185], v[212:215], v[34:37]
	v_mfma_f32_16x16x32_bf16 v[46:49], v[182:185], v[220:223], v[46:49]
	v_mfma_f32_16x16x32_bf16 v[58:61], v[190:193], v[212:215], v[58:61]
	v_mfma_f32_16x16x32_bf16 v[70:73], v[190:193], v[220:223], v[70:73]
	v_mfma_f32_16x16x32_bf16 v[78:81], v[198:201], v[212:215], v[78:81]
	v_mfma_f32_16x16x32_bf16 v[86:89], v[198:201], v[220:223], v[86:89]
	s_barrier
	s_setprio 0
	ds_read_b128 v[154:157], v204 offset:16384
	ds_read_b128 v[158:161], v204 offset:17408
	ds_read_b128 v[178:181], v204 offset:18432
	ds_read_b128 v[182:185], v204 offset:19456
	ds_read_b128 v[186:189], v204 offset:20480
	ds_read_b128 v[190:193], v204 offset:21504
	ds_read_b128 v[194:197], v204 offset:22528
	ds_read_b128 v[198:201], v204 offset:23552
	s_mov_b32 m0, s80
	s_nop 0
	global_load_lds_dwordx4 v224, s[100:101]
	s_mov_b32 m0, s81
	s_nop 0
	global_load_lds_dwordx4 v225, s[100:101]
	s_mov_b32 m0, s77
	s_nop 0
	global_load_lds_dwordx4 v226, s[98:99]
	s_mov_b32 m0, s82
	s_nop 0
	global_load_lds_dwordx4 v227, s[98:99]
	s_mov_b32 m0, s83
	s_nop 0
	global_load_lds_dwordx4 v228, s[100:101]
	s_mov_b32 m0, s84
	s_nop 0
	global_load_lds_dwordx4 v229, s[100:101]
	s_waitcnt vmcnt(8)
	s_waitcnt lgkmcnt(0)
	s_setprio 1
	s_barrier
	v_mfma_f32_16x16x32_bf16 v[26:29], v[154:157], v[138:141], v[26:29]
	v_mfma_f32_16x16x32_bf16 v[38:41], v[154:157], v[146:149], v[38:41]
	v_mfma_f32_16x16x32_bf16 v[50:53], v[178:181], v[138:141], v[50:53]
	v_mfma_f32_16x16x32_bf16 v[62:65], v[178:181], v[146:149], v[62:65]
	v_mfma_f32_16x16x32_bf16 v[74:77], v[186:189], v[138:141], v[74:77]
	v_mfma_f32_16x16x32_bf16 v[82:85], v[186:189], v[146:149], v[82:85]
	v_mfma_f32_16x16x32_bf16 v[90:93], v[194:197], v[138:141], v[90:93]
	v_mfma_f32_16x16x32_bf16 v[94:97], v[194:197], v[146:149], v[94:97]
	v_mfma_f32_16x16x32_bf16 v[26:29], v[158:161], v[142:145], v[26:29]
	v_mfma_f32_16x16x32_bf16 v[38:41], v[158:161], v[150:153], v[38:41]
	v_mfma_f32_16x16x32_bf16 v[50:53], v[182:185], v[142:145], v[50:53]
	v_mfma_f32_16x16x32_bf16 v[62:65], v[182:185], v[150:153], v[62:65]
	v_mfma_f32_16x16x32_bf16 v[74:77], v[190:193], v[142:145], v[74:77]
	v_mfma_f32_16x16x32_bf16 v[82:85], v[190:193], v[150:153], v[82:85]
	v_mfma_f32_16x16x32_bf16 v[90:93], v[198:201], v[142:145], v[90:93]
	v_mfma_f32_16x16x32_bf16 v[94:97], v[198:201], v[150:153], v[94:97]
	v_mfma_f32_16x16x32_bf16 v[98:101], v[154:157], v[208:211], v[98:101]
	v_mfma_f32_16x16x32_bf16 v[102:105], v[154:157], v[216:219], v[102:105]
	v_mfma_f32_16x16x32_bf16 v[106:109], v[178:181], v[208:211], v[106:109]
	v_mfma_f32_16x16x32_bf16 v[110:113], v[178:181], v[216:219], v[110:113]
	v_mfma_f32_16x16x32_bf16 v[114:117], v[186:189], v[208:211], v[114:117]
	v_mfma_f32_16x16x32_bf16 v[118:121], v[186:189], v[216:219], v[118:121]
	v_mfma_f32_16x16x32_bf16 v[122:125], v[194:197], v[208:211], v[122:125]
	v_mfma_f32_16x16x32_bf16 v[126:129], v[194:197], v[216:219], v[126:129]
	v_mfma_f32_16x16x32_bf16 v[98:101], v[158:161], v[212:215], v[98:101]
	v_mfma_f32_16x16x32_bf16 v[102:105], v[158:161], v[220:223], v[102:105]
	v_mfma_f32_16x16x32_bf16 v[106:109], v[182:185], v[212:215], v[106:109]
	v_mfma_f32_16x16x32_bf16 v[110:113], v[182:185], v[220:223], v[110:113]
	v_mfma_f32_16x16x32_bf16 v[114:117], v[190:193], v[212:215], v[114:117]
	v_mfma_f32_16x16x32_bf16 v[118:121], v[190:193], v[220:223], v[118:121]
	v_mfma_f32_16x16x32_bf16 v[122:125], v[198:201], v[212:215], v[122:125]
	v_mfma_f32_16x16x32_bf16 v[126:129], v[198:201], v[220:223], v[126:129]
	s_barrier
; #define LDA(dst, b, h)                                                                                     \
;   _Pragma("unroll") for (int m = 0; m < 4; ++m) _Pragma("unroll") for (int k = 0; k < 2; ++k) dst[m][k] = \
;       *reinterpret_cast<const bf16x8*>(shmc + aL + (((b) * 2 + (h)) * 16384 + (m * 2 + k) * 1024))
; #define LDB(dst, b, h)                                                                                     \
;   _Pragma("unroll") for (int n = 0; n < 2; ++n) _Pragma("unroll") for (int k = 0; k < 2; ++k) dst[n][k] = \
;       *reinterpret_cast<const bf16x8*>(shmc + bL + (((b) * 2 + (h)) * 16384 + (n * 2 + k) * 1024))
; #define WAIT_V(n) asm volatile("s_waitcnt vmcnt(" #n ")" ::: "memory")
; #define WAIT_L(n) asm volatile("s_waitcnt lgkmcnt(" #n ")" ::: "memory")
; #define BAR __builtin_amdgcn_s_barrier()
; #define SCHED __builtin_amdgcn_sched_barrier(0)
; template <int EPI>
; __device__ __forceinline__ void phase_gemm(const Params& p, const GemmDesc& d, char* shmc) {
;     ...
;       LDB(B0, 1, 0); SCHED; LDA(At, 1, 0); STAGE_A(SA(0, 1), 1, t + 2);
;       WAIT_L(8); BAR; WAIT_L(0); MMA(0, 0, At, B0); BAR; SCHED;
;       LDB(B1, 1, 1); STAGE_B(SB(1, 0), 0, t + 3);
;       BAR; WAIT_L(0); MMA(0, 1, At, B1); BAR;
;       LDA(At, 1, 1); STAGE_A(SA(1, 0), 0, t + 3);
;       BAR; WAIT_L(0); MMA(1, 0, At, B0); BAR; SCHED;
;       STAGE_B(SB(1, 1), 1, t + 3);
;       WAIT_V(6); BAR; MMA(1, 1, At, B1); BAR;
	s_setprio 0
	ds_read_b128 v[138:141], v205 offset:32768
	ds_read_b128 v[142:145], v205 offset:33792
	ds_read_b128 v[146:149], v205 offset:34816
	ds_read_b128 v[150:153], v205 offset:35840
	ds_read_b128 v[208:211], v205 offset:49152
	ds_read_b128 v[212:215], v205 offset:50176
	ds_read_b128 v[216:219], v205 offset:51200
	ds_read_b128 v[220:223], v205 offset:52224
	ds_read_b128 v[154:157], v204 offset:32768
	ds_read_b128 v[158:161], v204 offset:33792
	ds_read_b128 v[178:181], v204 offset:34816
	ds_read_b128 v[182:185], v204 offset:35840
	ds_read_b128 v[186:189], v204 offset:36864
	ds_read_b128 v[190:193], v204 offset:37888
	ds_read_b128 v[194:197], v204 offset:38912
	ds_read_b128 v[198:201], v204 offset:39936
	s_mov_b32 m0, s85
	s_nop 0
	global_load_lds_dwordx4 v230, s[98:99]
	s_mov_b32 m0, s86
	s_nop 0
	global_load_lds_dwordx4 v231, s[98:99]
	s_waitcnt vmcnt(8)
	s_waitcnt lgkmcnt(0)
	s_setprio 1
	s_barrier
	v_mfma_f32_16x16x32_bf16 v[2:5], v[154:157], v[138:141], v[2:5]
	v_mfma_f32_16x16x32_bf16 v[6:9], v[154:157], v[146:149], v[6:9]
	v_mfma_f32_16x16x32_bf16 v[10:13], v[178:181], v[138:141], v[10:13]
	v_mfma_f32_16x16x32_bf16 v[18:21], v[178:181], v[146:149], v[18:21]
	v_mfma_f32_16x16x32_bf16 v[30:33], v[186:189], v[138:141], v[30:33]
	v_mfma_f32_16x16x32_bf16 v[42:45], v[186:189], v[146:149], v[42:45]
	v_mfma_f32_16x16x32_bf16 v[54:57], v[194:197], v[138:141], v[54:57]
	v_mfma_f32_16x16x32_bf16 v[66:69], v[194:197], v[146:149], v[66:69]
	v_mfma_f32_16x16x32_bf16 v[2:5], v[158:161], v[142:145], v[2:5]
	v_mfma_f32_16x16x32_bf16 v[6:9], v[158:161], v[150:153], v[6:9]
	v_mfma_f32_16x16x32_bf16 v[10:13], v[182:185], v[142:145], v[10:13]
	v_mfma_f32_16x16x32_bf16 v[18:21], v[182:185], v[150:153], v[18:21]
	v_mfma_f32_16x16x32_bf16 v[30:33], v[190:193], v[142:145], v[30:33]
	v_mfma_f32_16x16x32_bf16 v[42:45], v[190:193], v[150:153], v[42:45]
	v_mfma_f32_16x16x32_bf16 v[54:57], v[198:201], v[142:145], v[54:57]
	v_mfma_f32_16x16x32_bf16 v[66:69], v[198:201], v[150:153], v[66:69]
	v_mfma_f32_16x16x32_bf16 v[14:17], v[154:157], v[208:211], v[14:17]
	v_mfma_f32_16x16x32_bf16 v[22:25], v[154:157], v[216:219], v[22:25]
	v_mfma_f32_16x16x32_bf16 v[34:37], v[178:181], v[208:211], v[34:37]
	v_mfma_f32_16x16x32_bf16 v[46:49], v[178:181], v[216:219], v[46:49]
	v_mfma_f32_16x16x32_bf16 v[58:61], v[186:189], v[208:211], v[58:61]
	v_mfma_f32_16x16x32_bf16 v[70:73], v[186:189], v[216:219], v[70:73]
	v_mfma_f32_16x16x32_bf16 v[78:81], v[194:197], v[208:211], v[78:81]
	v_mfma_f32_16x16x32_bf16 v[86:89], v[194:197], v[216:219], v[86:89]
	v_mfma_f32_16x16x32_bf16 v[14:17], v[158:161], v[212:215], v[14:17]
	v_mfma_f32_16x16x32_bf16 v[22:25], v[158:161], v[220:223], v[22:25]
	v_mfma_f32_16x16x32_bf16 v[34:37], v[182:185], v[212:215], v[34:37]
	v_mfma_f32_16x16x32_bf16 v[46:49], v[182:185], v[220:223], v[46:49]
	v_mfma_f32_16x16x32_bf16 v[58:61], v[190:193], v[212:215], v[58:61]
	v_mfma_f32_16x16x32_bf16 v[70:73], v[190:193], v[220:223], v[70:73]
	v_mfma_f32_16x16x32_bf16 v[78:81], v[198:201], v[212:215], v[78:81]
	v_mfma_f32_16x16x32_bf16 v[86:89], v[198:201], v[220:223], v[86:89]
	s_barrier
	s_setprio 0
	ds_read_b128 v[154:157], v204 offset:49152
	ds_read_b128 v[158:161], v204 offset:50176
	ds_read_b128 v[178:181], v204 offset:51200
	ds_read_b128 v[182:185], v204 offset:52224
	ds_read_b128 v[186:189], v204 offset:53248
	ds_read_b128 v[190:193], v204 offset:54272
	ds_read_b128 v[194:197], v204 offset:55296
	ds_read_b128 v[198:201], v204 offset:56320
	s_mov_b32 m0, s87
	s_nop 0
	global_load_lds_dwordx4 v232, s[100:101]
	s_mov_b32 m0, s88
	s_nop 0
	global_load_lds_dwordx4 v233, s[100:101]
	s_mov_b32 m0, s89
	s_nop 0
	global_load_lds_dwordx4 v234, s[98:99]
	s_mov_b32 m0, s90
	s_nop 0
	global_load_lds_dwordx4 v235, s[98:99]
	s_mov_b32 m0, s91
	s_nop 0
	global_load_lds_dwordx4 v236, s[100:101]
	s_mov_b32 m0, s92
	s_nop 0
	global_load_lds_dwordx4 v237, s[100:101]
	s_add_i32 s35, s35, 2
	s_add_u32 s10, s10, 0x100
	s_addc_u32 s11, s11, 0
	s_add_u32 s98, s98, 0x100
	s_addc_u32 s99, s99, 0
	s_add_u32 s100, s100, 0x100
	s_addc_u32 s101, s101, 0
	s_cmp_gt_u32 s35, 27
	s_waitcnt vmcnt(8)
	s_waitcnt lgkmcnt(0)
	s_setprio 1
	s_barrier
	v_mfma_f32_16x16x32_bf16 v[26:29], v[154:157], v[138:141], v[26:29]
	v_mfma_f32_16x16x32_bf16 v[38:41], v[154:157], v[146:149], v[38:41]
	v_mfma_f32_16x16x32_bf16 v[50:53], v[178:181], v[138:141], v[50:53]
	v_mfma_f32_16x16x32_bf16 v[62:65], v[178:181], v[146:149], v[62:65]
	v_mfma_f32_16x16x32_bf16 v[74:77], v[186:189], v[138:141], v[74:77]
	v_mfma_f32_16x16x32_bf16 v[82:85], v[186:189], v[146:149], v[82:85]
	v_mfma_f32_16x16x32_bf16 v[90:93], v[194:197], v[138:141], v[90:93]
	v_mfma_f32_16x16x32_bf16 v[94:97], v[194:197], v[146:149], v[94:97]
	v_mfma_f32_16x16x32_bf16 v[26:29], v[158:161], v[142:145], v[26:29]
	v_mfma_f32_16x16x32_bf16 v[38:41], v[158:161], v[150:153], v[38:41]
	v_mfma_f32_16x16x32_bf16 v[50:53], v[182:185], v[142:145], v[50:53]
	v_mfma_f32_16x16x32_bf16 v[62:65], v[182:185], v[150:153], v[62:65]
	v_mfma_f32_16x16x32_bf16 v[74:77], v[190:193], v[142:145], v[74:77]
	v_mfma_f32_16x16x32_bf16 v[82:85], v[190:193], v[150:153], v[82:85]
	v_mfma_f32_16x16x32_bf16 v[90:93], v[198:201], v[142:145], v[90:93]
	v_mfma_f32_16x16x32_bf16 v[94:97], v[198:201], v[150:153], v[94:97]
	v_mfma_f32_16x16x32_bf16 v[98:101], v[154:157], v[208:211], v[98:101]
	v_mfma_f32_16x16x32_bf16 v[102:105], v[154:157], v[216:219], v[102:105]
	v_mfma_f32_16x16x32_bf16 v[106:109], v[178:181], v[208:211], v[106:109]
	v_mfma_f32_16x16x32_bf16 v[110:113], v[178:181], v[216:219], v[110:113]
	v_mfma_f32_16x16x32_bf16 v[114:117], v[186:189], v[208:211], v[114:117]
	v_mfma_f32_16x16x32_bf16 v[118:121], v[186:189], v[216:219], v[118:121]
	v_mfma_f32_16x16x32_bf16 v[122:125], v[194:197], v[208:211], v[122:125]
	v_mfma_f32_16x16x32_bf16 v[126:129], v[194:197], v[216:219], v[126:129]
	v_mfma_f32_16x16x32_bf16 v[98:101], v[158:161], v[212:215], v[98:101]
	v_mfma_f32_16x16x32_bf16 v[102:105], v[158:161], v[220:223], v[102:105]
	v_mfma_f32_16x16x32_bf16 v[106:109], v[182:185], v[212:215], v[106:109]
	v_mfma_f32_16x16x32_bf16 v[110:113], v[182:185], v[220:223], v[110:113]
	v_mfma_f32_16x16x32_bf16 v[114:117], v[190:193], v[212:215], v[114:117]
	v_mfma_f32_16x16x32_bf16 v[118:121], v[190:193], v[220:223], v[118:121]
	v_mfma_f32_16x16x32_bf16 v[122:125], v[198:201], v[212:215], v[122:125]
	v_mfma_f32_16x16x32_bf16 v[126:129], v[198:201], v[220:223], v[126:129]
	s_barrier
; #define LDA(dst, b, h)                                                                                     \
;   _Pragma("unroll") for (int m = 0; m < 4; ++m) _Pragma("unroll") for (int k = 0; k < 2; ++k) dst[m][k] = \
;       *reinterpret_cast<const bf16x8*>(shmc + aL + (((b) * 2 + (h)) * 16384 + (m * 2 + k) * 1024))
; #define LDB(dst, b, h)                                                                                     \
;   _Pragma("unroll") for (int n = 0; n < 2; ++n) _Pragma("unroll") for (int k = 0; k < 2; ++k) dst[n][k] = \
;       *reinterpret_cast<const bf16x8*>(shmc + bL + (((b) * 2 + (h)) * 16384 + (n * 2 + k) * 1024))
; #define OPAQ asm volatile("" : "+v"(aL), "+v"(bL))
; #define WAIT_V(n) asm volatile("s_waitcnt vmcnt(" #n ")" ::: "memory")
; #define WAIT_L(n) asm volatile("s_waitcnt lgkmcnt(" #n ")" ::: "memory")
; #define BAR __builtin_amdgcn_s_barrier()
; template <int EPI>
; __device__ __forceinline__ void phase_gemm(const Params& p, const GemmDesc& d, char* shmc) {
;     ...
;     {
;       OPAQ;
;       LDB(B0, 0, 0); LDA(At, 0, 0); STAGE_A(SA(1, 1), 1, nt - 1);
;       BAR; WAIT_L(0); MMA(0, 0, At, B0); BAR;
;       LDB(B1, 0, 1); BAR; WAIT_L(0); MMA(0, 1, At, B1); BAR;
;       LDA(At, 0, 1); WAIT_V(4); BAR; WAIT_L(0); MMA(1, 0, At, B0); MMA(1, 1, At, B1); BAR;
;     }
	s_cbranch_scc0 .LBB0_296
	s_setprio 0
	s_add_u32 s8, s8, 0x80f80
	s_addc_u32 s9, s9, 0
	v_add_u32_e32 v162, 0, v205
	v_add_u32_e32 v175, 0, v204
	s_mov_b32 m0, s93
	ds_read_b128 v[130:133], v162
	ds_read_b128 v[134:137], v162 offset:1024
	ds_read_b128 v[138:141], v162 offset:2048
	ds_read_b128 v[142:145], v162 offset:3072
	ds_read_b128 v[146:149], v175
	ds_read_b128 v[150:153], v175 offset:1024
	ds_read_b128 v[154:157], v175 offset:2048
	ds_read_b128 v[158:161], v175 offset:3072
	ds_read_b128 v[178:181], v175 offset:4096
	ds_read_b128 v[182:185], v175 offset:5120
	ds_read_b128 v[186:189], v175 offset:6144
	ds_read_b128 v[190:193], v175 offset:7168
	global_load_lds_dwordx4 v174, s[8:9]
	s_mov_b32 m0, s94
	s_nop 0
	global_load_lds_dwordx4 v176, s[8:9]
	s_waitcnt vmcnt(8)
	s_barrier
	s_waitcnt lgkmcnt(0)
	s_setprio 1
	s_waitcnt lgkmcnt(0)
	v_mfma_f32_16x16x32_bf16 v[2:5], v[146:149], v[130:133], v[2:5]
	v_mfma_f32_16x16x32_bf16 v[6:9], v[146:149], v[138:141], v[6:9]
	v_mfma_f32_16x16x32_bf16 v[10:13], v[154:157], v[130:133], v[10:13]
	v_mfma_f32_16x16x32_bf16 v[18:21], v[154:157], v[138:141], v[18:21]
	v_mfma_f32_16x16x32_bf16 v[66:69], v[186:189], v[138:141], v[66:69]
	v_mfma_f32_16x16x32_bf16 v[2:5], v[150:153], v[134:137], v[2:5]
	v_mfma_f32_16x16x32_bf16 v[6:9], v[150:153], v[142:145], v[6:9]
	v_mfma_f32_16x16x32_bf16 v[10:13], v[158:161], v[134:137], v[10:13]
	v_mfma_f32_16x16x32_bf16 v[18:21], v[158:161], v[142:145], v[18:21]
	v_mfma_f32_16x16x32_bf16 v[30:33], v[178:181], v[130:133], v[30:33]
	v_mfma_f32_16x16x32_bf16 v[42:45], v[178:181], v[138:141], v[42:45]
	v_mfma_f32_16x16x32_bf16 v[54:57], v[186:189], v[130:133], v[54:57]
	v_mfma_f32_16x16x32_bf16 v[66:69], v[190:193], v[142:145], v[66:69]
	v_mfma_f32_16x16x32_bf16 v[30:33], v[182:185], v[134:137], v[30:33]
	v_mfma_f32_16x16x32_bf16 v[42:45], v[182:185], v[142:145], v[42:45]
	v_mfma_f32_16x16x32_bf16 v[54:57], v[190:193], v[134:137], v[54:57]
	s_setprio 0
	s_barrier
	ds_read_b128 v[194:197], v162 offset:16384
	ds_read_b128 v[198:201], v162 offset:17408
	ds_read_b128 v[208:211], v162 offset:18432
	ds_read_b128 v[212:215], v162 offset:19456
	s_barrier
	s_waitcnt lgkmcnt(0)
	s_setprio 1
	s_waitcnt lgkmcnt(0)
	v_mfma_f32_16x16x32_bf16 v[14:17], v[146:149], v[194:197], v[14:17]
	v_mfma_f32_16x16x32_bf16 v[22:25], v[146:149], v[208:211], v[22:25]
	v_mfma_f32_16x16x32_bf16 v[58:61], v[178:181], v[194:197], v[58:61]
	v_mfma_f32_16x16x32_bf16 v[14:17], v[150:153], v[198:201], v[14:17]
	v_mfma_f32_16x16x32_bf16 v[22:25], v[150:153], v[212:215], v[22:25]
	v_mfma_f32_16x16x32_bf16 v[150:153], v[182:185], v[198:201], v[58:61]
	v_mfma_f32_16x16x32_bf16 v[58:61], v[178:181], v[208:211], v[70:73]
	v_mfma_f32_16x16x32_bf16 v[34:37], v[154:157], v[194:197], v[34:37]
	v_mfma_f32_16x16x32_bf16 v[46:49], v[154:157], v[208:211], v[46:49]
	v_mfma_f32_16x16x32_bf16 v[154:157], v[182:185], v[212:215], v[58:61]
	v_mfma_f32_16x16x32_bf16 v[58:61], v[186:189], v[194:197], v[78:81]
	v_mfma_f32_16x16x32_bf16 v[78:81], v[190:193], v[198:201], v[58:61]
	v_mfma_f32_16x16x32_bf16 v[58:61], v[186:189], v[208:211], v[86:89]
	v_mfma_f32_16x16x32_bf16 v[86:89], v[190:193], v[212:215], v[58:61]
	v_mfma_f32_16x16x32_bf16 v[34:37], v[158:161], v[198:201], v[34:37]
	v_mfma_f32_16x16x32_bf16 v[46:49], v[158:161], v[212:215], v[46:49]
	s_setprio 0
	s_barrier
	s_nop 2
	ds_read_b128 v[58:61], v175 offset:16384
	ds_read_b128 v[70:73], v175 offset:17408
	ds_read_b128 v[146:149], v175 offset:18432
	ds_read_b128 v[158:161], v175 offset:19456
	ds_read_b128 v[178:181], v175 offset:20480
	ds_read_b128 v[182:185], v175 offset:21504
	ds_read_b128 v[186:189], v175 offset:22528
	ds_read_b128 v[190:193], v175 offset:23552
	s_waitcnt vmcnt(4)
	s_barrier
	s_waitcnt lgkmcnt(0)
	s_setprio 1
	s_waitcnt lgkmcnt(0)
	v_mfma_f32_16x16x32_bf16 v[74:77], v[178:181], v[130:133], v[74:77]
	v_mfma_f32_16x16x32_bf16 v[216:219], v[182:185], v[134:137], v[74:77]
	v_mfma_f32_16x16x32_bf16 v[74:77], v[178:181], v[138:141], v[82:85]
	v_mfma_f32_16x16x32_bf16 v[26:29], v[58:61], v[130:133], v[26:29]
	v_mfma_f32_16x16x32_bf16 v[82:85], v[182:185], v[142:145], v[74:77]
	v_mfma_f32_16x16x32_bf16 v[74:77], v[186:189], v[130:133], v[90:93]
	v_mfma_f32_16x16x32_bf16 v[26:29], v[70:73], v[134:137], v[26:29]
	v_mfma_f32_16x16x32_bf16 v[38:41], v[58:61], v[138:141], v[38:41]
	v_mfma_f32_16x16x32_bf16 v[50:53], v[146:149], v[130:133], v[50:53]
	v_mfma_f32_16x16x32_bf16 v[62:65], v[146:149], v[138:141], v[62:65]
	v_mfma_f32_16x16x32_bf16 v[90:93], v[190:193], v[134:137], v[74:77]
	v_mfma_f32_16x16x32_bf16 v[74:77], v[186:189], v[138:141], v[94:97]
	v_mfma_f32_16x16x32_bf16 v[38:41], v[70:73], v[142:145], v[38:41]
	v_mfma_f32_16x16x32_bf16 v[50:53], v[158:161], v[134:137], v[50:53]
	v_mfma_f32_16x16x32_bf16 v[62:65], v[158:161], v[142:145], v[62:65]
	v_mfma_f32_16x16x32_bf16 v[220:223], v[190:193], v[142:145], v[74:77]
	s_setprio 0
	s_setprio 1
	v_mfma_f32_16x16x32_bf16 v[74:77], v[58:61], v[194:197], v[98:101]
	v_mfma_f32_16x16x32_bf16 v[58:61], v[58:61], v[208:211], v[102:105]
	v_mfma_f32_16x16x32_bf16 v[228:231], v[70:73], v[212:215], v[58:61]
	v_mfma_f32_16x16x32_bf16 v[58:61], v[146:149], v[194:197], v[106:109]
	v_mfma_f32_16x16x32_bf16 v[232:235], v[158:161], v[198:201], v[58:61]
	v_mfma_f32_16x16x32_bf16 v[58:61], v[146:149], v[208:211], v[110:113]
	v_mfma_f32_16x16x32_bf16 v[236:239], v[158:161], v[212:215], v[58:61]
	v_mfma_f32_16x16x32_bf16 v[58:61], v[178:181], v[194:197], v[114:117]
	v_mfma_f32_16x16x32_bf16 v[240:243], v[182:185], v[198:201], v[58:61]
	v_mfma_f32_16x16x32_bf16 v[58:61], v[178:181], v[208:211], v[118:121]
	v_mfma_f32_16x16x32_bf16 v[178:181], v[182:185], v[212:215], v[58:61]
	v_mfma_f32_16x16x32_bf16 v[58:61], v[186:189], v[194:197], v[122:125]
	v_mfma_f32_16x16x32_bf16 v[182:185], v[190:193], v[198:201], v[58:61]
	v_mfma_f32_16x16x32_bf16 v[58:61], v[186:189], v[208:211], v[126:129]
	v_mfma_f32_16x16x32_bf16 v[224:227], v[70:73], v[198:201], v[74:77]
	v_mfma_f32_16x16x32_bf16 v[186:189], v[190:193], v[212:215], v[58:61]
	s_setprio 0
	s_barrier
; #define LDA(dst, b, h)                                                                                     \
;   _Pragma("unroll") for (int m = 0; m < 4; ++m) _Pragma("unroll") for (int k = 0; k < 2; ++k) dst[m][k] = \
;       *reinterpret_cast<const bf16x8*>(shmc + aL + (((b) * 2 + (h)) * 16384 + (m * 2 + k) * 1024))
; #define LDB(dst, b, h)                                                                                     \
;   _Pragma("unroll") for (int n = 0; n < 2; ++n) _Pragma("unroll") for (int k = 0; k < 2; ++k) dst[n][k] = \
;       *reinterpret_cast<const bf16x8*>(shmc + bL + (((b) * 2 + (h)) * 16384 + (n * 2 + k) * 1024))
; #define WAIT_V(n) asm volatile("s_waitcnt vmcnt(" #n ")" ::: "memory")
; #define WAIT_L(n) asm volatile("s_waitcnt lgkmcnt(" #n ")" ::: "memory")
; #define BAR __builtin_amdgcn_s_barrier()
; template <int EPI>
; __device__ __forceinline__ void phase_gemm(const Params& p, const GemmDesc& d, char* shmc) {
;     ...
;     {
;       LDB(B0, 1, 0); LDA(At, 1, 0); WAIT_V(2); BAR; WAIT_L(0); MMA(0, 0, At, B0); BAR;
;       LDB(B1, 1, 1); WAIT_V(0); BAR; WAIT_L(0); MMA(0, 1, At, B1); BAR;
;       LDA(At, 1, 1); BAR; WAIT_L(0); MMA(1, 0, At, B0); MMA(1, 1, At, B1); BAR;
;     }
;     if (wr == 0) BAR;
	ds_read_b128 v[98:101], v162 offset:32768
	ds_read_b128 v[106:109], v162 offset:33792
	ds_read_b128 v[190:193], v162 offset:34816
	ds_read_b128 v[194:197], v162 offset:35840
	ds_read_b128 v[58:61], v175 offset:32768
	ds_read_b128 v[70:73], v175 offset:33792
	ds_read_b128 v[114:117], v175 offset:34816
	ds_read_b128 v[122:125], v175 offset:35840
	ds_read_b128 v[130:133], v175 offset:36864
	ds_read_b128 v[138:141], v175 offset:37888
	ds_read_b128 v[198:201], v175 offset:38912
	ds_read_b128 v[208:211], v175 offset:39936
	s_waitcnt vmcnt(2)
	s_barrier
	s_waitcnt lgkmcnt(0)
	s_setprio 1
	s_waitcnt lgkmcnt(0)
	v_mfma_f32_16x16x32_bf16 v[2:5], v[58:61], v[98:101], v[2:5]
	v_mfma_f32_16x16x32_bf16 v[158:161], v[70:73], v[106:109], v[2:5]
	v_mfma_f32_16x16x32_bf16 v[2:5], v[58:61], v[190:193], v[6:9]
	v_mfma_f32_16x16x32_bf16 v[146:149], v[70:73], v[194:197], v[2:5]
	v_mfma_f32_16x16x32_bf16 v[2:5], v[114:117], v[98:101], v[10:13]
	v_mfma_f32_16x16x32_bf16 v[142:145], v[122:125], v[106:109], v[2:5]
	v_mfma_f32_16x16x32_bf16 v[2:5], v[114:117], v[190:193], v[18:21]
	v_mfma_f32_16x16x32_bf16 v[134:137], v[122:125], v[194:197], v[2:5]
	v_mfma_f32_16x16x32_bf16 v[2:5], v[130:133], v[98:101], v[30:33]
	v_mfma_f32_16x16x32_bf16 v[126:129], v[138:141], v[106:109], v[2:5]
	v_mfma_f32_16x16x32_bf16 v[2:5], v[130:133], v[190:193], v[42:45]
	v_mfma_f32_16x16x32_bf16 v[118:121], v[138:141], v[194:197], v[2:5]
	v_mfma_f32_16x16x32_bf16 v[2:5], v[198:201], v[98:101], v[54:57]
	v_mfma_f32_16x16x32_bf16 v[110:113], v[208:211], v[106:109], v[2:5]
	v_mfma_f32_16x16x32_bf16 v[2:5], v[198:201], v[190:193], v[66:69]
	v_mfma_f32_16x16x32_bf16 v[102:105], v[208:211], v[194:197], v[2:5]
	s_setprio 0
	s_barrier
	ds_read_b128 v[30:33], v162 offset:49152
	ds_read_b128 v[42:45], v162 offset:50176
	ds_read_b128 v[54:57], v162 offset:51200
	ds_read_b128 v[212:215], v162 offset:52224
	s_waitcnt vmcnt(0)
	s_barrier
	s_waitcnt lgkmcnt(0)
	s_setprio 1
	s_waitcnt lgkmcnt(0)
	v_mfma_f32_16x16x32_bf16 v[2:5], v[58:61], v[30:33], v[14:17]
	v_mfma_f32_16x16x32_bf16 v[94:97], v[70:73], v[42:45], v[2:5]
	v_mfma_f32_16x16x32_bf16 v[2:5], v[58:61], v[54:57], v[22:25]
	v_mfma_f32_16x16x32_bf16 v[58:61], v[70:73], v[212:215], v[2:5]
	v_mfma_f32_16x16x32_bf16 v[2:5], v[114:117], v[30:33], v[34:37]
	v_mfma_f32_16x16x32_bf16 v[74:77], v[122:125], v[42:45], v[2:5]
	v_mfma_f32_16x16x32_bf16 v[2:5], v[114:117], v[54:57], v[46:49]
	v_mfma_f32_16x16x32_bf16 v[10:13], v[122:125], v[212:215], v[2:5]
	v_mfma_f32_16x16x32_bf16 v[2:5], v[130:133], v[30:33], v[150:153]
	v_mfma_f32_16x16x32_bf16 v[70:73], v[138:141], v[42:45], v[2:5]
	v_mfma_f32_16x16x32_bf16 v[2:5], v[130:133], v[54:57], v[154:157]
	v_mfma_f32_16x16x32_bf16 v[6:9], v[138:141], v[212:215], v[2:5]
	v_mfma_f32_16x16x32_bf16 v[2:5], v[198:201], v[30:33], v[78:81]
	v_mfma_f32_16x16x32_bf16 v[66:69], v[208:211], v[42:45], v[2:5]
	v_mfma_f32_16x16x32_bf16 v[2:5], v[198:201], v[54:57], v[86:89]
	v_mfma_f32_16x16x32_bf16 v[2:5], v[208:211], v[212:215], v[2:5]
	s_setprio 0
	s_barrier
	ds_read_b128 v[14:17], v175 offset:49152
	ds_read_b128 v[18:21], v175 offset:50176
	ds_read_b128 v[22:25], v175 offset:51200
	ds_read_b128 v[34:37], v175 offset:52224
	ds_read_b128 v[46:49], v175 offset:53248
	ds_read_b128 v[78:81], v175 offset:54272
	ds_read_b128 v[198:201], v175 offset:55296
	ds_read_b128 v[208:211], v175 offset:56320
	s_barrier
	s_waitcnt lgkmcnt(0)
	s_setprio 1
	s_waitcnt lgkmcnt(0)
	v_mfma_f32_16x16x32_bf16 v[26:29], v[14:17], v[98:101], v[26:29]
	v_mfma_f32_16x16x32_bf16 v[154:157], v[18:21], v[106:109], v[26:29]
	v_mfma_f32_16x16x32_bf16 v[26:29], v[14:17], v[190:193], v[38:41]
	v_mfma_f32_16x16x32_bf16 v[150:153], v[18:21], v[194:197], v[26:29]
	v_mfma_f32_16x16x32_bf16 v[26:29], v[22:25], v[98:101], v[50:53]
	v_mfma_f32_16x16x32_bf16 v[138:141], v[34:37], v[106:109], v[26:29]
	v_mfma_f32_16x16x32_bf16 v[26:29], v[22:25], v[190:193], v[62:65]
	v_mfma_f32_16x16x32_bf16 v[130:133], v[34:37], v[194:197], v[26:29]
	v_mfma_f32_16x16x32_bf16 v[26:29], v[46:49], v[98:101], v[216:219]
	v_mfma_f32_16x16x32_bf16 v[122:125], v[78:81], v[106:109], v[26:29]
	v_mfma_f32_16x16x32_bf16 v[26:29], v[46:49], v[190:193], v[82:85]
	v_mfma_f32_16x16x32_bf16 v[114:117], v[78:81], v[194:197], v[26:29]
	v_mfma_f32_16x16x32_bf16 v[26:29], v[198:201], v[98:101], v[90:93]
	v_mfma_f32_16x16x32_bf16 v[106:109], v[208:211], v[106:109], v[26:29]
	v_mfma_f32_16x16x32_bf16 v[26:29], v[198:201], v[190:193], v[220:223]
	v_mfma_f32_16x16x32_bf16 v[98:101], v[208:211], v[194:197], v[26:29]
	s_setprio 0
	s_setprio 1
	v_mfma_f32_16x16x32_bf16 v[26:29], v[14:17], v[30:33], v[224:227]
	v_mfma_f32_16x16x32_bf16 v[14:17], v[14:17], v[54:57], v[228:231]
	v_mfma_f32_16x16x32_bf16 v[90:93], v[18:21], v[42:45], v[26:29]
	v_mfma_f32_16x16x32_bf16 v[26:29], v[18:21], v[212:215], v[14:17]
	v_mfma_f32_16x16x32_bf16 v[14:17], v[22:25], v[30:33], v[232:235]
	v_mfma_f32_16x16x32_bf16 v[86:89], v[34:37], v[42:45], v[14:17]
	v_mfma_f32_16x16x32_bf16 v[14:17], v[22:25], v[54:57], v[236:239]
	v_mfma_f32_16x16x32_bf16 v[22:25], v[34:37], v[212:215], v[14:17]
	v_mfma_f32_16x16x32_bf16 v[14:17], v[46:49], v[30:33], v[240:243]
	v_mfma_f32_16x16x32_bf16 v[82:85], v[78:81], v[42:45], v[14:17]
	v_mfma_f32_16x16x32_bf16 v[14:17], v[46:49], v[54:57], v[178:181]
	v_mfma_f32_16x16x32_bf16 v[18:21], v[78:81], v[212:215], v[14:17]
	v_mfma_f32_16x16x32_bf16 v[14:17], v[198:201], v[30:33], v[182:185]
	v_mfma_f32_16x16x32_bf16 v[78:81], v[208:211], v[42:45], v[14:17]
	v_mfma_f32_16x16x32_bf16 v[14:17], v[198:201], v[54:57], v[186:189]
	v_mfma_f32_16x16x32_bf16 v[14:17], v[208:211], v[212:215], v[14:17]
	s_setprio 0
	s_barrier
	s_and_saveexec_b64 s[8:9], s[6:7]
	s_cbranch_execz .LBB0_299
	s_barrier

; #define LDA(dst, b, h)                                                                                     \
;   _Pragma("unroll") for (int m = 0; m < 4; ++m) _Pragma("unroll") for (int k = 0; k < 2; ++k) dst[m][k] = \
;       *reinterpret_cast<const bf16x8*>(shmc + aL + (((b) * 2 + (h)) * 16384 + (m * 2 + k) * 1024))
; #define LDB(dst, b, h)                                                                                     \
;   _Pragma("unroll") for (int n = 0; n < 2; ++n) _Pragma("unroll") for (int k = 0; k < 2; ++k) dst[n][k] = \
;       *reinterpret_cast<const bf16x8*>(shmc + bL + (((b) * 2 + (h)) * 16384 + (n * 2 + k) * 1024))
; #define OPAQ asm volatile("" : "+v"(aL), "+v"(bL))
; #define WAIT_V(n) asm volatile("s_waitcnt vmcnt(" #n ")" ::: "memory")
; #define WAIT_L(n) asm volatile("s_waitcnt lgkmcnt(" #n ")" ::: "memory")
; #define BAR __builtin_amdgcn_s_barrier()
; #define SCHED __builtin_amdgcn_sched_barrier(0)
; template <int EPI>
; __device__ __forceinline__ void phase_gemm(const Params& p, const GemmDesc& d, char* shmc) {
;     ...
;     for (int t = 0; t < nt - 2; t += 2) {
;       OPAQ;
;       LDB(B0, 0, 0); SCHED; LDA(At, 0, 0); STAGE_A(SA(1, 1), 1, t + 1);
;       WAIT_L(8); BAR; WAIT_L(0); MMA(0, 0, At, B0); BAR; SCHED;
;       LDB(B1, 0, 1); STAGE_B(SB(0, 0), 0, t + 2);
;       BAR; WAIT_L(0); MMA(0, 1, At, B1); BAR;
;       LDA(At, 0, 1); STAGE_A(SA(0, 0), 0, t + 2);
;       BAR; WAIT_L(0); MMA(1, 0, At, B0); BAR; SCHED;
;       STAGE_B(SB(0, 1), 1, t + 2);
;       WAIT_V(6); BAR; MMA(1, 1, At, B1); BAR;
.LBB0_455:
	s_nop 0
	s_setprio 0
	ds_read_b128 v[156:159], v153
	ds_read_b128 v[160:163], v153 offset:1024
	ds_read_b128 v[164:167], v153 offset:2048
	ds_read_b128 v[168:171], v153 offset:3072
	ds_read_b128 v[204:207], v153 offset:16384
	ds_read_b128 v[208:211], v153 offset:17408
	ds_read_b128 v[212:215], v153 offset:18432
	ds_read_b128 v[216:219], v153 offset:19456
	ds_read_b128 v[172:175], v152
	ds_read_b128 v[176:179], v152 offset:1024
	ds_read_b128 v[180:183], v152 offset:2048
	ds_read_b128 v[184:187], v152 offset:3072
	ds_read_b128 v[188:191], v152 offset:4096
	ds_read_b128 v[192:195], v152 offset:5120
	ds_read_b128 v[196:199], v152 offset:6144
	ds_read_b128 v[200:203], v152 offset:7168
	s_mov_b32 m0, s70
	s_nop 0
	global_load_lds_dwordx4 v220, s[98:99]
	s_mov_b32 m0, s71
	s_nop 0
	global_load_lds_dwordx4 v221, s[98:99]
	s_waitcnt vmcnt(8)
	s_waitcnt lgkmcnt(0)
	s_setprio 1
	s_barrier
	v_mfma_f32_16x16x32_bf16 v[126:129], v[156:159], v[172:175], v[126:129]
	v_mfma_f32_16x16x32_bf16 v[122:125], v[164:167], v[172:175], v[122:125]
	v_mfma_f32_16x16x32_bf16 v[118:121], v[156:159], v[180:183], v[118:121]
	v_mfma_f32_16x16x32_bf16 v[114:117], v[164:167], v[180:183], v[114:117]
	v_mfma_f32_16x16x32_bf16 v[110:113], v[156:159], v[188:191], v[110:113]
	v_mfma_f32_16x16x32_bf16 v[106:109], v[164:167], v[188:191], v[106:109]
	v_mfma_f32_16x16x32_bf16 v[102:105], v[156:159], v[196:199], v[102:105]
	v_mfma_f32_16x16x32_bf16 v[98:101], v[164:167], v[196:199], v[98:101]
	v_mfma_f32_16x16x32_bf16 v[126:129], v[160:163], v[176:179], v[126:129]
	v_mfma_f32_16x16x32_bf16 v[122:125], v[168:171], v[176:179], v[122:125]
	v_mfma_f32_16x16x32_bf16 v[118:121], v[160:163], v[184:187], v[118:121]
	v_mfma_f32_16x16x32_bf16 v[114:117], v[168:171], v[184:187], v[114:117]
	v_mfma_f32_16x16x32_bf16 v[110:113], v[160:163], v[192:195], v[110:113]
	v_mfma_f32_16x16x32_bf16 v[106:109], v[168:171], v[192:195], v[106:109]
	v_mfma_f32_16x16x32_bf16 v[102:105], v[160:163], v[200:203], v[102:105]
	v_mfma_f32_16x16x32_bf16 v[98:101], v[168:171], v[200:203], v[98:101]
	v_mfma_f32_16x16x32_bf16 v[86:89], v[204:207], v[172:175], v[86:89]
	v_mfma_f32_16x16x32_bf16 v[70:73], v[212:215], v[172:175], v[70:73]
	v_mfma_f32_16x16x32_bf16 v[54:57], v[204:207], v[180:183], v[54:57]
	v_mfma_f32_16x16x32_bf16 v[50:53], v[212:215], v[180:183], v[50:53]
	v_mfma_f32_16x16x32_bf16 v[46:49], v[204:207], v[188:191], v[46:49]
	v_mfma_f32_16x16x32_bf16 v[42:45], v[212:215], v[188:191], v[42:45]
	v_mfma_f32_16x16x32_bf16 v[38:41], v[204:207], v[196:199], v[38:41]
	v_mfma_f32_16x16x32_bf16 v[34:37], v[212:215], v[196:199], v[34:37]
	v_mfma_f32_16x16x32_bf16 v[86:89], v[208:211], v[176:179], v[86:89]
	v_mfma_f32_16x16x32_bf16 v[70:73], v[216:219], v[176:179], v[70:73]
	v_mfma_f32_16x16x32_bf16 v[54:57], v[208:211], v[184:187], v[54:57]
	v_mfma_f32_16x16x32_bf16 v[50:53], v[216:219], v[184:187], v[50:53]
	v_mfma_f32_16x16x32_bf16 v[46:49], v[208:211], v[192:195], v[46:49]
	v_mfma_f32_16x16x32_bf16 v[42:45], v[216:219], v[192:195], v[42:45]
	v_mfma_f32_16x16x32_bf16 v[38:41], v[208:211], v[200:203], v[38:41]
	v_mfma_f32_16x16x32_bf16 v[34:37], v[216:219], v[200:203], v[34:37]
	s_barrier
	s_setprio 0
	ds_read_b128 v[172:175], v152 offset:16384
	ds_read_b128 v[176:179], v152 offset:17408
	ds_read_b128 v[180:183], v152 offset:18432
	ds_read_b128 v[184:187], v152 offset:19456
	ds_read_b128 v[188:191], v152 offset:20480
	ds_read_b128 v[192:195], v152 offset:21504
	ds_read_b128 v[196:199], v152 offset:22528
	ds_read_b128 v[200:203], v152 offset:23552
	s_mov_b32 m0, s33
	s_nop 0
	global_load_lds_dwordx4 v222, s[100:101]
	s_mov_b32 m0, s34
	s_nop 0
	global_load_lds_dwordx4 v223, s[100:101]
	s_mov_b32 m0, s14
	s_nop 0
	global_load_lds_dwordx4 v224, s[98:99]
	s_mov_b32 m0, s35
	s_nop 0
	global_load_lds_dwordx4 v225, s[98:99]
	s_mov_b32 m0, s58
	s_nop 0
	global_load_lds_dwordx4 v226, s[100:101]
	s_mov_b32 m0, s59
	s_nop 0
	global_load_lds_dwordx4 v227, s[100:101]
	s_waitcnt vmcnt(8)
	s_waitcnt lgkmcnt(0)
	s_setprio 1
	s_barrier
	v_mfma_f32_16x16x32_bf16 v[30:33], v[156:159], v[172:175], v[30:33]
	v_mfma_f32_16x16x32_bf16 v[26:29], v[164:167], v[172:175], v[26:29]
	v_mfma_f32_16x16x32_bf16 v[22:25], v[156:159], v[180:183], v[22:25]
	v_mfma_f32_16x16x32_bf16 v[18:21], v[164:167], v[180:183], v[18:21]
	v_mfma_f32_16x16x32_bf16 v[14:17], v[156:159], v[188:191], v[14:17]
	v_mfma_f32_16x16x32_bf16 v[10:13], v[164:167], v[188:191], v[10:13]
	v_mfma_f32_16x16x32_bf16 v[6:9], v[156:159], v[196:199], v[6:9]
	v_mfma_f32_16x16x32_bf16 v[2:5], v[164:167], v[196:199], v[2:5]
	v_mfma_f32_16x16x32_bf16 v[30:33], v[160:163], v[176:179], v[30:33]
	v_mfma_f32_16x16x32_bf16 v[26:29], v[168:171], v[176:179], v[26:29]
	v_mfma_f32_16x16x32_bf16 v[22:25], v[160:163], v[184:187], v[22:25]
	v_mfma_f32_16x16x32_bf16 v[18:21], v[168:171], v[184:187], v[18:21]
	v_mfma_f32_16x16x32_bf16 v[14:17], v[160:163], v[192:195], v[14:17]
	v_mfma_f32_16x16x32_bf16 v[10:13], v[168:171], v[192:195], v[10:13]
	v_mfma_f32_16x16x32_bf16 v[6:9], v[160:163], v[200:203], v[6:9]
	v_mfma_f32_16x16x32_bf16 v[2:5], v[168:171], v[200:203], v[2:5]
	v_mfma_f32_16x16x32_bf16 v[58:61], v[204:207], v[172:175], v[58:61]
	v_mfma_f32_16x16x32_bf16 v[62:65], v[212:215], v[172:175], v[62:65]
	v_mfma_f32_16x16x32_bf16 v[66:69], v[204:207], v[180:183], v[66:69]
	v_mfma_f32_16x16x32_bf16 v[74:77], v[212:215], v[180:183], v[74:77]
	v_mfma_f32_16x16x32_bf16 v[78:81], v[204:207], v[188:191], v[78:81]
	v_mfma_f32_16x16x32_bf16 v[82:85], v[212:215], v[188:191], v[82:85]
	v_mfma_f32_16x16x32_bf16 v[90:93], v[204:207], v[196:199], v[90:93]
	v_mfma_f32_16x16x32_bf16 v[94:97], v[212:215], v[196:199], v[94:97]
	v_mfma_f32_16x16x32_bf16 v[58:61], v[208:211], v[176:179], v[58:61]
	v_mfma_f32_16x16x32_bf16 v[62:65], v[216:219], v[176:179], v[62:65]
	v_mfma_f32_16x16x32_bf16 v[66:69], v[208:211], v[184:187], v[66:69]
	v_mfma_f32_16x16x32_bf16 v[74:77], v[216:219], v[184:187], v[74:77]
	v_mfma_f32_16x16x32_bf16 v[78:81], v[208:211], v[192:195], v[78:81]
	v_mfma_f32_16x16x32_bf16 v[82:85], v[216:219], v[192:195], v[82:85]
	v_mfma_f32_16x16x32_bf16 v[90:93], v[208:211], v[200:203], v[90:93]
	v_mfma_f32_16x16x32_bf16 v[94:97], v[216:219], v[200:203], v[94:97]
	s_barrier
; #define LDA(dst, b, h)                                                                                     \
;   _Pragma("unroll") for (int m = 0; m < 4; ++m) _Pragma("unroll") for (int k = 0; k < 2; ++k) dst[m][k] = \
;       *reinterpret_cast<const bf16x8*>(shmc + aL + (((b) * 2 + (h)) * 16384 + (m * 2 + k) * 1024))
; #define LDB(dst, b, h)                                                                                     \
;   _Pragma("unroll") for (int n = 0; n < 2; ++n) _Pragma("unroll") for (int k = 0; k < 2; ++k) dst[n][k] = \
;       *reinterpret_cast<const bf16x8*>(shmc + bL + (((b) * 2 + (h)) * 16384 + (n * 2 + k) * 1024))
; #define WAIT_V(n) asm volatile("s_waitcnt vmcnt(" #n ")" ::: "memory")
; #define WAIT_L(n) asm volatile("s_waitcnt lgkmcnt(" #n ")" ::: "memory")
; #define BAR __builtin_amdgcn_s_barrier()
; #define SCHED __builtin_amdgcn_sched_barrier(0)
; template <int EPI>
; __device__ __forceinline__ void phase_gemm(const Params& p, const GemmDesc& d, char* shmc) {
;     ...
;       LDB(B0, 1, 0); SCHED; LDA(At, 1, 0); STAGE_A(SA(0, 1), 1, t + 2);
;       WAIT_L(8); BAR; WAIT_L(0); MMA(0, 0, At, B0); BAR; SCHED;
;       LDB(B1, 1, 1); STAGE_B(SB(1, 0), 0, t + 3);
;       BAR; WAIT_L(0); MMA(0, 1, At, B1); BAR;
;       LDA(At, 1, 1); STAGE_A(SA(1, 0), 0, t + 3);
;       BAR; WAIT_L(0); MMA(1, 0, At, B0); BAR; SCHED;
;       STAGE_B(SB(1, 1), 1, t + 3);
;       WAIT_V(6); BAR; MMA(1, 1, At, B1); BAR;
	s_setprio 0
	ds_read_b128 v[156:159], v153 offset:32768
	ds_read_b128 v[160:163], v153 offset:33792
	ds_read_b128 v[164:167], v153 offset:34816
	ds_read_b128 v[168:171], v153 offset:35840
	ds_read_b128 v[204:207], v153 offset:49152
	ds_read_b128 v[208:211], v153 offset:50176
	ds_read_b128 v[212:215], v153 offset:51200
	ds_read_b128 v[216:219], v153 offset:52224
	ds_read_b128 v[172:175], v152 offset:32768
	ds_read_b128 v[176:179], v152 offset:33792
	ds_read_b128 v[180:183], v152 offset:34816
	ds_read_b128 v[184:187], v152 offset:35840
	ds_read_b128 v[188:191], v152 offset:36864
	ds_read_b128 v[192:195], v152 offset:37888
	ds_read_b128 v[196:199], v152 offset:38912
	ds_read_b128 v[200:203], v152 offset:39936
	s_mov_b32 m0, s60
	s_nop 0
	global_load_lds_dwordx4 v228, s[98:99]
	s_mov_b32 m0, s61
	s_nop 0
	global_load_lds_dwordx4 v229, s[98:99]
	s_waitcnt vmcnt(8)
	s_waitcnt lgkmcnt(0)
	s_setprio 1
	s_barrier
	v_mfma_f32_16x16x32_bf16 v[126:129], v[156:159], v[172:175], v[126:129]
	v_mfma_f32_16x16x32_bf16 v[122:125], v[164:167], v[172:175], v[122:125]
	v_mfma_f32_16x16x32_bf16 v[118:121], v[156:159], v[180:183], v[118:121]
	v_mfma_f32_16x16x32_bf16 v[114:117], v[164:167], v[180:183], v[114:117]
	v_mfma_f32_16x16x32_bf16 v[110:113], v[156:159], v[188:191], v[110:113]
	v_mfma_f32_16x16x32_bf16 v[106:109], v[164:167], v[188:191], v[106:109]
	v_mfma_f32_16x16x32_bf16 v[102:105], v[156:159], v[196:199], v[102:105]
	v_mfma_f32_16x16x32_bf16 v[98:101], v[164:167], v[196:199], v[98:101]
	v_mfma_f32_16x16x32_bf16 v[126:129], v[160:163], v[176:179], v[126:129]
	v_mfma_f32_16x16x32_bf16 v[122:125], v[168:171], v[176:179], v[122:125]
	v_mfma_f32_16x16x32_bf16 v[118:121], v[160:163], v[184:187], v[118:121]
	v_mfma_f32_16x16x32_bf16 v[114:117], v[168:171], v[184:187], v[114:117]
	v_mfma_f32_16x16x32_bf16 v[110:113], v[160:163], v[192:195], v[110:113]
	v_mfma_f32_16x16x32_bf16 v[106:109], v[168:171], v[192:195], v[106:109]
	v_mfma_f32_16x16x32_bf16 v[102:105], v[160:163], v[200:203], v[102:105]
	v_mfma_f32_16x16x32_bf16 v[98:101], v[168:171], v[200:203], v[98:101]
	v_mfma_f32_16x16x32_bf16 v[86:89], v[204:207], v[172:175], v[86:89]
	v_mfma_f32_16x16x32_bf16 v[70:73], v[212:215], v[172:175], v[70:73]
	v_mfma_f32_16x16x32_bf16 v[54:57], v[204:207], v[180:183], v[54:57]
	v_mfma_f32_16x16x32_bf16 v[50:53], v[212:215], v[180:183], v[50:53]
	v_mfma_f32_16x16x32_bf16 v[46:49], v[204:207], v[188:191], v[46:49]
	v_mfma_f32_16x16x32_bf16 v[42:45], v[212:215], v[188:191], v[42:45]
	v_mfma_f32_16x16x32_bf16 v[38:41], v[204:207], v[196:199], v[38:41]
	v_mfma_f32_16x16x32_bf16 v[34:37], v[212:215], v[196:199], v[34:37]
	v_mfma_f32_16x16x32_bf16 v[86:89], v[208:211], v[176:179], v[86:89]
	v_mfma_f32_16x16x32_bf16 v[70:73], v[216:219], v[176:179], v[70:73]
	v_mfma_f32_16x16x32_bf16 v[54:57], v[208:211], v[184:187], v[54:57]
	v_mfma_f32_16x16x32_bf16 v[50:53], v[216:219], v[184:187], v[50:53]
	v_mfma_f32_16x16x32_bf16 v[46:49], v[208:211], v[192:195], v[46:49]
	v_mfma_f32_16x16x32_bf16 v[42:45], v[216:219], v[192:195], v[42:45]
	v_mfma_f32_16x16x32_bf16 v[38:41], v[208:211], v[200:203], v[38:41]
	v_mfma_f32_16x16x32_bf16 v[34:37], v[216:219], v[200:203], v[34:37]
	s_barrier
	s_setprio 0
	ds_read_b128 v[172:175], v152 offset:49152
	ds_read_b128 v[176:179], v152 offset:50176
	ds_read_b128 v[180:183], v152 offset:51200
	ds_read_b128 v[184:187], v152 offset:52224
	ds_read_b128 v[188:191], v152 offset:53248
	ds_read_b128 v[192:195], v152 offset:54272
	ds_read_b128 v[196:199], v152 offset:55296
	ds_read_b128 v[200:203], v152 offset:56320
	s_mov_b32 m0, s62
	s_nop 0
	global_load_lds_dwordx4 v232, s[100:101]
	s_mov_b32 m0, s63
	s_nop 0
	global_load_lds_dwordx4 v233, s[100:101]
	s_mov_b32 m0, s64
	s_nop 0
	global_load_lds_dwordx4 v234, s[98:99]
	s_mov_b32 m0, s65
	s_nop 0
	global_load_lds_dwordx4 v235, s[98:99]
	s_mov_b32 m0, s68
	s_nop 0
	global_load_lds_dwordx4 v236, s[100:101]
	s_mov_b32 m0, s69
	s_nop 0
	global_load_lds_dwordx4 v237, s[100:101]
	s_add_i32 s54, s54, 2
	s_add_u32 s52, s52, 0x100
	s_addc_u32 s53, s53, 0
	s_add_u32 s98, s98, 0x100
	s_addc_u32 s99, s99, 0
	s_add_u32 s100, s100, 0x100
	s_addc_u32 s101, s101, 0
	s_cmpk_gt_u32 s54, 0x53
	s_waitcnt vmcnt(8)
	s_waitcnt lgkmcnt(0)
	s_setprio 1
	s_barrier
	v_mfma_f32_16x16x32_bf16 v[30:33], v[156:159], v[172:175], v[30:33]
	v_mfma_f32_16x16x32_bf16 v[26:29], v[164:167], v[172:175], v[26:29]
	v_mfma_f32_16x16x32_bf16 v[22:25], v[156:159], v[180:183], v[22:25]
	v_mfma_f32_16x16x32_bf16 v[18:21], v[164:167], v[180:183], v[18:21]
	v_mfma_f32_16x16x32_bf16 v[14:17], v[156:159], v[188:191], v[14:17]
	v_mfma_f32_16x16x32_bf16 v[10:13], v[164:167], v[188:191], v[10:13]
	v_mfma_f32_16x16x32_bf16 v[6:9], v[156:159], v[196:199], v[6:9]
	v_mfma_f32_16x16x32_bf16 v[2:5], v[164:167], v[196:199], v[2:5]
	v_mfma_f32_16x16x32_bf16 v[30:33], v[160:163], v[176:179], v[30:33]
	v_mfma_f32_16x16x32_bf16 v[26:29], v[168:171], v[176:179], v[26:29]
	v_mfma_f32_16x16x32_bf16 v[22:25], v[160:163], v[184:187], v[22:25]
	v_mfma_f32_16x16x32_bf16 v[18:21], v[168:171], v[184:187], v[18:21]
	v_mfma_f32_16x16x32_bf16 v[14:17], v[160:163], v[192:195], v[14:17]
	v_mfma_f32_16x16x32_bf16 v[10:13], v[168:171], v[192:195], v[10:13]
	v_mfma_f32_16x16x32_bf16 v[6:9], v[160:163], v[200:203], v[6:9]
	v_mfma_f32_16x16x32_bf16 v[2:5], v[168:171], v[200:203], v[2:5]
	v_mfma_f32_16x16x32_bf16 v[58:61], v[204:207], v[172:175], v[58:61]
	v_mfma_f32_16x16x32_bf16 v[62:65], v[212:215], v[172:175], v[62:65]
	v_mfma_f32_16x16x32_bf16 v[66:69], v[204:207], v[180:183], v[66:69]
	v_mfma_f32_16x16x32_bf16 v[74:77], v[212:215], v[180:183], v[74:77]
	v_mfma_f32_16x16x32_bf16 v[78:81], v[204:207], v[188:191], v[78:81]
	v_mfma_f32_16x16x32_bf16 v[82:85], v[212:215], v[188:191], v[82:85]
	v_mfma_f32_16x16x32_bf16 v[90:93], v[204:207], v[196:199], v[90:93]
	v_mfma_f32_16x16x32_bf16 v[94:97], v[212:215], v[196:199], v[94:97]
	v_mfma_f32_16x16x32_bf16 v[58:61], v[208:211], v[176:179], v[58:61]
	v_mfma_f32_16x16x32_bf16 v[62:65], v[216:219], v[176:179], v[62:65]
	v_mfma_f32_16x16x32_bf16 v[66:69], v[208:211], v[184:187], v[66:69]
	v_mfma_f32_16x16x32_bf16 v[74:77], v[216:219], v[184:187], v[74:77]
	v_mfma_f32_16x16x32_bf16 v[78:81], v[208:211], v[192:195], v[78:81]
	v_mfma_f32_16x16x32_bf16 v[82:85], v[216:219], v[192:195], v[82:85]
	v_mfma_f32_16x16x32_bf16 v[90:93], v[208:211], v[200:203], v[90:93]
	v_mfma_f32_16x16x32_bf16 v[94:97], v[216:219], v[200:203], v[94:97]
	s_barrier
; #define LDA(dst, b, h)                                                                                     \
;   _Pragma("unroll") for (int m = 0; m < 4; ++m) _Pragma("unroll") for (int k = 0; k < 2; ++k) dst[m][k] = \
;       *reinterpret_cast<const bf16x8*>(shmc + aL + (((b) * 2 + (h)) * 16384 + (m * 2 + k) * 1024))
; #define LDB(dst, b, h)                                                                                     \
;   _Pragma("unroll") for (int n = 0; n < 2; ++n) _Pragma("unroll") for (int k = 0; k < 2; ++k) dst[n][k] = \
;       *reinterpret_cast<const bf16x8*>(shmc + bL + (((b) * 2 + (h)) * 16384 + (n * 2 + k) * 1024))
; #define OPAQ asm volatile("" : "+v"(aL), "+v"(bL))
; #define WAIT_V(n) asm volatile("s_waitcnt vmcnt(" #n ")" ::: "memory")
; #define WAIT_L(n) asm volatile("s_waitcnt lgkmcnt(" #n ")" ::: "memory")
; #define BAR __builtin_amdgcn_s_barrier()
; template <int EPI>
; __device__ __forceinline__ void phase_gemm(const Params& p, const GemmDesc& d, char* shmc) {
;     ...
;     {
;       OPAQ;
;       LDB(B0, 0, 0); LDA(At, 0, 0); STAGE_A(SA(1, 1), 1, nt - 1);
;       BAR; WAIT_L(0); MMA(0, 0, At, B0); BAR;
;       LDB(B1, 0, 1); BAR; WAIT_L(0); MMA(0, 1, At, B1); BAR;
;       LDA(At, 0, 1); WAIT_V(4); BAR; WAIT_L(0); MMA(1, 0, At, B0); MMA(1, 1, At, B1); BAR;
;     }
	s_cbranch_scc0 .LBB0_455
	s_setprio 0
	s_add_u32 s48, s48, 0x162b80
	s_addc_u32 s49, s49, 0
	v_add_u32_e32 v130, 0, v153
	v_add_u32_e32 v141, 0, v152
	s_mov_b32 m0, s70
	ds_read_b128 v[144:147], v130
	ds_read_b128 v[148:151], v130 offset:1024
	ds_read_b128 v[156:159], v130 offset:2048
	ds_read_b128 v[160:163], v130 offset:3072
	ds_read_b128 v[164:167], v141
	ds_read_b128 v[168:171], v141 offset:1024
	ds_read_b128 v[172:175], v141 offset:2048
	ds_read_b128 v[176:179], v141 offset:3072
	ds_read_b128 v[180:183], v141 offset:4096
	ds_read_b128 v[184:187], v141 offset:5120
	ds_read_b128 v[188:191], v141 offset:6144
	ds_read_b128 v[192:195], v141 offset:7168
	global_load_lds_dwordx4 v140, s[48:49]
	s_mov_b32 m0, s71
	s_nop 0
	global_load_lds_dwordx4 v142, s[48:49]
	s_waitcnt vmcnt(8)
	s_barrier
	s_waitcnt lgkmcnt(0)
	s_setprio 1
	s_waitcnt lgkmcnt(0)
	v_mfma_f32_16x16x32_bf16 v[126:129], v[144:147], v[164:167], v[126:129]
	v_mfma_f32_16x16x32_bf16 v[122:125], v[156:159], v[164:167], v[122:125]
	v_mfma_f32_16x16x32_bf16 v[114:117], v[156:159], v[172:175], v[114:117]
	v_mfma_f32_16x16x32_bf16 v[110:113], v[144:147], v[180:183], v[110:113]
	v_mfma_f32_16x16x32_bf16 v[102:105], v[144:147], v[188:191], v[102:105]
	v_mfma_f32_16x16x32_bf16 v[126:129], v[148:151], v[168:171], v[126:129]
	v_mfma_f32_16x16x32_bf16 v[122:125], v[160:163], v[168:171], v[122:125]
	v_mfma_f32_16x16x32_bf16 v[118:121], v[144:147], v[172:175], v[118:121]
	v_mfma_f32_16x16x32_bf16 v[114:117], v[160:163], v[176:179], v[114:117]
	v_mfma_f32_16x16x32_bf16 v[110:113], v[148:151], v[184:187], v[110:113]
	v_mfma_f32_16x16x32_bf16 v[106:109], v[156:159], v[180:183], v[106:109]
	v_mfma_f32_16x16x32_bf16 v[102:105], v[148:151], v[192:195], v[102:105]
	v_mfma_f32_16x16x32_bf16 v[98:101], v[156:159], v[188:191], v[98:101]
	v_mfma_f32_16x16x32_bf16 v[196:199], v[148:151], v[176:179], v[118:121]
	v_mfma_f32_16x16x32_bf16 v[200:203], v[160:163], v[184:187], v[106:109]
	v_mfma_f32_16x16x32_bf16 v[204:207], v[160:163], v[192:195], v[98:101]
	s_setprio 0
	s_barrier
	s_nop 2
	ds_read_b128 v[98:101], v130 offset:16384
	ds_read_b128 v[106:109], v130 offset:17408
	ds_read_b128 v[118:121], v130 offset:18432
	ds_read_b128 v[208:211], v130 offset:19456
	s_barrier
	s_waitcnt lgkmcnt(0)
	s_setprio 1
	s_waitcnt lgkmcnt(0)
	v_mfma_f32_16x16x32_bf16 v[86:89], v[98:101], v[164:167], v[86:89]
	v_mfma_f32_16x16x32_bf16 v[70:73], v[118:121], v[164:167], v[70:73]
	v_mfma_f32_16x16x32_bf16 v[54:57], v[98:101], v[172:175], v[54:57]
	v_mfma_f32_16x16x32_bf16 v[50:53], v[118:121], v[172:175], v[50:53]
	v_mfma_f32_16x16x32_bf16 v[46:49], v[98:101], v[180:183], v[46:49]
	v_mfma_f32_16x16x32_bf16 v[42:45], v[118:121], v[180:183], v[42:45]
	v_mfma_f32_16x16x32_bf16 v[38:41], v[98:101], v[188:191], v[38:41]
	v_mfma_f32_16x16x32_bf16 v[34:37], v[118:121], v[188:191], v[34:37]
	v_mfma_f32_16x16x32_bf16 v[86:89], v[106:109], v[168:171], v[86:89]
	v_mfma_f32_16x16x32_bf16 v[70:73], v[208:211], v[168:171], v[70:73]
	v_mfma_f32_16x16x32_bf16 v[54:57], v[106:109], v[176:179], v[54:57]
	v_mfma_f32_16x16x32_bf16 v[50:53], v[208:211], v[176:179], v[50:53]
	v_mfma_f32_16x16x32_bf16 v[46:49], v[106:109], v[184:187], v[46:49]
	v_mfma_f32_16x16x32_bf16 v[42:45], v[208:211], v[184:187], v[42:45]
	v_mfma_f32_16x16x32_bf16 v[38:41], v[106:109], v[192:195], v[38:41]
	v_mfma_f32_16x16x32_bf16 v[34:37], v[208:211], v[192:195], v[34:37]
	s_setprio 0
	s_barrier
	ds_read_b128 v[164:167], v141 offset:16384
	ds_read_b128 v[168:171], v141 offset:17408
	ds_read_b128 v[172:175], v141 offset:18432
	ds_read_b128 v[176:179], v141 offset:19456
	ds_read_b128 v[180:183], v141 offset:20480
	ds_read_b128 v[184:187], v141 offset:21504
	ds_read_b128 v[188:191], v141 offset:22528
	ds_read_b128 v[192:195], v141 offset:23552
	s_waitcnt vmcnt(4)
	s_barrier
	s_waitcnt lgkmcnt(0)
	s_setprio 1
	s_waitcnt lgkmcnt(0)
	v_mfma_f32_16x16x32_bf16 v[30:33], v[144:147], v[164:167], v[30:33]
	v_mfma_f32_16x16x32_bf16 v[26:29], v[156:159], v[164:167], v[26:29]
	v_mfma_f32_16x16x32_bf16 v[22:25], v[144:147], v[172:175], v[22:25]
	v_mfma_f32_16x16x32_bf16 v[18:21], v[156:159], v[172:175], v[18:21]
	v_mfma_f32_16x16x32_bf16 v[14:17], v[144:147], v[180:183], v[14:17]
	v_mfma_f32_16x16x32_bf16 v[10:13], v[156:159], v[180:183], v[10:13]
	v_mfma_f32_16x16x32_bf16 v[6:9], v[144:147], v[188:191], v[6:9]
	v_mfma_f32_16x16x32_bf16 v[2:5], v[156:159], v[188:191], v[2:5]
	v_mfma_f32_16x16x32_bf16 v[30:33], v[148:151], v[168:171], v[30:33]
	v_mfma_f32_16x16x32_bf16 v[26:29], v[160:163], v[168:171], v[26:29]
	v_mfma_f32_16x16x32_bf16 v[22:25], v[148:151], v[176:179], v[22:25]
	v_mfma_f32_16x16x32_bf16 v[18:21], v[160:163], v[176:179], v[18:21]
	v_mfma_f32_16x16x32_bf16 v[14:17], v[148:151], v[184:187], v[14:17]
	v_mfma_f32_16x16x32_bf16 v[10:13], v[160:163], v[184:187], v[10:13]
	v_mfma_f32_16x16x32_bf16 v[6:9], v[148:151], v[192:195], v[6:9]
	v_mfma_f32_16x16x32_bf16 v[2:5], v[160:163], v[192:195], v[2:5]
	s_setprio 0
	s_setprio 1
	v_mfma_f32_16x16x32_bf16 v[62:65], v[118:121], v[164:167], v[62:65]
	v_mfma_f32_16x16x32_bf16 v[144:147], v[208:211], v[168:171], v[62:65]
	v_mfma_f32_16x16x32_bf16 v[62:65], v[98:101], v[172:175], v[66:69]
	v_mfma_f32_16x16x32_bf16 v[148:151], v[106:109], v[176:179], v[62:65]
	v_mfma_f32_16x16x32_bf16 v[62:65], v[118:121], v[172:175], v[74:77]
	v_mfma_f32_16x16x32_bf16 v[156:159], v[208:211], v[176:179], v[62:65]
	v_mfma_f32_16x16x32_bf16 v[62:65], v[98:101], v[180:183], v[78:81]
	v_mfma_f32_16x16x32_bf16 v[160:163], v[106:109], v[184:187], v[62:65]
	v_mfma_f32_16x16x32_bf16 v[62:65], v[118:121], v[180:183], v[82:85]
	v_mfma_f32_16x16x32_bf16 v[58:61], v[98:101], v[164:167], v[58:61]
	v_mfma_f32_16x16x32_bf16 v[164:167], v[208:211], v[184:187], v[62:65]
	v_mfma_f32_16x16x32_bf16 v[62:65], v[98:101], v[188:191], v[90:93]
	v_mfma_f32_16x16x32_bf16 v[58:61], v[106:109], v[168:171], v[58:61]
	v_mfma_f32_16x16x32_bf16 v[168:171], v[106:109], v[192:195], v[62:65]
	v_mfma_f32_16x16x32_bf16 v[62:65], v[118:121], v[188:191], v[94:97]
	v_mfma_f32_16x16x32_bf16 v[172:175], v[208:211], v[192:195], v[62:65]
	s_setprio 0
	s_barrier
; #define LDA(dst, b, h)                                                                                     \
;   _Pragma("unroll") for (int m = 0; m < 4; ++m) _Pragma("unroll") for (int k = 0; k < 2; ++k) dst[m][k] = \
;       *reinterpret_cast<const bf16x8*>(shmc + aL + (((b) * 2 + (h)) * 16384 + (m * 2 + k) * 1024))
; #define LDB(dst, b, h)                                                                                     \
;   _Pragma("unroll") for (int n = 0; n < 2; ++n) _Pragma("unroll") for (int k = 0; k < 2; ++k) dst[n][k] = \
;       *reinterpret_cast<const bf16x8*>(shmc + bL + (((b) * 2 + (h)) * 16384 + (n * 2 + k) * 1024))
; #define WAIT_V(n) asm volatile("s_waitcnt vmcnt(" #n ")" ::: "memory")
; #define WAIT_L(n) asm volatile("s_waitcnt lgkmcnt(" #n ")" ::: "memory")
; #define BAR __builtin_amdgcn_s_barrier()
; template <int EPI>
; __device__ __forceinline__ void phase_gemm(const Params& p, const GemmDesc& d, char* shmc) {
;     ...
;     {
;       LDB(B0, 1, 0); LDA(At, 1, 0); WAIT_V(2); BAR; WAIT_L(0); MMA(0, 0, At, B0); BAR;
;       LDB(B1, 1, 1); WAIT_V(0); BAR; WAIT_L(0); MMA(0, 1, At, B1); BAR;
;       LDA(At, 1, 1); BAR; WAIT_L(0); MMA(1, 0, At, B0); MMA(1, 1, At, B1); BAR;
;     }
;     if (wr == 0) BAR;
	ds_read_b128 v[176:179], v130 offset:32768
	ds_read_b128 v[180:183], v130 offset:33792
	ds_read_b128 v[184:187], v130 offset:34816
	ds_read_b128 v[188:191], v130 offset:35840
	s_nop 0
	ds_read_b128 v[62:65], v141 offset:32768
	ds_read_b128 v[78:81], v141 offset:33792
	ds_read_b128 v[94:97], v141 offset:34816
	ds_read_b128 v[192:195], v141 offset:35840
	ds_read_b128 v[208:211], v141 offset:36864
	ds_read_b128 v[212:215], v141 offset:37888
	ds_read_b128 v[216:219], v141 offset:38912
	ds_read_b128 v[220:223], v141 offset:39936
	s_waitcnt vmcnt(2)
	s_barrier
	s_waitcnt lgkmcnt(0)
	s_setprio 1
	s_waitcnt lgkmcnt(0)
	v_mfma_f32_16x16x32_bf16 v[66:69], v[176:179], v[62:65], v[126:129]
	v_mfma_f32_16x16x32_bf16 v[126:129], v[180:183], v[78:81], v[66:69]
	v_mfma_f32_16x16x32_bf16 v[66:69], v[184:187], v[62:65], v[122:125]
	v_mfma_f32_16x16x32_bf16 v[118:121], v[188:191], v[78:81], v[66:69]
	v_mfma_f32_16x16x32_bf16 v[66:69], v[176:179], v[94:97], v[196:199]
	v_mfma_f32_16x16x32_bf16 v[106:109], v[180:183], v[192:195], v[66:69]
	v_mfma_f32_16x16x32_bf16 v[66:69], v[184:187], v[94:97], v[114:117]
	v_mfma_f32_16x16x32_bf16 v[98:101], v[188:191], v[192:195], v[66:69]
	v_mfma_f32_16x16x32_bf16 v[66:69], v[176:179], v[208:211], v[110:113]
	v_mfma_f32_16x16x32_bf16 v[90:93], v[180:183], v[212:215], v[66:69]
	v_mfma_f32_16x16x32_bf16 v[66:69], v[184:187], v[208:211], v[200:203]
	v_mfma_f32_16x16x32_bf16 v[82:85], v[188:191], v[212:215], v[66:69]
	v_mfma_f32_16x16x32_bf16 v[66:69], v[176:179], v[216:219], v[102:105]
	v_mfma_f32_16x16x32_bf16 v[74:77], v[180:183], v[220:223], v[66:69]
	v_mfma_f32_16x16x32_bf16 v[66:69], v[184:187], v[216:219], v[204:207]
	v_mfma_f32_16x16x32_bf16 v[66:69], v[188:191], v[220:223], v[66:69]
	s_setprio 0
	s_barrier
	ds_read_b128 v[196:199], v130 offset:49152
	ds_read_b128 v[200:203], v130 offset:50176
	ds_read_b128 v[204:207], v130 offset:51200
	ds_read_b128 v[224:227], v130 offset:52224
	s_waitcnt vmcnt(0)
	s_barrier
	s_waitcnt lgkmcnt(0)
	s_setprio 1
	s_waitcnt lgkmcnt(0)
	v_mfma_f32_16x16x32_bf16 v[86:89], v[196:199], v[62:65], v[86:89]
	v_mfma_f32_16x16x32_bf16 v[62:65], v[204:207], v[62:65], v[70:73]
	v_mfma_f32_16x16x32_bf16 v[54:57], v[196:199], v[94:97], v[54:57]
	v_mfma_f32_16x16x32_bf16 v[50:53], v[204:207], v[94:97], v[50:53]
	v_mfma_f32_16x16x32_bf16 v[46:49], v[196:199], v[208:211], v[46:49]
	v_mfma_f32_16x16x32_bf16 v[42:45], v[204:207], v[208:211], v[42:45]
	v_mfma_f32_16x16x32_bf16 v[38:41], v[196:199], v[216:219], v[38:41]
	v_mfma_f32_16x16x32_bf16 v[34:37], v[204:207], v[216:219], v[34:37]
	v_mfma_f32_16x16x32_bf16 v[122:125], v[200:203], v[78:81], v[86:89]
	v_mfma_f32_16x16x32_bf16 v[114:117], v[224:227], v[78:81], v[62:65]
	v_mfma_f32_16x16x32_bf16 v[110:113], v[200:203], v[192:195], v[54:57]
	v_mfma_f32_16x16x32_bf16 v[102:105], v[224:227], v[192:195], v[50:53]
	v_mfma_f32_16x16x32_bf16 v[94:97], v[200:203], v[212:215], v[46:49]
	v_mfma_f32_16x16x32_bf16 v[86:89], v[224:227], v[212:215], v[42:45]
	v_mfma_f32_16x16x32_bf16 v[78:81], v[200:203], v[220:223], v[38:41]
	v_mfma_f32_16x16x32_bf16 v[70:73], v[224:227], v[220:223], v[34:37]
	s_setprio 0
	s_barrier
	s_nop 0
	ds_read_b128 v[34:37], v141 offset:49152
	ds_read_b128 v[42:45], v141 offset:50176
	ds_read_b128 v[192:195], v141 offset:51200
	ds_read_b128 v[208:211], v141 offset:52224
	ds_read_b128 v[212:215], v141 offset:53248
	ds_read_b128 v[216:219], v141 offset:54272
	ds_read_b128 v[220:223], v141 offset:55296
	ds_read_b128 v[228:231], v141 offset:56320
	s_barrier
	s_waitcnt lgkmcnt(0)
	s_setprio 1
	s_waitcnt lgkmcnt(0)
	v_mfma_f32_16x16x32_bf16 v[30:33], v[176:179], v[34:37], v[30:33]
	v_mfma_f32_16x16x32_bf16 v[26:29], v[184:187], v[34:37], v[26:29]
	v_mfma_f32_16x16x32_bf16 v[22:25], v[176:179], v[192:195], v[22:25]
	v_mfma_f32_16x16x32_bf16 v[18:21], v[184:187], v[192:195], v[18:21]
	v_mfma_f32_16x16x32_bf16 v[14:17], v[176:179], v[212:215], v[14:17]
	v_mfma_f32_16x16x32_bf16 v[10:13], v[184:187], v[212:215], v[10:13]
	v_mfma_f32_16x16x32_bf16 v[6:9], v[176:179], v[220:223], v[6:9]
	v_mfma_f32_16x16x32_bf16 v[2:5], v[184:187], v[220:223], v[2:5]
	v_mfma_f32_16x16x32_bf16 v[62:65], v[180:183], v[42:45], v[30:33]
	v_mfma_f32_16x16x32_bf16 v[54:57], v[188:191], v[42:45], v[26:29]
	v_mfma_f32_16x16x32_bf16 v[46:49], v[180:183], v[208:211], v[22:25]
	v_mfma_f32_16x16x32_bf16 v[38:41], v[188:191], v[208:211], v[18:21]
	v_mfma_f32_16x16x32_bf16 v[30:33], v[180:183], v[216:219], v[14:17]
	v_mfma_f32_16x16x32_bf16 v[22:25], v[188:191], v[216:219], v[10:13]
	v_mfma_f32_16x16x32_bf16 v[14:17], v[180:183], v[228:231], v[6:9]
	v_mfma_f32_16x16x32_bf16 v[6:9], v[188:191], v[228:231], v[2:5]
	s_setprio 0
	s_setprio 1
	v_mfma_f32_16x16x32_bf16 v[2:5], v[196:199], v[34:37], v[58:61]
	v_mfma_f32_16x16x32_bf16 v[58:61], v[200:203], v[42:45], v[2:5]
	v_mfma_f32_16x16x32_bf16 v[2:5], v[204:207], v[34:37], v[144:147]
	v_mfma_f32_16x16x32_bf16 v[50:53], v[224:227], v[42:45], v[2:5]
	v_mfma_f32_16x16x32_bf16 v[2:5], v[196:199], v[192:195], v[148:151]
	v_mfma_f32_16x16x32_bf16 v[42:45], v[200:203], v[208:211], v[2:5]
	v_mfma_f32_16x16x32_bf16 v[2:5], v[204:207], v[192:195], v[156:159]
	v_mfma_f32_16x16x32_bf16 v[34:37], v[224:227], v[208:211], v[2:5]
	v_mfma_f32_16x16x32_bf16 v[2:5], v[196:199], v[212:215], v[160:163]
	v_mfma_f32_16x16x32_bf16 v[26:29], v[200:203], v[216:219], v[2:5]
	v_mfma_f32_16x16x32_bf16 v[2:5], v[204:207], v[212:215], v[164:167]
	v_mfma_f32_16x16x32_bf16 v[18:21], v[224:227], v[216:219], v[2:5]
	v_mfma_f32_16x16x32_bf16 v[2:5], v[196:199], v[220:223], v[168:171]
	v_mfma_f32_16x16x32_bf16 v[10:13], v[200:203], v[228:231], v[2:5]
	v_mfma_f32_16x16x32_bf16 v[2:5], v[204:207], v[220:223], v[172:175]
	v_mfma_f32_16x16x32_bf16 v[2:5], v[224:227], v[228:231], v[2:5]
	s_setprio 0
	s_barrier
	s_and_saveexec_b64 s[48:49], s[4:5]
	s_cbranch_execz .LBB0_458
	s_barrier

; #define LDA(dst, b, h)                                                                                     \
;   _Pragma("unroll") for (int m = 0; m < 4; ++m) _Pragma("unroll") for (int k = 0; k < 2; ++k) dst[m][k] = \
;       *reinterpret_cast<const bf16x8*>(shmc + aL + (((b) * 2 + (h)) * 16384 + (m * 2 + k) * 1024))
; #define LDB(dst, b, h)                                                                                     \
;   _Pragma("unroll") for (int n = 0; n < 2; ++n) _Pragma("unroll") for (int k = 0; k < 2; ++k) dst[n][k] = \
;       *reinterpret_cast<const bf16x8*>(shmc + bL + (((b) * 2 + (h)) * 16384 + (n * 2 + k) * 1024))
; #define OPAQ asm volatile("" : "+v"(aL), "+v"(bL))
; #define WAIT_V(n) asm volatile("s_waitcnt vmcnt(" #n ")" ::: "memory")
; #define WAIT_L(n) asm volatile("s_waitcnt lgkmcnt(" #n ")" ::: "memory")
; #define BAR __builtin_amdgcn_s_barrier()
; #define SCHED __builtin_amdgcn_sched_barrier(0)
; template <int EPI>
; __device__ __forceinline__ void phase_gemm(const Params& p, const GemmDesc& d, char* shmc) {
;     ...
;     for (int t = 0; t < nt - 2; t += 2) {
;       OPAQ;
;       LDB(B0, 0, 0); SCHED; LDA(At, 0, 0); STAGE_A(SA(1, 1), 1, t + 1);
;       WAIT_L(8); BAR; WAIT_L(0); MMA(0, 0, At, B0); BAR; SCHED;
;       LDB(B1, 0, 1); STAGE_B(SB(0, 0), 0, t + 2);
;       BAR; WAIT_L(0); MMA(0, 1, At, B1); BAR;
;       LDA(At, 0, 1); STAGE_A(SA(0, 0), 0, t + 2);
;       BAR; WAIT_L(0); MMA(1, 0, At, B0); BAR; SCHED;
;       STAGE_B(SB(0, 1), 1, t + 2);
;       WAIT_V(6); BAR; MMA(1, 1, At, B1); BAR;
;       LDB(B0, 1, 0); SCHED; LDA(At, 1, 0); STAGE_A(SA(0, 1), 1, t + 2);
;       WAIT_L(8); BAR; WAIT_L(0); MMA(0, 0, At, B0); BAR; SCHED;
;       LDB(B1, 1, 1); STAGE_B(SB(1, 0), 0, t + 3);
;       BAR; WAIT_L(0); MMA(0, 1, At, B1); BAR;
;       LDA(At, 1, 1); STAGE_A(SA(1, 0), 0, t + 3);
;       BAR; WAIT_L(0); MMA(1, 0, At, B0); BAR; SCHED;
;       STAGE_B(SB(1, 1), 1, t + 3);
;       WAIT_V(6); BAR; MMA(1, 1, At, B1); BAR;
;     }
.LBB0_598:
	s_nop 0
	s_setprio 0
	ds_read_b128 v[138:141], v179
	ds_read_b128 v[142:145], v179 offset:1024
	ds_read_b128 v[146:149], v179 offset:2048
	ds_read_b128 v[150:153], v179 offset:3072
	ds_read_b128 v[206:209], v179 offset:16384
	ds_read_b128 v[210:213], v179 offset:17408
	ds_read_b128 v[214:217], v179 offset:18432
	ds_read_b128 v[218:221], v179 offset:19456
	ds_read_b128 v[154:157], v177
	ds_read_b128 v[158:161], v177 offset:1024
	ds_read_b128 v[182:185], v177 offset:2048
	ds_read_b128 v[186:189], v177 offset:3072
	ds_read_b128 v[190:193], v177 offset:4096
	ds_read_b128 v[194:197], v177 offset:5120
	ds_read_b128 v[198:201], v177 offset:6144
	ds_read_b128 v[202:205], v177 offset:7168
	s_add_i32 s88, s68, 0xc000
	s_mov_b32 m0, s88
	s_nop 0
	global_load_lds_dwordx4 v222, s[98:99]
	s_add_i32 s89, s68, 0xe000
	s_mov_b32 m0, s89
	s_nop 0
	global_load_lds_dwordx4 v223, s[98:99]
	s_waitcnt vmcnt(8)
	s_waitcnt lgkmcnt(0)
	s_setprio 1
	s_barrier
	v_mfma_f32_16x16x32_bf16 v[126:129], v[154:157], v[138:141], v[126:129]
	v_mfma_f32_16x16x32_bf16 v[122:125], v[154:157], v[146:149], v[122:125]
	v_mfma_f32_16x16x32_bf16 v[118:121], v[182:185], v[138:141], v[118:121]
	v_mfma_f32_16x16x32_bf16 v[114:117], v[182:185], v[146:149], v[114:117]
	v_mfma_f32_16x16x32_bf16 v[110:113], v[190:193], v[138:141], v[110:113]
	v_mfma_f32_16x16x32_bf16 v[106:109], v[190:193], v[146:149], v[106:109]
	v_mfma_f32_16x16x32_bf16 v[102:105], v[198:201], v[138:141], v[102:105]
	v_mfma_f32_16x16x32_bf16 v[94:97], v[198:201], v[146:149], v[94:97]
	v_mfma_f32_16x16x32_bf16 v[126:129], v[158:161], v[142:145], v[126:129]
	v_mfma_f32_16x16x32_bf16 v[122:125], v[158:161], v[150:153], v[122:125]
	v_mfma_f32_16x16x32_bf16 v[118:121], v[186:189], v[142:145], v[118:121]
	v_mfma_f32_16x16x32_bf16 v[114:117], v[186:189], v[150:153], v[114:117]
	v_mfma_f32_16x16x32_bf16 v[110:113], v[194:197], v[142:145], v[110:113]
	v_mfma_f32_16x16x32_bf16 v[106:109], v[194:197], v[150:153], v[106:109]
	v_mfma_f32_16x16x32_bf16 v[102:105], v[202:205], v[142:145], v[102:105]
	v_mfma_f32_16x16x32_bf16 v[94:97], v[202:205], v[150:153], v[94:97]
	v_mfma_f32_16x16x32_bf16 v[50:53], v[154:157], v[206:209], v[50:53]
	v_mfma_f32_16x16x32_bf16 v[42:45], v[154:157], v[214:217], v[42:45]
	v_mfma_f32_16x16x32_bf16 v[38:41], v[182:185], v[206:209], v[38:41]
	v_mfma_f32_16x16x32_bf16 v[34:37], v[182:185], v[214:217], v[34:37]
	v_mfma_f32_16x16x32_bf16 v[30:33], v[190:193], v[206:209], v[30:33]
	v_mfma_f32_16x16x32_bf16 v[26:29], v[190:193], v[214:217], v[26:29]
	v_mfma_f32_16x16x32_bf16 v[22:25], v[198:201], v[206:209], v[22:25]
	v_mfma_f32_16x16x32_bf16 v[18:21], v[198:201], v[214:217], v[18:21]
	v_mfma_f32_16x16x32_bf16 v[50:53], v[158:161], v[210:213], v[50:53]
	v_mfma_f32_16x16x32_bf16 v[42:45], v[158:161], v[218:221], v[42:45]
	v_mfma_f32_16x16x32_bf16 v[38:41], v[186:189], v[210:213], v[38:41]
	v_mfma_f32_16x16x32_bf16 v[34:37], v[186:189], v[218:221], v[34:37]
	v_mfma_f32_16x16x32_bf16 v[30:33], v[194:197], v[210:213], v[30:33]
	v_mfma_f32_16x16x32_bf16 v[26:29], v[194:197], v[218:221], v[26:29]
	v_mfma_f32_16x16x32_bf16 v[22:25], v[202:205], v[210:213], v[22:25]
	v_mfma_f32_16x16x32_bf16 v[18:21], v[202:205], v[218:221], v[18:21]
	s_barrier
	s_setprio 0
	ds_read_b128 v[154:157], v177 offset:16384
	ds_read_b128 v[158:161], v177 offset:17408
	ds_read_b128 v[182:185], v177 offset:18432
	ds_read_b128 v[186:189], v177 offset:19456
	ds_read_b128 v[190:193], v177 offset:20480
	ds_read_b128 v[194:197], v177 offset:21504
	ds_read_b128 v[198:201], v177 offset:22528
	ds_read_b128 v[202:205], v177 offset:23552
	s_mov_b32 m0, s69
	s_nop 0
	global_load_lds_dwordx4 v224, s[100:101]
	s_mov_b32 m0, s70
	s_nop 0
	global_load_lds_dwordx4 v225, s[100:101]
	s_mov_b32 m0, s68
	s_nop 0
	global_load_lds_dwordx4 v226, s[98:99]
	s_mov_b32 m0, s71
	s_nop 0
	global_load_lds_dwordx4 v227, s[98:99]
	s_mov_b32 m0, s76
	s_nop 0
	global_load_lds_dwordx4 v228, s[100:101]
	s_mov_b32 m0, s77
	s_nop 0
	global_load_lds_dwordx4 v229, s[100:101]
	s_waitcnt vmcnt(8)
	s_waitcnt lgkmcnt(0)
	s_setprio 1
	s_barrier
	v_mfma_f32_16x16x32_bf16 v[14:17], v[154:157], v[138:141], v[14:17]
	v_mfma_f32_16x16x32_bf16 v[10:13], v[154:157], v[146:149], v[10:13]
	v_mfma_f32_16x16x32_bf16 v[6:9], v[182:185], v[138:141], v[6:9]
	v_mfma_f32_16x16x32_bf16 v[2:5], v[182:185], v[146:149], v[2:5]
	v_mfma_f32_16x16x32_bf16 v[46:49], v[190:193], v[138:141], v[46:49]
	v_mfma_f32_16x16x32_bf16 v[54:57], v[190:193], v[146:149], v[54:57]
	v_mfma_f32_16x16x32_bf16 v[58:61], v[198:201], v[138:141], v[58:61]
	v_mfma_f32_16x16x32_bf16 v[62:65], v[198:201], v[146:149], v[62:65]
	v_mfma_f32_16x16x32_bf16 v[14:17], v[158:161], v[142:145], v[14:17]
	v_mfma_f32_16x16x32_bf16 v[10:13], v[158:161], v[150:153], v[10:13]
	v_mfma_f32_16x16x32_bf16 v[6:9], v[186:189], v[142:145], v[6:9]
	v_mfma_f32_16x16x32_bf16 v[2:5], v[186:189], v[150:153], v[2:5]
	v_mfma_f32_16x16x32_bf16 v[46:49], v[194:197], v[142:145], v[46:49]
	v_mfma_f32_16x16x32_bf16 v[54:57], v[194:197], v[150:153], v[54:57]
	v_mfma_f32_16x16x32_bf16 v[58:61], v[202:205], v[142:145], v[58:61]
	v_mfma_f32_16x16x32_bf16 v[62:65], v[202:205], v[150:153], v[62:65]
	v_mfma_f32_16x16x32_bf16 v[66:69], v[154:157], v[206:209], v[66:69]
	v_mfma_f32_16x16x32_bf16 v[70:73], v[154:157], v[214:217], v[70:73]
	v_mfma_f32_16x16x32_bf16 v[74:77], v[182:185], v[206:209], v[74:77]
	v_mfma_f32_16x16x32_bf16 v[78:81], v[182:185], v[214:217], v[78:81]
	v_mfma_f32_16x16x32_bf16 v[82:85], v[190:193], v[206:209], v[82:85]
	v_mfma_f32_16x16x32_bf16 v[86:89], v[190:193], v[214:217], v[86:89]
	v_mfma_f32_16x16x32_bf16 v[90:93], v[198:201], v[206:209], v[90:93]
	v_mfma_f32_16x16x32_bf16 v[98:101], v[198:201], v[214:217], v[98:101]
	v_mfma_f32_16x16x32_bf16 v[66:69], v[158:161], v[210:213], v[66:69]
	v_mfma_f32_16x16x32_bf16 v[70:73], v[158:161], v[218:221], v[70:73]
	v_mfma_f32_16x16x32_bf16 v[74:77], v[186:189], v[210:213], v[74:77]
	v_mfma_f32_16x16x32_bf16 v[78:81], v[186:189], v[218:221], v[78:81]
	v_mfma_f32_16x16x32_bf16 v[82:85], v[194:197], v[210:213], v[82:85]
	v_mfma_f32_16x16x32_bf16 v[86:89], v[194:197], v[218:221], v[86:89]
	v_mfma_f32_16x16x32_bf16 v[90:93], v[202:205], v[210:213], v[90:93]
	v_mfma_f32_16x16x32_bf16 v[98:101], v[202:205], v[218:221], v[98:101]
	s_barrier
; #define LDA(dst, b, h)                                                                                     \
;   _Pragma("unroll") for (int m = 0; m < 4; ++m) _Pragma("unroll") for (int k = 0; k < 2; ++k) dst[m][k] = \
;       *reinterpret_cast<const bf16x8*>(shmc + aL + (((b) * 2 + (h)) * 16384 + (m * 2 + k) * 1024))
; #define LDB(dst, b, h)                                                                                     \
;   _Pragma("unroll") for (int n = 0; n < 2; ++n) _Pragma("unroll") for (int k = 0; k < 2; ++k) dst[n][k] = \
;       *reinterpret_cast<const bf16x8*>(shmc + bL + (((b) * 2 + (h)) * 16384 + (n * 2 + k) * 1024))
; #define OPAQ asm volatile("" : "+v"(aL), "+v"(bL))
; #define WAIT_V(n) asm volatile("s_waitcnt vmcnt(" #n ")" ::: "memory")
; #define WAIT_L(n) asm volatile("s_waitcnt lgkmcnt(" #n ")" ::: "memory")
; #define BAR __builtin_amdgcn_s_barrier()
; #define SCHED __builtin_amdgcn_sched_barrier(0)
; template <int EPI>
; __device__ __forceinline__ void phase_gemm(const Params& p, const GemmDesc& d, char* shmc) {
;     ...
;     for (int t = 0; t < nt - 2; t += 2) {
;       OPAQ;
;       LDB(B0, 0, 0); SCHED; LDA(At, 0, 0); STAGE_A(SA(1, 1), 1, t + 1);
;       WAIT_L(8); BAR; WAIT_L(0); MMA(0, 0, At, B0); BAR; SCHED;
;       LDB(B1, 0, 1); STAGE_B(SB(0, 0), 0, t + 2);
;       BAR; WAIT_L(0); MMA(0, 1, At, B1); BAR;
;       LDA(At, 0, 1); STAGE_A(SA(0, 0), 0, t + 2);
;       BAR; WAIT_L(0); MMA(1, 0, At, B0); BAR; SCHED;
;       STAGE_B(SB(0, 1), 1, t + 2);
;       WAIT_V(6); BAR; MMA(1, 1, At, B1); BAR;
;       LDB(B0, 1, 0); SCHED; LDA(At, 1, 0); STAGE_A(SA(0, 1), 1, t + 2);
;       WAIT_L(8); BAR; WAIT_L(0); MMA(0, 0, At, B0); BAR; SCHED;
;       LDB(B1, 1, 1); STAGE_B(SB(1, 0), 0, t + 3);
;       BAR; WAIT_L(0); MMA(0, 1, At, B1); BAR;
;       LDA(At, 1, 1); STAGE_A(SA(1, 0), 0, t + 3);
;       BAR; WAIT_L(0); MMA(1, 0, At, B0); BAR; SCHED;
;       STAGE_B(SB(1, 1), 1, t + 3);
;       WAIT_V(6); BAR; MMA(1, 1, At, B1); BAR;
;     }
	s_setprio 0
	ds_read_b128 v[138:141], v179 offset:32768
	ds_read_b128 v[142:145], v179 offset:33792
	ds_read_b128 v[146:149], v179 offset:34816
	ds_read_b128 v[150:153], v179 offset:35840
	ds_read_b128 v[206:209], v179 offset:49152
	ds_read_b128 v[210:213], v179 offset:50176
	ds_read_b128 v[214:217], v179 offset:51200
	ds_read_b128 v[218:221], v179 offset:52224
	ds_read_b128 v[154:157], v177 offset:32768
	ds_read_b128 v[158:161], v177 offset:33792
	ds_read_b128 v[182:185], v177 offset:34816
	ds_read_b128 v[186:189], v177 offset:35840
	ds_read_b128 v[190:193], v177 offset:36864
	ds_read_b128 v[194:197], v177 offset:37888
	ds_read_b128 v[198:201], v177 offset:38912
	ds_read_b128 v[202:205], v177 offset:39936
	s_mov_b32 m0, s80
	s_nop 0
	global_load_lds_dwordx4 v230, s[98:99]
	s_mov_b32 m0, s81
	s_nop 0
	global_load_lds_dwordx4 v231, s[98:99]
	s_waitcnt vmcnt(8)
	s_waitcnt lgkmcnt(0)
	s_setprio 1
	s_barrier
	v_mfma_f32_16x16x32_bf16 v[126:129], v[154:157], v[138:141], v[126:129]
	v_mfma_f32_16x16x32_bf16 v[122:125], v[154:157], v[146:149], v[122:125]
	v_mfma_f32_16x16x32_bf16 v[118:121], v[182:185], v[138:141], v[118:121]
	v_mfma_f32_16x16x32_bf16 v[114:117], v[182:185], v[146:149], v[114:117]
	v_mfma_f32_16x16x32_bf16 v[110:113], v[190:193], v[138:141], v[110:113]
	v_mfma_f32_16x16x32_bf16 v[106:109], v[190:193], v[146:149], v[106:109]
	v_mfma_f32_16x16x32_bf16 v[102:105], v[198:201], v[138:141], v[102:105]
	v_mfma_f32_16x16x32_bf16 v[94:97], v[198:201], v[146:149], v[94:97]
	v_mfma_f32_16x16x32_bf16 v[126:129], v[158:161], v[142:145], v[126:129]
	v_mfma_f32_16x16x32_bf16 v[122:125], v[158:161], v[150:153], v[122:125]
	v_mfma_f32_16x16x32_bf16 v[118:121], v[186:189], v[142:145], v[118:121]
	v_mfma_f32_16x16x32_bf16 v[114:117], v[186:189], v[150:153], v[114:117]
	v_mfma_f32_16x16x32_bf16 v[110:113], v[194:197], v[142:145], v[110:113]
	v_mfma_f32_16x16x32_bf16 v[106:109], v[194:197], v[150:153], v[106:109]
	v_mfma_f32_16x16x32_bf16 v[102:105], v[202:205], v[142:145], v[102:105]
	v_mfma_f32_16x16x32_bf16 v[94:97], v[202:205], v[150:153], v[94:97]
	v_mfma_f32_16x16x32_bf16 v[50:53], v[154:157], v[206:209], v[50:53]
	v_mfma_f32_16x16x32_bf16 v[42:45], v[154:157], v[214:217], v[42:45]
	v_mfma_f32_16x16x32_bf16 v[38:41], v[182:185], v[206:209], v[38:41]
	v_mfma_f32_16x16x32_bf16 v[34:37], v[182:185], v[214:217], v[34:37]
	v_mfma_f32_16x16x32_bf16 v[30:33], v[190:193], v[206:209], v[30:33]
	v_mfma_f32_16x16x32_bf16 v[26:29], v[190:193], v[214:217], v[26:29]
	v_mfma_f32_16x16x32_bf16 v[22:25], v[198:201], v[206:209], v[22:25]
	v_mfma_f32_16x16x32_bf16 v[18:21], v[198:201], v[214:217], v[18:21]
	v_mfma_f32_16x16x32_bf16 v[50:53], v[158:161], v[210:213], v[50:53]
	v_mfma_f32_16x16x32_bf16 v[42:45], v[158:161], v[218:221], v[42:45]
	v_mfma_f32_16x16x32_bf16 v[38:41], v[186:189], v[210:213], v[38:41]
	v_mfma_f32_16x16x32_bf16 v[34:37], v[186:189], v[218:221], v[34:37]
	v_mfma_f32_16x16x32_bf16 v[30:33], v[194:197], v[210:213], v[30:33]
	v_mfma_f32_16x16x32_bf16 v[26:29], v[194:197], v[218:221], v[26:29]
	v_mfma_f32_16x16x32_bf16 v[22:25], v[202:205], v[210:213], v[22:25]
	v_mfma_f32_16x16x32_bf16 v[18:21], v[202:205], v[218:221], v[18:21]
	s_barrier
	s_setprio 0
	ds_read_b128 v[154:157], v177 offset:49152
	ds_read_b128 v[158:161], v177 offset:50176
	ds_read_b128 v[182:185], v177 offset:51200
	ds_read_b128 v[186:189], v177 offset:52224
	ds_read_b128 v[190:193], v177 offset:53248
	ds_read_b128 v[194:197], v177 offset:54272
	ds_read_b128 v[198:201], v177 offset:55296
	ds_read_b128 v[202:205], v177 offset:56320
	s_mov_b32 m0, s61
	s_nop 0
	global_load_lds_dwordx4 v232, s[100:101]
	s_mov_b32 m0, s78
	s_nop 0
	global_load_lds_dwordx4 v233, s[100:101]
	s_mov_b32 m0, s79
	s_nop 0
	global_load_lds_dwordx4 v234, s[98:99]
	s_mov_b32 m0, s86
	s_nop 0
	global_load_lds_dwordx4 v235, s[98:99]
	s_mov_b32 m0, s64
	s_nop 0
	global_load_lds_dwordx4 v236, s[100:101]
	s_mov_b32 m0, s65
	s_nop 0
	global_load_lds_dwordx4 v237, s[100:101]
	s_add_i32 s87, s87, 2
	s_add_u32 s62, s62, 0x100
	s_addc_u32 s63, s63, 0
	s_add_u32 s98, s98, 0x100
	s_addc_u32 s99, s99, 0
	s_add_u32 s100, s100, 0x100
	s_addc_u32 s101, s101, 0
	s_cmp_gt_u32 s87, 27
	s_waitcnt vmcnt(8)
	s_waitcnt lgkmcnt(0)
	s_setprio 1
	s_barrier
	v_mfma_f32_16x16x32_bf16 v[14:17], v[154:157], v[138:141], v[14:17]
	v_mfma_f32_16x16x32_bf16 v[10:13], v[154:157], v[146:149], v[10:13]
	v_mfma_f32_16x16x32_bf16 v[6:9], v[182:185], v[138:141], v[6:9]
	v_mfma_f32_16x16x32_bf16 v[2:5], v[182:185], v[146:149], v[2:5]
	v_mfma_f32_16x16x32_bf16 v[46:49], v[190:193], v[138:141], v[46:49]
	v_mfma_f32_16x16x32_bf16 v[54:57], v[190:193], v[146:149], v[54:57]
	v_mfma_f32_16x16x32_bf16 v[58:61], v[198:201], v[138:141], v[58:61]
	v_mfma_f32_16x16x32_bf16 v[62:65], v[198:201], v[146:149], v[62:65]
	v_mfma_f32_16x16x32_bf16 v[14:17], v[158:161], v[142:145], v[14:17]
	v_mfma_f32_16x16x32_bf16 v[10:13], v[158:161], v[150:153], v[10:13]
	v_mfma_f32_16x16x32_bf16 v[6:9], v[186:189], v[142:145], v[6:9]
	v_mfma_f32_16x16x32_bf16 v[2:5], v[186:189], v[150:153], v[2:5]
	v_mfma_f32_16x16x32_bf16 v[46:49], v[194:197], v[142:145], v[46:49]
	v_mfma_f32_16x16x32_bf16 v[54:57], v[194:197], v[150:153], v[54:57]
	v_mfma_f32_16x16x32_bf16 v[58:61], v[202:205], v[142:145], v[58:61]
	v_mfma_f32_16x16x32_bf16 v[62:65], v[202:205], v[150:153], v[62:65]
	v_mfma_f32_16x16x32_bf16 v[66:69], v[154:157], v[206:209], v[66:69]
	v_mfma_f32_16x16x32_bf16 v[70:73], v[154:157], v[214:217], v[70:73]
	v_mfma_f32_16x16x32_bf16 v[74:77], v[182:185], v[206:209], v[74:77]
	v_mfma_f32_16x16x32_bf16 v[78:81], v[182:185], v[214:217], v[78:81]
	v_mfma_f32_16x16x32_bf16 v[82:85], v[190:193], v[206:209], v[82:85]
	v_mfma_f32_16x16x32_bf16 v[86:89], v[190:193], v[214:217], v[86:89]
	v_mfma_f32_16x16x32_bf16 v[90:93], v[198:201], v[206:209], v[90:93]
	v_mfma_f32_16x16x32_bf16 v[98:101], v[198:201], v[214:217], v[98:101]
	v_mfma_f32_16x16x32_bf16 v[66:69], v[158:161], v[210:213], v[66:69]
	v_mfma_f32_16x16x32_bf16 v[70:73], v[158:161], v[218:221], v[70:73]
	v_mfma_f32_16x16x32_bf16 v[74:77], v[186:189], v[210:213], v[74:77]
	v_mfma_f32_16x16x32_bf16 v[78:81], v[186:189], v[218:221], v[78:81]
	v_mfma_f32_16x16x32_bf16 v[82:85], v[194:197], v[210:213], v[82:85]
	v_mfma_f32_16x16x32_bf16 v[86:89], v[194:197], v[218:221], v[86:89]
	v_mfma_f32_16x16x32_bf16 v[90:93], v[202:205], v[210:213], v[90:93]
	v_mfma_f32_16x16x32_bf16 v[98:101], v[202:205], v[218:221], v[98:101]
	s_barrier
; #define LDA(dst, b, h)                                                                                     \
;   _Pragma("unroll") for (int m = 0; m < 4; ++m) _Pragma("unroll") for (int k = 0; k < 2; ++k) dst[m][k] = \
;       *reinterpret_cast<const bf16x8*>(shmc + aL + (((b) * 2 + (h)) * 16384 + (m * 2 + k) * 1024))
; #define LDB(dst, b, h)                                                                                     \
;   _Pragma("unroll") for (int n = 0; n < 2; ++n) _Pragma("unroll") for (int k = 0; k < 2; ++k) dst[n][k] = \
;       *reinterpret_cast<const bf16x8*>(shmc + bL + (((b) * 2 + (h)) * 16384 + (n * 2 + k) * 1024))
; #define OPAQ asm volatile("" : "+v"(aL), "+v"(bL))
; #define WAIT_V(n) asm volatile("s_waitcnt vmcnt(" #n ")" ::: "memory")
; #define WAIT_L(n) asm volatile("s_waitcnt lgkmcnt(" #n ")" ::: "memory")
; #define BAR __builtin_amdgcn_s_barrier()
; template <int EPI>
; __device__ __forceinline__ void phase_gemm(const Params& p, const GemmDesc& d, char* shmc) {
;     ...
;     }
;     {
;       OPAQ;
;       LDB(B0, 0, 0); LDA(At, 0, 0); STAGE_A(SA(1, 1), 1, nt - 1);
;       BAR; WAIT_L(0); MMA(0, 0, At, B0); BAR;
;       LDB(B1, 0, 1); BAR; WAIT_L(0); MMA(0, 1, At, B1); BAR;
;       LDA(At, 0, 1); WAIT_V(4); BAR; WAIT_L(0); MMA(1, 0, At, B0); MMA(1, 1, At, B1); BAR;
;     }
	s_cbranch_scc0 .LBB0_598
	s_setprio 0
	s_add_u32 s8, s8, 0x80f80
	s_addc_u32 s9, s9, 0
	v_add_u32_e32 v175, 0, v179
	v_add_u32_e32 v176, 0, v177
	s_mov_b32 m0, s88
	ds_read_b128 v[130:133], v175
	ds_read_b128 v[134:137], v175 offset:1024
	ds_read_b128 v[138:141], v175 offset:2048
	ds_read_b128 v[142:145], v175 offset:3072
	ds_read_b128 v[146:149], v176
	ds_read_b128 v[150:153], v176 offset:1024
	ds_read_b128 v[154:157], v176 offset:2048
	ds_read_b128 v[158:161], v176 offset:3072
	ds_read_b128 v[182:185], v176 offset:4096
	ds_read_b128 v[186:189], v176 offset:5120
	ds_read_b128 v[190:193], v176 offset:6144
	ds_read_b128 v[194:197], v176 offset:7168
	global_load_lds_dwordx4 v162, s[8:9]
	s_mov_b32 m0, s89
	s_nop 0
	global_load_lds_dwordx4 v174, s[8:9]
	s_waitcnt vmcnt(8)
	s_barrier
	s_waitcnt lgkmcnt(0)
	s_setprio 1
	s_waitcnt lgkmcnt(0)
	v_mfma_f32_16x16x32_bf16 v[126:129], v[146:149], v[130:133], v[126:129]
	v_mfma_f32_16x16x32_bf16 v[122:125], v[146:149], v[138:141], v[122:125]
	v_mfma_f32_16x16x32_bf16 v[114:117], v[154:157], v[138:141], v[114:117]
	v_mfma_f32_16x16x32_bf16 v[110:113], v[182:185], v[130:133], v[110:113]
	v_mfma_f32_16x16x32_bf16 v[126:129], v[150:153], v[134:137], v[126:129]
	v_mfma_f32_16x16x32_bf16 v[122:125], v[150:153], v[142:145], v[122:125]
	v_mfma_f32_16x16x32_bf16 v[118:121], v[154:157], v[130:133], v[118:121]
	v_mfma_f32_16x16x32_bf16 v[114:117], v[158:161], v[142:145], v[114:117]
	v_mfma_f32_16x16x32_bf16 v[110:113], v[186:189], v[134:137], v[110:113]
	v_mfma_f32_16x16x32_bf16 v[106:109], v[182:185], v[138:141], v[106:109]
	v_mfma_f32_16x16x32_bf16 v[102:105], v[190:193], v[130:133], v[102:105]
	v_mfma_f32_16x16x32_bf16 v[94:97], v[190:193], v[138:141], v[94:97]
	v_mfma_f32_16x16x32_bf16 v[118:121], v[158:161], v[134:137], v[118:121]
	v_mfma_f32_16x16x32_bf16 v[106:109], v[186:189], v[142:145], v[106:109]
	v_mfma_f32_16x16x32_bf16 v[102:105], v[194:197], v[134:137], v[102:105]
	v_mfma_f32_16x16x32_bf16 v[94:97], v[194:197], v[142:145], v[94:97]
	s_setprio 0
	s_barrier
	ds_read_b128 v[198:201], v175 offset:16384
	ds_read_b128 v[202:205], v175 offset:17408
	ds_read_b128 v[206:209], v175 offset:18432
	ds_read_b128 v[210:213], v175 offset:19456
	s_barrier
	s_waitcnt lgkmcnt(0)
	s_setprio 1
	s_waitcnt lgkmcnt(0)
	v_mfma_f32_16x16x32_bf16 v[50:53], v[146:149], v[198:201], v[50:53]
	v_mfma_f32_16x16x32_bf16 v[42:45], v[146:149], v[206:209], v[42:45]
	v_mfma_f32_16x16x32_bf16 v[38:41], v[154:157], v[198:201], v[38:41]
	v_mfma_f32_16x16x32_bf16 v[30:33], v[182:185], v[198:201], v[30:33]
	v_mfma_f32_16x16x32_bf16 v[22:25], v[190:193], v[198:201], v[22:25]
	v_mfma_f32_16x16x32_bf16 v[50:53], v[150:153], v[202:205], v[50:53]
	v_mfma_f32_16x16x32_bf16 v[42:45], v[150:153], v[210:213], v[42:45]
	v_mfma_f32_16x16x32_bf16 v[38:41], v[158:161], v[202:205], v[38:41]
	v_mfma_f32_16x16x32_bf16 v[34:37], v[154:157], v[206:209], v[34:37]
	v_mfma_f32_16x16x32_bf16 v[30:33], v[186:189], v[202:205], v[30:33]
	v_mfma_f32_16x16x32_bf16 v[26:29], v[182:185], v[206:209], v[26:29]
	v_mfma_f32_16x16x32_bf16 v[22:25], v[194:197], v[202:205], v[22:25]
	v_mfma_f32_16x16x32_bf16 v[18:21], v[190:193], v[206:209], v[18:21]
	v_mfma_f32_16x16x32_bf16 v[34:37], v[158:161], v[210:213], v[34:37]
	v_mfma_f32_16x16x32_bf16 v[26:29], v[186:189], v[210:213], v[26:29]
	v_mfma_f32_16x16x32_bf16 v[18:21], v[194:197], v[210:213], v[18:21]
	s_setprio 0
	s_barrier
	ds_read_b128 v[146:149], v176 offset:16384
	ds_read_b128 v[150:153], v176 offset:17408
	ds_read_b128 v[154:157], v176 offset:18432
	ds_read_b128 v[158:161], v176 offset:19456
	ds_read_b128 v[182:185], v176 offset:20480
	ds_read_b128 v[186:189], v176 offset:21504
	ds_read_b128 v[190:193], v176 offset:22528
	ds_read_b128 v[194:197], v176 offset:23552
	s_waitcnt vmcnt(4)
	s_barrier
	s_waitcnt lgkmcnt(0)
	s_setprio 1
	s_waitcnt lgkmcnt(0)
	v_mfma_f32_16x16x32_bf16 v[14:17], v[146:149], v[130:133], v[14:17]
	v_mfma_f32_16x16x32_bf16 v[6:9], v[154:157], v[130:133], v[6:9]
	v_mfma_f32_16x16x32_bf16 v[2:5], v[154:157], v[138:141], v[2:5]
	v_mfma_f32_16x16x32_bf16 v[46:49], v[182:185], v[130:133], v[46:49]
	v_mfma_f32_16x16x32_bf16 v[54:57], v[182:185], v[138:141], v[54:57]
	v_mfma_f32_16x16x32_bf16 v[58:61], v[190:193], v[130:133], v[58:61]
	v_mfma_f32_16x16x32_bf16 v[14:17], v[150:153], v[134:137], v[14:17]
	v_mfma_f32_16x16x32_bf16 v[10:13], v[146:149], v[138:141], v[10:13]
	v_mfma_f32_16x16x32_bf16 v[6:9], v[158:161], v[134:137], v[6:9]
	v_mfma_f32_16x16x32_bf16 v[2:5], v[158:161], v[142:145], v[2:5]
	v_mfma_f32_16x16x32_bf16 v[46:49], v[186:189], v[134:137], v[46:49]
	v_mfma_f32_16x16x32_bf16 v[54:57], v[186:189], v[142:145], v[54:57]
	v_mfma_f32_16x16x32_bf16 v[214:217], v[194:197], v[134:137], v[58:61]
	v_mfma_f32_16x16x32_bf16 v[58:61], v[190:193], v[138:141], v[62:65]
	v_mfma_f32_16x16x32_bf16 v[10:13], v[150:153], v[142:145], v[10:13]
	v_mfma_f32_16x16x32_bf16 v[218:221], v[194:197], v[142:145], v[58:61]
	s_setprio 0
	s_setprio 1
	v_mfma_f32_16x16x32_bf16 v[58:61], v[146:149], v[198:201], v[66:69]
	v_mfma_f32_16x16x32_bf16 v[222:225], v[150:153], v[202:205], v[58:61]
	v_mfma_f32_16x16x32_bf16 v[58:61], v[146:149], v[206:209], v[70:73]
	v_mfma_f32_16x16x32_bf16 v[226:229], v[150:153], v[210:213], v[58:61]
	v_mfma_f32_16x16x32_bf16 v[58:61], v[154:157], v[198:201], v[74:77]
	v_mfma_f32_16x16x32_bf16 v[230:233], v[158:161], v[202:205], v[58:61]
	v_mfma_f32_16x16x32_bf16 v[58:61], v[154:157], v[206:209], v[78:81]
	v_mfma_f32_16x16x32_bf16 v[234:237], v[158:161], v[210:213], v[58:61]
	v_mfma_f32_16x16x32_bf16 v[58:61], v[182:185], v[198:201], v[82:85]
	v_mfma_f32_16x16x32_bf16 v[238:241], v[186:189], v[202:205], v[58:61]
	v_mfma_f32_16x16x32_bf16 v[58:61], v[182:185], v[206:209], v[86:89]
	v_mfma_f32_16x16x32_bf16 v[182:185], v[186:189], v[210:213], v[58:61]
	v_mfma_f32_16x16x32_bf16 v[58:61], v[190:193], v[198:201], v[90:93]
	v_mfma_f32_16x16x32_bf16 v[186:189], v[194:197], v[202:205], v[58:61]
	v_mfma_f32_16x16x32_bf16 v[58:61], v[190:193], v[206:209], v[98:101]
	v_mfma_f32_16x16x32_bf16 v[190:193], v[194:197], v[210:213], v[58:61]
	s_setprio 0
	s_barrier
; #define LDA(dst, b, h)                                                                                     \
;   _Pragma("unroll") for (int m = 0; m < 4; ++m) _Pragma("unroll") for (int k = 0; k < 2; ++k) dst[m][k] = \
;       *reinterpret_cast<const bf16x8*>(shmc + aL + (((b) * 2 + (h)) * 16384 + (m * 2 + k) * 1024))
; #define LDB(dst, b, h)                                                                                     \
;   _Pragma("unroll") for (int n = 0; n < 2; ++n) _Pragma("unroll") for (int k = 0; k < 2; ++k) dst[n][k] = \
;       *reinterpret_cast<const bf16x8*>(shmc + bL + (((b) * 2 + (h)) * 16384 + (n * 2 + k) * 1024))
; #define WAIT_V(n) asm volatile("s_waitcnt vmcnt(" #n ")" ::: "memory")
; #define WAIT_L(n) asm volatile("s_waitcnt lgkmcnt(" #n ")" ::: "memory")
; #define BAR __builtin_amdgcn_s_barrier()
; template <int EPI>
; __device__ __forceinline__ void phase_gemm(const Params& p, const GemmDesc& d, char* shmc) {
;     ...
;     {
;       LDB(B0, 1, 0); LDA(At, 1, 0); WAIT_V(2); BAR; WAIT_L(0); MMA(0, 0, At, B0); BAR;
;       LDB(B1, 1, 1); WAIT_V(0); BAR; WAIT_L(0); MMA(0, 1, At, B1); BAR;
;       LDA(At, 1, 1); BAR; WAIT_L(0); MMA(1, 0, At, B0); MMA(1, 1, At, B1); BAR;
;     }
;     if (wr == 0) BAR;
	ds_read_b128 v[66:69], v175 offset:32768
	ds_read_b128 v[194:197], v175 offset:33792
	ds_read_b128 v[198:201], v175 offset:34816
	ds_read_b128 v[202:205], v175 offset:35840
	s_nop 0
	ds_read_b128 v[58:61], v176 offset:32768
	ds_read_b128 v[62:65], v176 offset:33792
	ds_read_b128 v[70:73], v176 offset:34816
	ds_read_b128 v[74:77], v176 offset:35840
	ds_read_b128 v[78:81], v176 offset:36864
	ds_read_b128 v[82:85], v176 offset:37888
	ds_read_b128 v[206:209], v176 offset:38912
	ds_read_b128 v[210:213], v176 offset:39936
	s_waitcnt vmcnt(2)
	s_barrier
	s_waitcnt lgkmcnt(0)
	s_setprio 1
	s_waitcnt lgkmcnt(0)
	v_mfma_f32_16x16x32_bf16 v[86:89], v[58:61], v[66:69], v[126:129]
	v_mfma_f32_16x16x32_bf16 v[158:161], v[62:65], v[194:197], v[86:89]
	v_mfma_f32_16x16x32_bf16 v[86:89], v[58:61], v[198:201], v[122:125]
	v_mfma_f32_16x16x32_bf16 v[142:145], v[62:65], v[202:205], v[86:89]
	v_mfma_f32_16x16x32_bf16 v[86:89], v[70:73], v[66:69], v[118:121]
	v_mfma_f32_16x16x32_bf16 v[154:157], v[74:77], v[194:197], v[86:89]
	v_mfma_f32_16x16x32_bf16 v[86:89], v[70:73], v[198:201], v[114:117]
	v_mfma_f32_16x16x32_bf16 v[138:141], v[74:77], v[202:205], v[86:89]
	v_mfma_f32_16x16x32_bf16 v[86:89], v[78:81], v[66:69], v[110:113]
	v_mfma_f32_16x16x32_bf16 v[150:153], v[82:85], v[194:197], v[86:89]
	v_mfma_f32_16x16x32_bf16 v[86:89], v[78:81], v[198:201], v[106:109]
	v_mfma_f32_16x16x32_bf16 v[134:137], v[82:85], v[202:205], v[86:89]
	v_mfma_f32_16x16x32_bf16 v[86:89], v[206:209], v[66:69], v[102:105]
	v_mfma_f32_16x16x32_bf16 v[146:149], v[210:213], v[194:197], v[86:89]
	v_mfma_f32_16x16x32_bf16 v[86:89], v[206:209], v[198:201], v[94:97]
	v_mfma_f32_16x16x32_bf16 v[130:133], v[210:213], v[202:205], v[86:89]
	s_setprio 0
	s_barrier
	ds_read_b128 v[94:97], v175 offset:49152
	ds_read_b128 v[102:105], v175 offset:50176
	ds_read_b128 v[106:109], v175 offset:51200
	ds_read_b128 v[118:121], v175 offset:52224
	s_waitcnt vmcnt(0)
	s_barrier
	s_waitcnt lgkmcnt(0)
	s_setprio 1
	s_waitcnt lgkmcnt(0)
	v_mfma_f32_16x16x32_bf16 v[50:53], v[58:61], v[94:97], v[50:53]
	v_mfma_f32_16x16x32_bf16 v[42:45], v[58:61], v[106:109], v[42:45]
	v_mfma_f32_16x16x32_bf16 v[38:41], v[70:73], v[94:97], v[38:41]
	v_mfma_f32_16x16x32_bf16 v[34:37], v[70:73], v[106:109], v[34:37]
	v_mfma_f32_16x16x32_bf16 v[30:33], v[78:81], v[94:97], v[30:33]
	v_mfma_f32_16x16x32_bf16 v[26:29], v[78:81], v[106:109], v[26:29]
	v_mfma_f32_16x16x32_bf16 v[22:25], v[206:209], v[94:97], v[22:25]
	v_mfma_f32_16x16x32_bf16 v[18:21], v[206:209], v[106:109], v[18:21]
	v_mfma_f32_16x16x32_bf16 v[126:129], v[62:65], v[102:105], v[50:53]
	v_mfma_f32_16x16x32_bf16 v[98:101], v[62:65], v[118:121], v[42:45]
	v_mfma_f32_16x16x32_bf16 v[122:125], v[74:77], v[102:105], v[38:41]
	v_mfma_f32_16x16x32_bf16 v[90:93], v[74:77], v[118:121], v[34:37]
	v_mfma_f32_16x16x32_bf16 v[114:117], v[82:85], v[102:105], v[30:33]
	v_mfma_f32_16x16x32_bf16 v[86:89], v[82:85], v[118:121], v[26:29]
	v_mfma_f32_16x16x32_bf16 v[110:113], v[210:213], v[102:105], v[22:25]
	v_mfma_f32_16x16x32_bf16 v[82:85], v[210:213], v[118:121], v[18:21]
	s_setprio 0
	s_barrier
	s_nop 0
	ds_read_b128 v[18:21], v176 offset:49152
	ds_read_b128 v[22:25], v176 offset:50176
	ds_read_b128 v[26:29], v176 offset:51200
	ds_read_b128 v[30:33], v176 offset:52224
	ds_read_b128 v[34:37], v176 offset:53248
	ds_read_b128 v[206:209], v176 offset:54272
	ds_read_b128 v[210:213], v176 offset:55296
	ds_read_b128 v[242:245], v176 offset:56320
	s_barrier
	s_waitcnt lgkmcnt(0)
	s_setprio 1
	s_waitcnt lgkmcnt(0)
	v_mfma_f32_16x16x32_bf16 v[2:5], v[26:29], v[198:201], v[2:5]
	v_mfma_f32_16x16x32_bf16 v[58:61], v[30:33], v[202:205], v[2:5]
	v_mfma_f32_16x16x32_bf16 v[2:5], v[34:37], v[66:69], v[46:49]
	v_mfma_f32_16x16x32_bf16 v[70:73], v[206:209], v[194:197], v[2:5]
	v_mfma_f32_16x16x32_bf16 v[2:5], v[34:37], v[198:201], v[54:57]
	v_mfma_f32_16x16x32_bf16 v[54:57], v[206:209], v[202:205], v[2:5]
	v_mfma_f32_16x16x32_bf16 v[2:5], v[210:213], v[66:69], v[214:217]
	v_mfma_f32_16x16x32_bf16 v[14:17], v[18:21], v[66:69], v[14:17]
	v_mfma_f32_16x16x32_bf16 v[10:13], v[18:21], v[198:201], v[10:13]
	v_mfma_f32_16x16x32_bf16 v[6:9], v[26:29], v[66:69], v[6:9]
	v_mfma_f32_16x16x32_bf16 v[66:69], v[242:245], v[194:197], v[2:5]
	v_mfma_f32_16x16x32_bf16 v[2:5], v[210:213], v[198:201], v[218:221]
	v_mfma_f32_16x16x32_bf16 v[78:81], v[22:25], v[194:197], v[14:17]
	v_mfma_f32_16x16x32_bf16 v[62:65], v[22:25], v[202:205], v[10:13]
	v_mfma_f32_16x16x32_bf16 v[74:77], v[30:33], v[194:197], v[6:9]
	v_mfma_f32_16x16x32_bf16 v[50:53], v[242:245], v[202:205], v[2:5]
	s_setprio 0
	s_setprio 1
	v_mfma_f32_16x16x32_bf16 v[2:5], v[18:21], v[94:97], v[222:225]
	v_mfma_f32_16x16x32_bf16 v[46:49], v[22:25], v[102:105], v[2:5]
	v_mfma_f32_16x16x32_bf16 v[2:5], v[18:21], v[106:109], v[226:229]
	v_mfma_f32_16x16x32_bf16 v[22:25], v[22:25], v[118:121], v[2:5]
	v_mfma_f32_16x16x32_bf16 v[2:5], v[26:29], v[94:97], v[230:233]
	v_mfma_f32_16x16x32_bf16 v[42:45], v[30:33], v[102:105], v[2:5]
	v_mfma_f32_16x16x32_bf16 v[2:5], v[26:29], v[106:109], v[234:237]
	v_mfma_f32_16x16x32_bf16 v[14:17], v[30:33], v[118:121], v[2:5]
	v_mfma_f32_16x16x32_bf16 v[2:5], v[34:37], v[94:97], v[238:241]
	v_mfma_f32_16x16x32_bf16 v[38:41], v[206:209], v[102:105], v[2:5]
	v_mfma_f32_16x16x32_bf16 v[2:5], v[34:37], v[106:109], v[182:185]
	v_mfma_f32_16x16x32_bf16 v[6:9], v[206:209], v[118:121], v[2:5]
	v_mfma_f32_16x16x32_bf16 v[2:5], v[210:213], v[94:97], v[186:189]
	v_mfma_f32_16x16x32_bf16 v[30:33], v[242:245], v[102:105], v[2:5]
	v_mfma_f32_16x16x32_bf16 v[2:5], v[210:213], v[106:109], v[190:193]
	v_mfma_f32_16x16x32_bf16 v[2:5], v[242:245], v[118:121], v[2:5]
	s_setprio 0
	s_barrier
	s_and_saveexec_b64 s[8:9], s[6:7]
	s_cbranch_execz .LBB0_601
	s_barrier

; #define LDA(dst, b, h)                                                                                     \
;   _Pragma("unroll") for (int m = 0; m < 4; ++m) _Pragma("unroll") for (int k = 0; k < 2; ++k) dst[m][k] = \
;       *reinterpret_cast<const bf16x8*>(shmc + aL + (((b) * 2 + (h)) * 16384 + (m * 2 + k) * 1024))
; #define LDB(dst, b, h)                                                                                     \
;   _Pragma("unroll") for (int n = 0; n < 2; ++n) _Pragma("unroll") for (int k = 0; k < 2; ++k) dst[n][k] = \
;       *reinterpret_cast<const bf16x8*>(shmc + bL + (((b) * 2 + (h)) * 16384 + (n * 2 + k) * 1024))
; #define OPAQ asm volatile("" : "+v"(aL), "+v"(bL))
; #define WAIT_V(n) asm volatile("s_waitcnt vmcnt(" #n ")" ::: "memory")
; #define WAIT_L(n) asm volatile("s_waitcnt lgkmcnt(" #n ")" ::: "memory")
; #define BAR __builtin_amdgcn_s_barrier()
; #define SCHED __builtin_amdgcn_sched_barrier(0)
; template <int EPI>
; __device__ __forceinline__ void phase_gemm(const Params& p, const GemmDesc& d, char* shmc) {
;     ...
;     for (int t = 0; t < nt - 2; t += 2) {
;       OPAQ;
;       LDB(B0, 0, 0); SCHED; LDA(At, 0, 0); STAGE_A(SA(1, 1), 1, t + 1);
;       WAIT_L(8); BAR; WAIT_L(0); MMA(0, 0, At, B0); BAR; SCHED;
;       LDB(B1, 0, 1); STAGE_B(SB(0, 0), 0, t + 2);
;       BAR; WAIT_L(0); MMA(0, 1, At, B1); BAR;
;       LDA(At, 0, 1); STAGE_A(SA(0, 0), 0, t + 2);
;       BAR; WAIT_L(0); MMA(1, 0, At, B0); BAR; SCHED;
;       STAGE_B(SB(0, 1), 1, t + 2);
;       WAIT_V(6); BAR; MMA(1, 1, At, B1); BAR;
;       LDB(B0, 1, 0); SCHED; LDA(At, 1, 0); STAGE_A(SA(0, 1), 1, t + 2);
;       WAIT_L(8); BAR; WAIT_L(0); MMA(0, 0, At, B0); BAR; SCHED;
;       LDB(B1, 1, 1); STAGE_B(SB(1, 0), 0, t + 3);
;       BAR; WAIT_L(0); MMA(0, 1, At, B1); BAR;
;       LDA(At, 1, 1); STAGE_A(SA(1, 0), 0, t + 3);
;       BAR; WAIT_L(0); MMA(1, 0, At, B0); BAR; SCHED;
;       STAGE_B(SB(1, 1), 1, t + 3);
;       WAIT_V(6); BAR; MMA(1, 1, At, B1); BAR;
;     }
.LBB0_1010:
	s_nop 0
	s_setprio 0
	ds_read_b128 v[156:159], v153
	ds_read_b128 v[160:163], v153 offset:1024
	ds_read_b128 v[164:167], v153 offset:2048
	ds_read_b128 v[168:171], v153 offset:3072
	ds_read_b128 v[204:207], v153 offset:16384
	ds_read_b128 v[208:211], v153 offset:17408
	ds_read_b128 v[212:215], v153 offset:18432
	ds_read_b128 v[216:219], v153 offset:19456
	ds_read_b128 v[172:175], v152
	ds_read_b128 v[176:179], v152 offset:1024
	ds_read_b128 v[180:183], v152 offset:2048
	ds_read_b128 v[184:187], v152 offset:3072
	ds_read_b128 v[188:191], v152 offset:4096
	ds_read_b128 v[192:195], v152 offset:5120
	ds_read_b128 v[196:199], v152 offset:6144
	ds_read_b128 v[200:203], v152 offset:7168
	s_mov_b32 m0, s80
	s_nop 0
	global_load_lds_dwordx4 v220, s[98:99]
	s_mov_b32 m0, s81
	s_nop 0
	global_load_lds_dwordx4 v221, s[98:99]
	s_waitcnt vmcnt(8)
	s_waitcnt lgkmcnt(0)
	s_setprio 1
	s_barrier
	v_mfma_f32_16x16x32_bf16 v[126:129], v[156:159], v[172:175], v[126:129]
	v_mfma_f32_16x16x32_bf16 v[122:125], v[164:167], v[172:175], v[122:125]
	v_mfma_f32_16x16x32_bf16 v[118:121], v[156:159], v[180:183], v[118:121]
	v_mfma_f32_16x16x32_bf16 v[114:117], v[164:167], v[180:183], v[114:117]
	v_mfma_f32_16x16x32_bf16 v[110:113], v[156:159], v[188:191], v[110:113]
	v_mfma_f32_16x16x32_bf16 v[106:109], v[164:167], v[188:191], v[106:109]
	v_mfma_f32_16x16x32_bf16 v[102:105], v[156:159], v[196:199], v[102:105]
	v_mfma_f32_16x16x32_bf16 v[98:101], v[164:167], v[196:199], v[98:101]
	v_mfma_f32_16x16x32_bf16 v[126:129], v[160:163], v[176:179], v[126:129]
	v_mfma_f32_16x16x32_bf16 v[122:125], v[168:171], v[176:179], v[122:125]
	v_mfma_f32_16x16x32_bf16 v[118:121], v[160:163], v[184:187], v[118:121]
	v_mfma_f32_16x16x32_bf16 v[114:117], v[168:171], v[184:187], v[114:117]
	v_mfma_f32_16x16x32_bf16 v[110:113], v[160:163], v[192:195], v[110:113]
	v_mfma_f32_16x16x32_bf16 v[106:109], v[168:171], v[192:195], v[106:109]
	v_mfma_f32_16x16x32_bf16 v[102:105], v[160:163], v[200:203], v[102:105]
	v_mfma_f32_16x16x32_bf16 v[98:101], v[168:171], v[200:203], v[98:101]
	v_mfma_f32_16x16x32_bf16 v[86:89], v[204:207], v[172:175], v[86:89]
	v_mfma_f32_16x16x32_bf16 v[70:73], v[212:215], v[172:175], v[70:73]
	v_mfma_f32_16x16x32_bf16 v[54:57], v[204:207], v[180:183], v[54:57]
	v_mfma_f32_16x16x32_bf16 v[50:53], v[212:215], v[180:183], v[50:53]
	v_mfma_f32_16x16x32_bf16 v[46:49], v[204:207], v[188:191], v[46:49]
	v_mfma_f32_16x16x32_bf16 v[42:45], v[212:215], v[188:191], v[42:45]
	v_mfma_f32_16x16x32_bf16 v[38:41], v[204:207], v[196:199], v[38:41]
	v_mfma_f32_16x16x32_bf16 v[34:37], v[212:215], v[196:199], v[34:37]
	v_mfma_f32_16x16x32_bf16 v[86:89], v[208:211], v[176:179], v[86:89]
	v_mfma_f32_16x16x32_bf16 v[70:73], v[216:219], v[176:179], v[70:73]
	v_mfma_f32_16x16x32_bf16 v[54:57], v[208:211], v[184:187], v[54:57]
	v_mfma_f32_16x16x32_bf16 v[50:53], v[216:219], v[184:187], v[50:53]
	v_mfma_f32_16x16x32_bf16 v[46:49], v[208:211], v[192:195], v[46:49]
	v_mfma_f32_16x16x32_bf16 v[42:45], v[216:219], v[192:195], v[42:45]
	v_mfma_f32_16x16x32_bf16 v[38:41], v[208:211], v[200:203], v[38:41]
	v_mfma_f32_16x16x32_bf16 v[34:37], v[216:219], v[200:203], v[34:37]
	s_barrier
	s_setprio 0
	ds_read_b128 v[172:175], v152 offset:16384
	ds_read_b128 v[176:179], v152 offset:17408
	ds_read_b128 v[180:183], v152 offset:18432
	ds_read_b128 v[184:187], v152 offset:19456
	ds_read_b128 v[188:191], v152 offset:20480
	ds_read_b128 v[192:195], v152 offset:21504
	ds_read_b128 v[196:199], v152 offset:22528
	ds_read_b128 v[200:203], v152 offset:23552
	s_mov_b32 m0, s35
	s_nop 0
	global_load_lds_dwordx4 v222, s[100:101]
	s_mov_b32 m0, s64
	s_nop 0
	global_load_lds_dwordx4 v223, s[100:101]
	s_mov_b32 m0, s34
	s_nop 0
	global_load_lds_dwordx4 v224, s[98:99]
	s_mov_b32 m0, s65
	s_nop 0
	global_load_lds_dwordx4 v225, s[98:99]
	s_mov_b32 m0, s66
	s_nop 0
	global_load_lds_dwordx4 v226, s[100:101]
	s_mov_b32 m0, s67
	s_nop 0
	global_load_lds_dwordx4 v227, s[100:101]
	s_waitcnt vmcnt(8)
	s_waitcnt lgkmcnt(0)
	s_setprio 1
	s_barrier
	v_mfma_f32_16x16x32_bf16 v[30:33], v[156:159], v[172:175], v[30:33]
	v_mfma_f32_16x16x32_bf16 v[26:29], v[164:167], v[172:175], v[26:29]
	v_mfma_f32_16x16x32_bf16 v[22:25], v[156:159], v[180:183], v[22:25]
	v_mfma_f32_16x16x32_bf16 v[18:21], v[164:167], v[180:183], v[18:21]
	v_mfma_f32_16x16x32_bf16 v[14:17], v[156:159], v[188:191], v[14:17]
	v_mfma_f32_16x16x32_bf16 v[10:13], v[164:167], v[188:191], v[10:13]
	v_mfma_f32_16x16x32_bf16 v[6:9], v[156:159], v[196:199], v[6:9]
	v_mfma_f32_16x16x32_bf16 v[2:5], v[164:167], v[196:199], v[2:5]
	v_mfma_f32_16x16x32_bf16 v[30:33], v[160:163], v[176:179], v[30:33]
	v_mfma_f32_16x16x32_bf16 v[26:29], v[168:171], v[176:179], v[26:29]
	v_mfma_f32_16x16x32_bf16 v[22:25], v[160:163], v[184:187], v[22:25]
	v_mfma_f32_16x16x32_bf16 v[18:21], v[168:171], v[184:187], v[18:21]
	v_mfma_f32_16x16x32_bf16 v[14:17], v[160:163], v[192:195], v[14:17]
	v_mfma_f32_16x16x32_bf16 v[10:13], v[168:171], v[192:195], v[10:13]
	v_mfma_f32_16x16x32_bf16 v[6:9], v[160:163], v[200:203], v[6:9]
	v_mfma_f32_16x16x32_bf16 v[2:5], v[168:171], v[200:203], v[2:5]
	v_mfma_f32_16x16x32_bf16 v[58:61], v[204:207], v[172:175], v[58:61]
	v_mfma_f32_16x16x32_bf16 v[62:65], v[212:215], v[172:175], v[62:65]
	v_mfma_f32_16x16x32_bf16 v[66:69], v[204:207], v[180:183], v[66:69]
	v_mfma_f32_16x16x32_bf16 v[74:77], v[212:215], v[180:183], v[74:77]
	v_mfma_f32_16x16x32_bf16 v[78:81], v[204:207], v[188:191], v[78:81]
	v_mfma_f32_16x16x32_bf16 v[82:85], v[212:215], v[188:191], v[82:85]
	v_mfma_f32_16x16x32_bf16 v[90:93], v[204:207], v[196:199], v[90:93]
	v_mfma_f32_16x16x32_bf16 v[94:97], v[212:215], v[196:199], v[94:97]
	v_mfma_f32_16x16x32_bf16 v[58:61], v[208:211], v[176:179], v[58:61]
	v_mfma_f32_16x16x32_bf16 v[62:65], v[216:219], v[176:179], v[62:65]
	v_mfma_f32_16x16x32_bf16 v[66:69], v[208:211], v[184:187], v[66:69]
	v_mfma_f32_16x16x32_bf16 v[74:77], v[216:219], v[184:187], v[74:77]
	v_mfma_f32_16x16x32_bf16 v[78:81], v[208:211], v[192:195], v[78:81]
	v_mfma_f32_16x16x32_bf16 v[82:85], v[216:219], v[192:195], v[82:85]
	v_mfma_f32_16x16x32_bf16 v[90:93], v[208:211], v[200:203], v[90:93]
	v_mfma_f32_16x16x32_bf16 v[94:97], v[216:219], v[200:203], v[94:97]
	s_barrier
; #define LDA(dst, b, h)                                                                                     \
;   _Pragma("unroll") for (int m = 0; m < 4; ++m) _Pragma("unroll") for (int k = 0; k < 2; ++k) dst[m][k] = \
;       *reinterpret_cast<const bf16x8*>(shmc + aL + (((b) * 2 + (h)) * 16384 + (m * 2 + k) * 1024))
; #define LDB(dst, b, h)                                                                                     \
;   _Pragma("unroll") for (int n = 0; n < 2; ++n) _Pragma("unroll") for (int k = 0; k < 2; ++k) dst[n][k] = \
;       *reinterpret_cast<const bf16x8*>(shmc + bL + (((b) * 2 + (h)) * 16384 + (n * 2 + k) * 1024))
; #define OPAQ asm volatile("" : "+v"(aL), "+v"(bL))
; #define WAIT_V(n) asm volatile("s_waitcnt vmcnt(" #n ")" ::: "memory")
; #define WAIT_L(n) asm volatile("s_waitcnt lgkmcnt(" #n ")" ::: "memory")
; #define BAR __builtin_amdgcn_s_barrier()
; #define SCHED __builtin_amdgcn_sched_barrier(0)
; template <int EPI>
; __device__ __forceinline__ void phase_gemm(const Params& p, const GemmDesc& d, char* shmc) {
;     ...
;     for (int t = 0; t < nt - 2; t += 2) {
;       OPAQ;
;       LDB(B0, 0, 0); SCHED; LDA(At, 0, 0); STAGE_A(SA(1, 1), 1, t + 1);
;       WAIT_L(8); BAR; WAIT_L(0); MMA(0, 0, At, B0); BAR; SCHED;
;       LDB(B1, 0, 1); STAGE_B(SB(0, 0), 0, t + 2);
;       BAR; WAIT_L(0); MMA(0, 1, At, B1); BAR;
;       LDA(At, 0, 1); STAGE_A(SA(0, 0), 0, t + 2);
;       BAR; WAIT_L(0); MMA(1, 0, At, B0); BAR; SCHED;
;       STAGE_B(SB(0, 1), 1, t + 2);
;       WAIT_V(6); BAR; MMA(1, 1, At, B1); BAR;
;       LDB(B0, 1, 0); SCHED; LDA(At, 1, 0); STAGE_A(SA(0, 1), 1, t + 2);
;       WAIT_L(8); BAR; WAIT_L(0); MMA(0, 0, At, B0); BAR; SCHED;
;       LDB(B1, 1, 1); STAGE_B(SB(1, 0), 0, t + 3);
;       BAR; WAIT_L(0); MMA(0, 1, At, B1); BAR;
;       LDA(At, 1, 1); STAGE_A(SA(1, 0), 0, t + 3);
;       BAR; WAIT_L(0); MMA(1, 0, At, B0); BAR; SCHED;
;       STAGE_B(SB(1, 1), 1, t + 3);
;       WAIT_V(6); BAR; MMA(1, 1, At, B1); BAR;
;     }
	s_setprio 0
	ds_read_b128 v[156:159], v153 offset:32768
	ds_read_b128 v[160:163], v153 offset:33792
	ds_read_b128 v[164:167], v153 offset:34816
	ds_read_b128 v[168:171], v153 offset:35840
	ds_read_b128 v[204:207], v153 offset:49152
	ds_read_b128 v[208:211], v153 offset:50176
	ds_read_b128 v[212:215], v153 offset:51200
	ds_read_b128 v[216:219], v153 offset:52224
	ds_read_b128 v[172:175], v152 offset:32768
	ds_read_b128 v[176:179], v152 offset:33792
	ds_read_b128 v[180:183], v152 offset:34816
	ds_read_b128 v[184:187], v152 offset:35840
	ds_read_b128 v[188:191], v152 offset:36864
	ds_read_b128 v[192:195], v152 offset:37888
	ds_read_b128 v[196:199], v152 offset:38912
	ds_read_b128 v[200:203], v152 offset:39936
	s_mov_b32 m0, s68
	s_nop 0
	global_load_lds_dwordx4 v228, s[98:99]
	s_mov_b32 m0, s69
	s_nop 0
	global_load_lds_dwordx4 v229, s[98:99]
	s_waitcnt vmcnt(8)
	s_waitcnt lgkmcnt(0)
	s_setprio 1
	s_barrier
	v_mfma_f32_16x16x32_bf16 v[126:129], v[156:159], v[172:175], v[126:129]
	v_mfma_f32_16x16x32_bf16 v[122:125], v[164:167], v[172:175], v[122:125]
	v_mfma_f32_16x16x32_bf16 v[118:121], v[156:159], v[180:183], v[118:121]
	v_mfma_f32_16x16x32_bf16 v[114:117], v[164:167], v[180:183], v[114:117]
	v_mfma_f32_16x16x32_bf16 v[110:113], v[156:159], v[188:191], v[110:113]
	v_mfma_f32_16x16x32_bf16 v[106:109], v[164:167], v[188:191], v[106:109]
	v_mfma_f32_16x16x32_bf16 v[102:105], v[156:159], v[196:199], v[102:105]
	v_mfma_f32_16x16x32_bf16 v[98:101], v[164:167], v[196:199], v[98:101]
	v_mfma_f32_16x16x32_bf16 v[126:129], v[160:163], v[176:179], v[126:129]
	v_mfma_f32_16x16x32_bf16 v[122:125], v[168:171], v[176:179], v[122:125]
	v_mfma_f32_16x16x32_bf16 v[118:121], v[160:163], v[184:187], v[118:121]
	v_mfma_f32_16x16x32_bf16 v[114:117], v[168:171], v[184:187], v[114:117]
	v_mfma_f32_16x16x32_bf16 v[110:113], v[160:163], v[192:195], v[110:113]
	v_mfma_f32_16x16x32_bf16 v[106:109], v[168:171], v[192:195], v[106:109]
	v_mfma_f32_16x16x32_bf16 v[102:105], v[160:163], v[200:203], v[102:105]
	v_mfma_f32_16x16x32_bf16 v[98:101], v[168:171], v[200:203], v[98:101]
	v_mfma_f32_16x16x32_bf16 v[86:89], v[204:207], v[172:175], v[86:89]
	v_mfma_f32_16x16x32_bf16 v[70:73], v[212:215], v[172:175], v[70:73]
	v_mfma_f32_16x16x32_bf16 v[54:57], v[204:207], v[180:183], v[54:57]
	v_mfma_f32_16x16x32_bf16 v[50:53], v[212:215], v[180:183], v[50:53]
	v_mfma_f32_16x16x32_bf16 v[46:49], v[204:207], v[188:191], v[46:49]
	v_mfma_f32_16x16x32_bf16 v[42:45], v[212:215], v[188:191], v[42:45]
	v_mfma_f32_16x16x32_bf16 v[38:41], v[204:207], v[196:199], v[38:41]
	v_mfma_f32_16x16x32_bf16 v[34:37], v[212:215], v[196:199], v[34:37]
	v_mfma_f32_16x16x32_bf16 v[86:89], v[208:211], v[176:179], v[86:89]
	v_mfma_f32_16x16x32_bf16 v[70:73], v[216:219], v[176:179], v[70:73]
	v_mfma_f32_16x16x32_bf16 v[54:57], v[208:211], v[184:187], v[54:57]
	v_mfma_f32_16x16x32_bf16 v[50:53], v[216:219], v[184:187], v[50:53]
	v_mfma_f32_16x16x32_bf16 v[46:49], v[208:211], v[192:195], v[46:49]
	v_mfma_f32_16x16x32_bf16 v[42:45], v[216:219], v[192:195], v[42:45]
	v_mfma_f32_16x16x32_bf16 v[38:41], v[208:211], v[200:203], v[38:41]
	v_mfma_f32_16x16x32_bf16 v[34:37], v[216:219], v[200:203], v[34:37]
	s_barrier
	s_setprio 0
	ds_read_b128 v[172:175], v152 offset:49152
	ds_read_b128 v[176:179], v152 offset:50176
	ds_read_b128 v[180:183], v152 offset:51200
	ds_read_b128 v[184:187], v152 offset:52224
	ds_read_b128 v[188:191], v152 offset:53248
	ds_read_b128 v[192:195], v152 offset:54272
	ds_read_b128 v[196:199], v152 offset:55296
	ds_read_b128 v[200:203], v152 offset:56320
	s_mov_b32 m0, s70
	s_nop 0
	global_load_lds_dwordx4 v232, s[100:101]
	s_mov_b32 m0, s71
	s_nop 0
	global_load_lds_dwordx4 v233, s[100:101]
	s_mov_b32 m0, s76
	s_nop 0
	global_load_lds_dwordx4 v234, s[98:99]
	s_mov_b32 m0, s77
	s_nop 0
	global_load_lds_dwordx4 v235, s[98:99]
	s_mov_b32 m0, s78
	s_nop 0
	global_load_lds_dwordx4 v236, s[100:101]
	s_mov_b32 m0, s79
	s_nop 0
	global_load_lds_dwordx4 v237, s[100:101]
	s_add_i32 s53, s53, 2
	s_add_u32 s58, s58, 0x100
	s_addc_u32 s59, s59, 0
	s_add_u32 s98, s98, 0x100
	s_addc_u32 s99, s99, 0
	s_add_u32 s100, s100, 0x100
	s_addc_u32 s101, s101, 0
	s_cmp_gt_u32 s53, 27
	s_waitcnt vmcnt(8)
	s_waitcnt lgkmcnt(0)
	s_setprio 1
	s_barrier
	v_mfma_f32_16x16x32_bf16 v[30:33], v[156:159], v[172:175], v[30:33]
	v_mfma_f32_16x16x32_bf16 v[26:29], v[164:167], v[172:175], v[26:29]
	v_mfma_f32_16x16x32_bf16 v[22:25], v[156:159], v[180:183], v[22:25]
	v_mfma_f32_16x16x32_bf16 v[18:21], v[164:167], v[180:183], v[18:21]
	v_mfma_f32_16x16x32_bf16 v[14:17], v[156:159], v[188:191], v[14:17]
	v_mfma_f32_16x16x32_bf16 v[10:13], v[164:167], v[188:191], v[10:13]
	v_mfma_f32_16x16x32_bf16 v[6:9], v[156:159], v[196:199], v[6:9]
	v_mfma_f32_16x16x32_bf16 v[2:5], v[164:167], v[196:199], v[2:5]
	v_mfma_f32_16x16x32_bf16 v[30:33], v[160:163], v[176:179], v[30:33]
	v_mfma_f32_16x16x32_bf16 v[26:29], v[168:171], v[176:179], v[26:29]
	v_mfma_f32_16x16x32_bf16 v[22:25], v[160:163], v[184:187], v[22:25]
	v_mfma_f32_16x16x32_bf16 v[18:21], v[168:171], v[184:187], v[18:21]
	v_mfma_f32_16x16x32_bf16 v[14:17], v[160:163], v[192:195], v[14:17]
	v_mfma_f32_16x16x32_bf16 v[10:13], v[168:171], v[192:195], v[10:13]
	v_mfma_f32_16x16x32_bf16 v[6:9], v[160:163], v[200:203], v[6:9]
	v_mfma_f32_16x16x32_bf16 v[2:5], v[168:171], v[200:203], v[2:5]
	v_mfma_f32_16x16x32_bf16 v[58:61], v[204:207], v[172:175], v[58:61]
	v_mfma_f32_16x16x32_bf16 v[62:65], v[212:215], v[172:175], v[62:65]
	v_mfma_f32_16x16x32_bf16 v[66:69], v[204:207], v[180:183], v[66:69]
	v_mfma_f32_16x16x32_bf16 v[74:77], v[212:215], v[180:183], v[74:77]
	v_mfma_f32_16x16x32_bf16 v[78:81], v[204:207], v[188:191], v[78:81]
	v_mfma_f32_16x16x32_bf16 v[82:85], v[212:215], v[188:191], v[82:85]
	v_mfma_f32_16x16x32_bf16 v[90:93], v[204:207], v[196:199], v[90:93]
	v_mfma_f32_16x16x32_bf16 v[94:97], v[212:215], v[196:199], v[94:97]
	v_mfma_f32_16x16x32_bf16 v[58:61], v[208:211], v[176:179], v[58:61]
	v_mfma_f32_16x16x32_bf16 v[62:65], v[216:219], v[176:179], v[62:65]
	v_mfma_f32_16x16x32_bf16 v[66:69], v[208:211], v[184:187], v[66:69]
	v_mfma_f32_16x16x32_bf16 v[74:77], v[216:219], v[184:187], v[74:77]
	v_mfma_f32_16x16x32_bf16 v[78:81], v[208:211], v[192:195], v[78:81]
	v_mfma_f32_16x16x32_bf16 v[82:85], v[216:219], v[192:195], v[82:85]
	v_mfma_f32_16x16x32_bf16 v[90:93], v[208:211], v[200:203], v[90:93]
	v_mfma_f32_16x16x32_bf16 v[94:97], v[216:219], v[200:203], v[94:97]
	s_barrier
; #define LDA(dst, b, h)                                                                                     \
;   _Pragma("unroll") for (int m = 0; m < 4; ++m) _Pragma("unroll") for (int k = 0; k < 2; ++k) dst[m][k] = \
;       *reinterpret_cast<const bf16x8*>(shmc + aL + (((b) * 2 + (h)) * 16384 + (m * 2 + k) * 1024))
; #define LDB(dst, b, h)                                                                                     \
;   _Pragma("unroll") for (int n = 0; n < 2; ++n) _Pragma("unroll") for (int k = 0; k < 2; ++k) dst[n][k] = \
;       *reinterpret_cast<const bf16x8*>(shmc + bL + (((b) * 2 + (h)) * 16384 + (n * 2 + k) * 1024))
; #define OPAQ asm volatile("" : "+v"(aL), "+v"(bL))
; #define WAIT_V(n) asm volatile("s_waitcnt vmcnt(" #n ")" ::: "memory")
; #define WAIT_L(n) asm volatile("s_waitcnt lgkmcnt(" #n ")" ::: "memory")
; #define BAR __builtin_amdgcn_s_barrier()
; template <int EPI>
; __device__ __forceinline__ void phase_gemm(const Params& p, const GemmDesc& d, char* shmc) {
;     ...
;     }
;     {
;       OPAQ;
;       LDB(B0, 0, 0); LDA(At, 0, 0); STAGE_A(SA(1, 1), 1, nt - 1);
;       BAR; WAIT_L(0); MMA(0, 0, At, B0); BAR;
;       LDB(B1, 0, 1); BAR; WAIT_L(0); MMA(0, 1, At, B1); BAR;
;       LDA(At, 0, 1); WAIT_V(4); BAR; WAIT_L(0); MMA(1, 0, At, B0); MMA(1, 1, At, B1); BAR;
;     }
	s_cbranch_scc0 .LBB0_1010
	s_setprio 0
	s_add_u32 s56, s56, 0x80f80
	s_addc_u32 s57, s57, 0
	v_add_u32_e32 v130, 0, v153
	v_add_u32_e32 v141, 0, v152
	s_mov_b32 m0, s80
	ds_read_b128 v[144:147], v130
	ds_read_b128 v[148:151], v130 offset:1024
	ds_read_b128 v[156:159], v130 offset:2048
	ds_read_b128 v[160:163], v130 offset:3072
	ds_read_b128 v[164:167], v141
	ds_read_b128 v[168:171], v141 offset:1024
	ds_read_b128 v[172:175], v141 offset:2048
	ds_read_b128 v[176:179], v141 offset:3072
	ds_read_b128 v[180:183], v141 offset:4096
	ds_read_b128 v[184:187], v141 offset:5120
	ds_read_b128 v[188:191], v141 offset:6144
	ds_read_b128 v[192:195], v141 offset:7168
	global_load_lds_dwordx4 v140, s[56:57]
	s_mov_b32 m0, s81
	s_nop 0
	global_load_lds_dwordx4 v142, s[56:57]
	s_waitcnt vmcnt(8)
	s_barrier
	s_waitcnt lgkmcnt(0)
	s_setprio 1
	s_waitcnt lgkmcnt(0)
	v_mfma_f32_16x16x32_bf16 v[126:129], v[144:147], v[164:167], v[126:129]
	v_mfma_f32_16x16x32_bf16 v[122:125], v[156:159], v[164:167], v[122:125]
	v_mfma_f32_16x16x32_bf16 v[114:117], v[156:159], v[172:175], v[114:117]
	v_mfma_f32_16x16x32_bf16 v[110:113], v[144:147], v[180:183], v[110:113]
	v_mfma_f32_16x16x32_bf16 v[102:105], v[144:147], v[188:191], v[102:105]
	v_mfma_f32_16x16x32_bf16 v[126:129], v[148:151], v[168:171], v[126:129]
	v_mfma_f32_16x16x32_bf16 v[122:125], v[160:163], v[168:171], v[122:125]
	v_mfma_f32_16x16x32_bf16 v[118:121], v[144:147], v[172:175], v[118:121]
	v_mfma_f32_16x16x32_bf16 v[114:117], v[160:163], v[176:179], v[114:117]
	v_mfma_f32_16x16x32_bf16 v[110:113], v[148:151], v[184:187], v[110:113]
	v_mfma_f32_16x16x32_bf16 v[106:109], v[156:159], v[180:183], v[106:109]
	v_mfma_f32_16x16x32_bf16 v[102:105], v[148:151], v[192:195], v[102:105]
	v_mfma_f32_16x16x32_bf16 v[98:101], v[156:159], v[188:191], v[98:101]
	v_mfma_f32_16x16x32_bf16 v[196:199], v[148:151], v[176:179], v[118:121]
	v_mfma_f32_16x16x32_bf16 v[200:203], v[160:163], v[184:187], v[106:109]
	v_mfma_f32_16x16x32_bf16 v[204:207], v[160:163], v[192:195], v[98:101]
	s_setprio 0
	s_barrier
	s_nop 2
	ds_read_b128 v[98:101], v130 offset:16384
	ds_read_b128 v[106:109], v130 offset:17408
	ds_read_b128 v[118:121], v130 offset:18432
	ds_read_b128 v[208:211], v130 offset:19456
	s_barrier
	s_waitcnt lgkmcnt(0)
	s_setprio 1
	s_waitcnt lgkmcnt(0)
	v_mfma_f32_16x16x32_bf16 v[86:89], v[98:101], v[164:167], v[86:89]
	v_mfma_f32_16x16x32_bf16 v[70:73], v[118:121], v[164:167], v[70:73]
	v_mfma_f32_16x16x32_bf16 v[54:57], v[98:101], v[172:175], v[54:57]
	v_mfma_f32_16x16x32_bf16 v[50:53], v[118:121], v[172:175], v[50:53]
	v_mfma_f32_16x16x32_bf16 v[46:49], v[98:101], v[180:183], v[46:49]
	v_mfma_f32_16x16x32_bf16 v[42:45], v[118:121], v[180:183], v[42:45]
	v_mfma_f32_16x16x32_bf16 v[38:41], v[98:101], v[188:191], v[38:41]
	v_mfma_f32_16x16x32_bf16 v[34:37], v[118:121], v[188:191], v[34:37]
	v_mfma_f32_16x16x32_bf16 v[86:89], v[106:109], v[168:171], v[86:89]
	v_mfma_f32_16x16x32_bf16 v[70:73], v[208:211], v[168:171], v[70:73]
	v_mfma_f32_16x16x32_bf16 v[54:57], v[106:109], v[176:179], v[54:57]
	v_mfma_f32_16x16x32_bf16 v[50:53], v[208:211], v[176:179], v[50:53]
	v_mfma_f32_16x16x32_bf16 v[46:49], v[106:109], v[184:187], v[46:49]
	v_mfma_f32_16x16x32_bf16 v[42:45], v[208:211], v[184:187], v[42:45]
	v_mfma_f32_16x16x32_bf16 v[38:41], v[106:109], v[192:195], v[38:41]
	v_mfma_f32_16x16x32_bf16 v[34:37], v[208:211], v[192:195], v[34:37]
	s_setprio 0
	s_barrier
	ds_read_b128 v[164:167], v141 offset:16384
	ds_read_b128 v[168:171], v141 offset:17408
	ds_read_b128 v[172:175], v141 offset:18432
	ds_read_b128 v[176:179], v141 offset:19456
	ds_read_b128 v[180:183], v141 offset:20480
	ds_read_b128 v[184:187], v141 offset:21504
	ds_read_b128 v[188:191], v141 offset:22528
	ds_read_b128 v[192:195], v141 offset:23552
	s_waitcnt vmcnt(4)
	s_barrier
	s_waitcnt lgkmcnt(0)
	s_setprio 1
	s_waitcnt lgkmcnt(0)
	v_mfma_f32_16x16x32_bf16 v[30:33], v[144:147], v[164:167], v[30:33]
	v_mfma_f32_16x16x32_bf16 v[26:29], v[156:159], v[164:167], v[26:29]
	v_mfma_f32_16x16x32_bf16 v[22:25], v[144:147], v[172:175], v[22:25]
	v_mfma_f32_16x16x32_bf16 v[18:21], v[156:159], v[172:175], v[18:21]
	v_mfma_f32_16x16x32_bf16 v[14:17], v[144:147], v[180:183], v[14:17]
	v_mfma_f32_16x16x32_bf16 v[10:13], v[156:159], v[180:183], v[10:13]
	v_mfma_f32_16x16x32_bf16 v[6:9], v[144:147], v[188:191], v[6:9]
	v_mfma_f32_16x16x32_bf16 v[2:5], v[156:159], v[188:191], v[2:5]
	v_mfma_f32_16x16x32_bf16 v[30:33], v[148:151], v[168:171], v[30:33]
	v_mfma_f32_16x16x32_bf16 v[26:29], v[160:163], v[168:171], v[26:29]
	v_mfma_f32_16x16x32_bf16 v[22:25], v[148:151], v[176:179], v[22:25]
	v_mfma_f32_16x16x32_bf16 v[18:21], v[160:163], v[176:179], v[18:21]
	v_mfma_f32_16x16x32_bf16 v[14:17], v[148:151], v[184:187], v[14:17]
	v_mfma_f32_16x16x32_bf16 v[10:13], v[160:163], v[184:187], v[10:13]
	v_mfma_f32_16x16x32_bf16 v[6:9], v[148:151], v[192:195], v[6:9]
	v_mfma_f32_16x16x32_bf16 v[2:5], v[160:163], v[192:195], v[2:5]
	s_setprio 0
	s_setprio 1
	v_mfma_f32_16x16x32_bf16 v[62:65], v[118:121], v[164:167], v[62:65]
	v_mfma_f32_16x16x32_bf16 v[144:147], v[208:211], v[168:171], v[62:65]
	v_mfma_f32_16x16x32_bf16 v[62:65], v[98:101], v[172:175], v[66:69]
	v_mfma_f32_16x16x32_bf16 v[148:151], v[106:109], v[176:179], v[62:65]
	v_mfma_f32_16x16x32_bf16 v[62:65], v[118:121], v[172:175], v[74:77]
	v_mfma_f32_16x16x32_bf16 v[156:159], v[208:211], v[176:179], v[62:65]
	v_mfma_f32_16x16x32_bf16 v[62:65], v[98:101], v[180:183], v[78:81]
	v_mfma_f32_16x16x32_bf16 v[160:163], v[106:109], v[184:187], v[62:65]
	v_mfma_f32_16x16x32_bf16 v[62:65], v[118:121], v[180:183], v[82:85]
	v_mfma_f32_16x16x32_bf16 v[58:61], v[98:101], v[164:167], v[58:61]
	v_mfma_f32_16x16x32_bf16 v[164:167], v[208:211], v[184:187], v[62:65]
	v_mfma_f32_16x16x32_bf16 v[62:65], v[98:101], v[188:191], v[90:93]
	v_mfma_f32_16x16x32_bf16 v[58:61], v[106:109], v[168:171], v[58:61]
	v_mfma_f32_16x16x32_bf16 v[168:171], v[106:109], v[192:195], v[62:65]
	v_mfma_f32_16x16x32_bf16 v[62:65], v[118:121], v[188:191], v[94:97]
	v_mfma_f32_16x16x32_bf16 v[172:175], v[208:211], v[192:195], v[62:65]
	s_setprio 0
	s_barrier
; #define LDA(dst, b, h)                                                                                     \
;   _Pragma("unroll") for (int m = 0; m < 4; ++m) _Pragma("unroll") for (int k = 0; k < 2; ++k) dst[m][k] = \
;       *reinterpret_cast<const bf16x8*>(shmc + aL + (((b) * 2 + (h)) * 16384 + (m * 2 + k) * 1024))
; #define LDB(dst, b, h)                                                                                     \
;   _Pragma("unroll") for (int n = 0; n < 2; ++n) _Pragma("unroll") for (int k = 0; k < 2; ++k) dst[n][k] = \
;       *reinterpret_cast<const bf16x8*>(shmc + bL + (((b) * 2 + (h)) * 16384 + (n * 2 + k) * 1024))
; #define WAIT_V(n) asm volatile("s_waitcnt vmcnt(" #n ")" ::: "memory")
; #define WAIT_L(n) asm volatile("s_waitcnt lgkmcnt(" #n ")" ::: "memory")
; #define BAR __builtin_amdgcn_s_barrier()
; template <int EPI>
; __device__ __forceinline__ void phase_gemm(const Params& p, const GemmDesc& d, char* shmc) {
;     ...
;     {
;       LDB(B0, 1, 0); LDA(At, 1, 0); WAIT_V(2); BAR; WAIT_L(0); MMA(0, 0, At, B0); BAR;
;       LDB(B1, 1, 1); WAIT_V(0); BAR; WAIT_L(0); MMA(0, 1, At, B1); BAR;
;       LDA(At, 1, 1); BAR; WAIT_L(0); MMA(1, 0, At, B0); MMA(1, 1, At, B1); BAR;
;     }
;     if (wr == 0) BAR;
	ds_read_b128 v[176:179], v130 offset:32768
	ds_read_b128 v[180:183], v130 offset:33792
	ds_read_b128 v[184:187], v130 offset:34816
	ds_read_b128 v[188:191], v130 offset:35840
	s_nop 0
	ds_read_b128 v[62:65], v141 offset:32768
	ds_read_b128 v[78:81], v141 offset:33792
	ds_read_b128 v[94:97], v141 offset:34816
	ds_read_b128 v[192:195], v141 offset:35840
	ds_read_b128 v[208:211], v141 offset:36864
	ds_read_b128 v[212:215], v141 offset:37888
	ds_read_b128 v[216:219], v141 offset:38912
	ds_read_b128 v[220:223], v141 offset:39936
	s_waitcnt vmcnt(2)
	s_barrier
	s_waitcnt lgkmcnt(0)
	s_setprio 1
	s_waitcnt lgkmcnt(0)
	v_mfma_f32_16x16x32_bf16 v[66:69], v[176:179], v[62:65], v[126:129]
	v_mfma_f32_16x16x32_bf16 v[126:129], v[180:183], v[78:81], v[66:69]
	v_mfma_f32_16x16x32_bf16 v[66:69], v[184:187], v[62:65], v[122:125]
	v_mfma_f32_16x16x32_bf16 v[118:121], v[188:191], v[78:81], v[66:69]
	v_mfma_f32_16x16x32_bf16 v[66:69], v[176:179], v[94:97], v[196:199]
	v_mfma_f32_16x16x32_bf16 v[106:109], v[180:183], v[192:195], v[66:69]
	v_mfma_f32_16x16x32_bf16 v[66:69], v[184:187], v[94:97], v[114:117]
	v_mfma_f32_16x16x32_bf16 v[98:101], v[188:191], v[192:195], v[66:69]
	v_mfma_f32_16x16x32_bf16 v[66:69], v[176:179], v[208:211], v[110:113]
	v_mfma_f32_16x16x32_bf16 v[90:93], v[180:183], v[212:215], v[66:69]
	v_mfma_f32_16x16x32_bf16 v[66:69], v[184:187], v[208:211], v[200:203]
	v_mfma_f32_16x16x32_bf16 v[82:85], v[188:191], v[212:215], v[66:69]
	v_mfma_f32_16x16x32_bf16 v[66:69], v[176:179], v[216:219], v[102:105]
	v_mfma_f32_16x16x32_bf16 v[74:77], v[180:183], v[220:223], v[66:69]
	v_mfma_f32_16x16x32_bf16 v[66:69], v[184:187], v[216:219], v[204:207]
	v_mfma_f32_16x16x32_bf16 v[66:69], v[188:191], v[220:223], v[66:69]
	s_setprio 0
	s_barrier
	ds_read_b128 v[196:199], v130 offset:49152
	ds_read_b128 v[200:203], v130 offset:50176
	ds_read_b128 v[204:207], v130 offset:51200
	ds_read_b128 v[224:227], v130 offset:52224
	s_waitcnt vmcnt(0)
	s_barrier
	s_waitcnt lgkmcnt(0)
	s_setprio 1
	s_waitcnt lgkmcnt(0)
	v_mfma_f32_16x16x32_bf16 v[86:89], v[196:199], v[62:65], v[86:89]
	v_mfma_f32_16x16x32_bf16 v[62:65], v[204:207], v[62:65], v[70:73]
	v_mfma_f32_16x16x32_bf16 v[54:57], v[196:199], v[94:97], v[54:57]
	v_mfma_f32_16x16x32_bf16 v[50:53], v[204:207], v[94:97], v[50:53]
	v_mfma_f32_16x16x32_bf16 v[46:49], v[196:199], v[208:211], v[46:49]
	v_mfma_f32_16x16x32_bf16 v[42:45], v[204:207], v[208:211], v[42:45]
	v_mfma_f32_16x16x32_bf16 v[38:41], v[196:199], v[216:219], v[38:41]
	v_mfma_f32_16x16x32_bf16 v[34:37], v[204:207], v[216:219], v[34:37]
	v_mfma_f32_16x16x32_bf16 v[122:125], v[200:203], v[78:81], v[86:89]
	v_mfma_f32_16x16x32_bf16 v[114:117], v[224:227], v[78:81], v[62:65]
	v_mfma_f32_16x16x32_bf16 v[110:113], v[200:203], v[192:195], v[54:57]
	v_mfma_f32_16x16x32_bf16 v[102:105], v[224:227], v[192:195], v[50:53]
	v_mfma_f32_16x16x32_bf16 v[94:97], v[200:203], v[212:215], v[46:49]
	v_mfma_f32_16x16x32_bf16 v[86:89], v[224:227], v[212:215], v[42:45]
	v_mfma_f32_16x16x32_bf16 v[78:81], v[200:203], v[220:223], v[38:41]
	v_mfma_f32_16x16x32_bf16 v[70:73], v[224:227], v[220:223], v[34:37]
	s_setprio 0
	s_barrier
	s_nop 0
	ds_read_b128 v[34:37], v141 offset:49152
	ds_read_b128 v[42:45], v141 offset:50176
	ds_read_b128 v[192:195], v141 offset:51200
	ds_read_b128 v[208:211], v141 offset:52224
	ds_read_b128 v[212:215], v141 offset:53248
	ds_read_b128 v[216:219], v141 offset:54272
	ds_read_b128 v[220:223], v141 offset:55296
	ds_read_b128 v[228:231], v141 offset:56320
	s_barrier
	s_waitcnt lgkmcnt(0)
	s_setprio 1
	s_waitcnt lgkmcnt(0)
	v_mfma_f32_16x16x32_bf16 v[30:33], v[176:179], v[34:37], v[30:33]
	v_mfma_f32_16x16x32_bf16 v[26:29], v[184:187], v[34:37], v[26:29]
	v_mfma_f32_16x16x32_bf16 v[22:25], v[176:179], v[192:195], v[22:25]
	v_mfma_f32_16x16x32_bf16 v[18:21], v[184:187], v[192:195], v[18:21]
	v_mfma_f32_16x16x32_bf16 v[14:17], v[176:179], v[212:215], v[14:17]
	v_mfma_f32_16x16x32_bf16 v[10:13], v[184:187], v[212:215], v[10:13]
	v_mfma_f32_16x16x32_bf16 v[6:9], v[176:179], v[220:223], v[6:9]
	v_mfma_f32_16x16x32_bf16 v[2:5], v[184:187], v[220:223], v[2:5]
	v_mfma_f32_16x16x32_bf16 v[62:65], v[180:183], v[42:45], v[30:33]
	v_mfma_f32_16x16x32_bf16 v[54:57], v[188:191], v[42:45], v[26:29]
	v_mfma_f32_16x16x32_bf16 v[46:49], v[180:183], v[208:211], v[22:25]
	v_mfma_f32_16x16x32_bf16 v[38:41], v[188:191], v[208:211], v[18:21]
	v_mfma_f32_16x16x32_bf16 v[30:33], v[180:183], v[216:219], v[14:17]
	v_mfma_f32_16x16x32_bf16 v[22:25], v[188:191], v[216:219], v[10:13]
	v_mfma_f32_16x16x32_bf16 v[14:17], v[180:183], v[228:231], v[6:9]
	v_mfma_f32_16x16x32_bf16 v[6:9], v[188:191], v[228:231], v[2:5]
	s_setprio 0
	s_setprio 1
	v_mfma_f32_16x16x32_bf16 v[2:5], v[196:199], v[34:37], v[58:61]
	v_mfma_f32_16x16x32_bf16 v[58:61], v[200:203], v[42:45], v[2:5]
	v_mfma_f32_16x16x32_bf16 v[2:5], v[204:207], v[34:37], v[144:147]
	v_mfma_f32_16x16x32_bf16 v[50:53], v[224:227], v[42:45], v[2:5]
	v_mfma_f32_16x16x32_bf16 v[2:5], v[196:199], v[192:195], v[148:151]
	v_mfma_f32_16x16x32_bf16 v[42:45], v[200:203], v[208:211], v[2:5]
	v_mfma_f32_16x16x32_bf16 v[2:5], v[204:207], v[192:195], v[156:159]
	v_mfma_f32_16x16x32_bf16 v[34:37], v[224:227], v[208:211], v[2:5]
	v_mfma_f32_16x16x32_bf16 v[2:5], v[196:199], v[212:215], v[160:163]
	v_mfma_f32_16x16x32_bf16 v[26:29], v[200:203], v[216:219], v[2:5]
	v_mfma_f32_16x16x32_bf16 v[2:5], v[204:207], v[212:215], v[164:167]
	v_mfma_f32_16x16x32_bf16 v[18:21], v[224:227], v[216:219], v[2:5]
	v_mfma_f32_16x16x32_bf16 v[2:5], v[196:199], v[220:223], v[168:171]
	v_mfma_f32_16x16x32_bf16 v[10:13], v[200:203], v[228:231], v[2:5]
	v_mfma_f32_16x16x32_bf16 v[2:5], v[204:207], v[220:223], v[172:175]
	v_mfma_f32_16x16x32_bf16 v[2:5], v[224:227], v[228:231], v[2:5]
	s_setprio 0
	s_barrier
	s_and_saveexec_b64 s[56:57], s[4:5]
	s_cbranch_execz .LBB0_1013
	s_barrier

; #define LDA(dst, b, h)                                                                                     \
;   _Pragma("unroll") for (int m = 0; m < 4; ++m) _Pragma("unroll") for (int k = 0; k < 2; ++k) dst[m][k] = \
;       *reinterpret_cast<const bf16x8*>(shmc + aL + (((b) * 2 + (h)) * 16384 + (m * 2 + k) * 1024))
; #define LDB(dst, b, h)                                                                                     \
;   _Pragma("unroll") for (int n = 0; n < 2; ++n) _Pragma("unroll") for (int k = 0; k < 2; ++k) dst[n][k] = \
;       *reinterpret_cast<const bf16x8*>(shmc + bL + (((b) * 2 + (h)) * 16384 + (n * 2 + k) * 1024))
; #define OPAQ asm volatile("" : "+v"(aL), "+v"(bL))
; #define WAIT_V(n) asm volatile("s_waitcnt vmcnt(" #n ")" ::: "memory")
; #define WAIT_L(n) asm volatile("s_waitcnt lgkmcnt(" #n ")" ::: "memory")
; #define BAR __builtin_amdgcn_s_barrier()
; #define SCHED __builtin_amdgcn_sched_barrier(0)
; template <int EPI>
; __device__ __forceinline__ void phase_gemm(const Params& p, const GemmDesc& d, char* shmc) {
;     ...
;     for (int t = 0; t < nt - 2; t += 2) {
;       OPAQ;
;       LDB(B0, 0, 0); SCHED; LDA(At, 0, 0); STAGE_A(SA(1, 1), 1, t + 1);
;       WAIT_L(8); BAR; WAIT_L(0); MMA(0, 0, At, B0); BAR; SCHED;
;       LDB(B1, 0, 1); STAGE_B(SB(0, 0), 0, t + 2);
;       BAR; WAIT_L(0); MMA(0, 1, At, B1); BAR;
;       LDA(At, 0, 1); STAGE_A(SA(0, 0), 0, t + 2);
;       BAR; WAIT_L(0); MMA(1, 0, At, B0); BAR; SCHED;
;       STAGE_B(SB(0, 1), 1, t + 2);
;       WAIT_V(6); BAR; MMA(1, 1, At, B1); BAR;
;       LDB(B0, 1, 0); SCHED; LDA(At, 1, 0); STAGE_A(SA(0, 1), 1, t + 2);
;       WAIT_L(8); BAR; WAIT_L(0); MMA(0, 0, At, B0); BAR; SCHED;
;       LDB(B1, 1, 1); STAGE_B(SB(1, 0), 0, t + 3);
;       BAR; WAIT_L(0); MMA(0, 1, At, B1); BAR;
;       LDA(At, 1, 1); STAGE_A(SA(1, 0), 0, t + 3);
;       BAR; WAIT_L(0); MMA(1, 0, At, B0); BAR; SCHED;
;       STAGE_B(SB(1, 1), 1, t + 3);
;       WAIT_V(6); BAR; MMA(1, 1, At, B1); BAR;
;     }
.LBB0_1153:
	s_nop 0
	s_setprio 0
	ds_read_b128 v[138:141], v205
	ds_read_b128 v[142:145], v205 offset:1024
	ds_read_b128 v[146:149], v205 offset:2048
	ds_read_b128 v[150:153], v205 offset:3072
	ds_read_b128 v[208:211], v205 offset:16384
	ds_read_b128 v[212:215], v205 offset:17408
	ds_read_b128 v[216:219], v205 offset:18432
	ds_read_b128 v[220:223], v205 offset:19456
	ds_read_b128 v[154:157], v204
	ds_read_b128 v[158:161], v204 offset:1024
	ds_read_b128 v[178:181], v204 offset:2048
	ds_read_b128 v[182:185], v204 offset:3072
	ds_read_b128 v[186:189], v204 offset:4096
	ds_read_b128 v[190:193], v204 offset:5120
	ds_read_b128 v[194:197], v204 offset:6144
	ds_read_b128 v[198:201], v204 offset:7168
	s_add_i32 s59, s64, 0xc000
	s_mov_b32 m0, s59
	s_nop 0
	global_load_lds_dwordx4 v202, s[98:99]
	s_add_i32 s68, s64, 0xe000
	s_mov_b32 m0, s68
	s_nop 0
	global_load_lds_dwordx4 v203, s[98:99]
	s_waitcnt vmcnt(8)
	s_waitcnt lgkmcnt(0)
	s_setprio 1
	s_barrier
	v_mfma_f32_16x16x32_bf16 v[2:5], v[154:157], v[138:141], v[2:5]
	v_mfma_f32_16x16x32_bf16 v[6:9], v[154:157], v[146:149], v[6:9]
	v_mfma_f32_16x16x32_bf16 v[10:13], v[178:181], v[138:141], v[10:13]
	v_mfma_f32_16x16x32_bf16 v[18:21], v[178:181], v[146:149], v[18:21]
	v_mfma_f32_16x16x32_bf16 v[30:33], v[186:189], v[138:141], v[30:33]
	v_mfma_f32_16x16x32_bf16 v[42:45], v[186:189], v[146:149], v[42:45]
	v_mfma_f32_16x16x32_bf16 v[54:57], v[194:197], v[138:141], v[54:57]
	v_mfma_f32_16x16x32_bf16 v[66:69], v[194:197], v[146:149], v[66:69]
	v_mfma_f32_16x16x32_bf16 v[2:5], v[158:161], v[142:145], v[2:5]
	v_mfma_f32_16x16x32_bf16 v[6:9], v[158:161], v[150:153], v[6:9]
	v_mfma_f32_16x16x32_bf16 v[10:13], v[182:185], v[142:145], v[10:13]
	v_mfma_f32_16x16x32_bf16 v[18:21], v[182:185], v[150:153], v[18:21]
	v_mfma_f32_16x16x32_bf16 v[30:33], v[190:193], v[142:145], v[30:33]
	v_mfma_f32_16x16x32_bf16 v[42:45], v[190:193], v[150:153], v[42:45]
	v_mfma_f32_16x16x32_bf16 v[54:57], v[198:201], v[142:145], v[54:57]
	v_mfma_f32_16x16x32_bf16 v[66:69], v[198:201], v[150:153], v[66:69]
	v_mfma_f32_16x16x32_bf16 v[14:17], v[154:157], v[208:211], v[14:17]
	v_mfma_f32_16x16x32_bf16 v[22:25], v[154:157], v[216:219], v[22:25]
	v_mfma_f32_16x16x32_bf16 v[34:37], v[178:181], v[208:211], v[34:37]
	v_mfma_f32_16x16x32_bf16 v[46:49], v[178:181], v[216:219], v[46:49]
	v_mfma_f32_16x16x32_bf16 v[58:61], v[186:189], v[208:211], v[58:61]
	v_mfma_f32_16x16x32_bf16 v[70:73], v[186:189], v[216:219], v[70:73]
	v_mfma_f32_16x16x32_bf16 v[78:81], v[194:197], v[208:211], v[78:81]
	v_mfma_f32_16x16x32_bf16 v[86:89], v[194:197], v[216:219], v[86:89]
	v_mfma_f32_16x16x32_bf16 v[14:17], v[158:161], v[212:215], v[14:17]
	v_mfma_f32_16x16x32_bf16 v[22:25], v[158:161], v[220:223], v[22:25]
	v_mfma_f32_16x16x32_bf16 v[34:37], v[182:185], v[212:215], v[34:37]
	v_mfma_f32_16x16x32_bf16 v[46:49], v[182:185], v[220:223], v[46:49]
	v_mfma_f32_16x16x32_bf16 v[58:61], v[190:193], v[212:215], v[58:61]
	v_mfma_f32_16x16x32_bf16 v[70:73], v[190:193], v[220:223], v[70:73]
	v_mfma_f32_16x16x32_bf16 v[78:81], v[198:201], v[212:215], v[78:81]
	v_mfma_f32_16x16x32_bf16 v[86:89], v[198:201], v[220:223], v[86:89]
	s_barrier
	s_setprio 0
	ds_read_b128 v[154:157], v204 offset:16384
	ds_read_b128 v[158:161], v204 offset:17408
	ds_read_b128 v[178:181], v204 offset:18432
	ds_read_b128 v[182:185], v204 offset:19456
	ds_read_b128 v[186:189], v204 offset:20480
	ds_read_b128 v[190:193], v204 offset:21504
	ds_read_b128 v[194:197], v204 offset:22528
	ds_read_b128 v[198:201], v204 offset:23552
	s_mov_b32 m0, s65
	s_nop 0
	global_load_lds_dwordx4 v224, s[100:101]
	s_mov_b32 m0, s66
	s_nop 0
	global_load_lds_dwordx4 v225, s[100:101]
	s_mov_b32 m0, s64
	s_nop 0
	global_load_lds_dwordx4 v226, s[98:99]
	s_mov_b32 m0, s67
	s_nop 0
	global_load_lds_dwordx4 v227, s[98:99]
	s_mov_b32 m0, s71
	s_nop 0
	global_load_lds_dwordx4 v228, s[100:101]
	s_mov_b32 m0, s76
	s_nop 0
	global_load_lds_dwordx4 v229, s[100:101]
	s_waitcnt vmcnt(8)
	s_waitcnt lgkmcnt(0)
	s_setprio 1
	s_barrier
	v_mfma_f32_16x16x32_bf16 v[26:29], v[154:157], v[138:141], v[26:29]
	v_mfma_f32_16x16x32_bf16 v[38:41], v[154:157], v[146:149], v[38:41]
	v_mfma_f32_16x16x32_bf16 v[50:53], v[178:181], v[138:141], v[50:53]
	v_mfma_f32_16x16x32_bf16 v[62:65], v[178:181], v[146:149], v[62:65]
	v_mfma_f32_16x16x32_bf16 v[74:77], v[186:189], v[138:141], v[74:77]
	v_mfma_f32_16x16x32_bf16 v[82:85], v[186:189], v[146:149], v[82:85]
	v_mfma_f32_16x16x32_bf16 v[90:93], v[194:197], v[138:141], v[90:93]
	v_mfma_f32_16x16x32_bf16 v[94:97], v[194:197], v[146:149], v[94:97]
	v_mfma_f32_16x16x32_bf16 v[26:29], v[158:161], v[142:145], v[26:29]
	v_mfma_f32_16x16x32_bf16 v[38:41], v[158:161], v[150:153], v[38:41]
	v_mfma_f32_16x16x32_bf16 v[50:53], v[182:185], v[142:145], v[50:53]
	v_mfma_f32_16x16x32_bf16 v[62:65], v[182:185], v[150:153], v[62:65]
	v_mfma_f32_16x16x32_bf16 v[74:77], v[190:193], v[142:145], v[74:77]
	v_mfma_f32_16x16x32_bf16 v[82:85], v[190:193], v[150:153], v[82:85]
	v_mfma_f32_16x16x32_bf16 v[90:93], v[198:201], v[142:145], v[90:93]
	v_mfma_f32_16x16x32_bf16 v[94:97], v[198:201], v[150:153], v[94:97]
	v_mfma_f32_16x16x32_bf16 v[98:101], v[154:157], v[208:211], v[98:101]
	v_mfma_f32_16x16x32_bf16 v[102:105], v[154:157], v[216:219], v[102:105]
	v_mfma_f32_16x16x32_bf16 v[106:109], v[178:181], v[208:211], v[106:109]
	v_mfma_f32_16x16x32_bf16 v[110:113], v[178:181], v[216:219], v[110:113]
	v_mfma_f32_16x16x32_bf16 v[114:117], v[186:189], v[208:211], v[114:117]
	v_mfma_f32_16x16x32_bf16 v[118:121], v[186:189], v[216:219], v[118:121]
	v_mfma_f32_16x16x32_bf16 v[122:125], v[194:197], v[208:211], v[122:125]
	v_mfma_f32_16x16x32_bf16 v[126:129], v[194:197], v[216:219], v[126:129]
	v_mfma_f32_16x16x32_bf16 v[98:101], v[158:161], v[212:215], v[98:101]
	v_mfma_f32_16x16x32_bf16 v[102:105], v[158:161], v[220:223], v[102:105]
	v_mfma_f32_16x16x32_bf16 v[106:109], v[182:185], v[212:215], v[106:109]
	v_mfma_f32_16x16x32_bf16 v[110:113], v[182:185], v[220:223], v[110:113]
	v_mfma_f32_16x16x32_bf16 v[114:117], v[190:193], v[212:215], v[114:117]
	v_mfma_f32_16x16x32_bf16 v[118:121], v[190:193], v[220:223], v[118:121]
	v_mfma_f32_16x16x32_bf16 v[122:125], v[198:201], v[212:215], v[122:125]
	v_mfma_f32_16x16x32_bf16 v[126:129], v[198:201], v[220:223], v[126:129]
	s_barrier
; #define LDA(dst, b, h)                                                                                     \
;   _Pragma("unroll") for (int m = 0; m < 4; ++m) _Pragma("unroll") for (int k = 0; k < 2; ++k) dst[m][k] = \
;       *reinterpret_cast<const bf16x8*>(shmc + aL + (((b) * 2 + (h)) * 16384 + (m * 2 + k) * 1024))
; #define LDB(dst, b, h)                                                                                     \
;   _Pragma("unroll") for (int n = 0; n < 2; ++n) _Pragma("unroll") for (int k = 0; k < 2; ++k) dst[n][k] = \
;       *reinterpret_cast<const bf16x8*>(shmc + bL + (((b) * 2 + (h)) * 16384 + (n * 2 + k) * 1024))
; #define OPAQ asm volatile("" : "+v"(aL), "+v"(bL))
; #define WAIT_V(n) asm volatile("s_waitcnt vmcnt(" #n ")" ::: "memory")
; #define WAIT_L(n) asm volatile("s_waitcnt lgkmcnt(" #n ")" ::: "memory")
; #define BAR __builtin_amdgcn_s_barrier()
; #define SCHED __builtin_amdgcn_sched_barrier(0)
; template <int EPI>
; __device__ __forceinline__ void phase_gemm(const Params& p, const GemmDesc& d, char* shmc) {
;     ...
;     for (int t = 0; t < nt - 2; t += 2) {
;       OPAQ;
;       LDB(B0, 0, 0); SCHED; LDA(At, 0, 0); STAGE_A(SA(1, 1), 1, t + 1);
;       WAIT_L(8); BAR; WAIT_L(0); MMA(0, 0, At, B0); BAR; SCHED;
;       LDB(B1, 0, 1); STAGE_B(SB(0, 0), 0, t + 2);
;       BAR; WAIT_L(0); MMA(0, 1, At, B1); BAR;
;       LDA(At, 0, 1); STAGE_A(SA(0, 0), 0, t + 2);
;       BAR; WAIT_L(0); MMA(1, 0, At, B0); BAR; SCHED;
;       STAGE_B(SB(0, 1), 1, t + 2);
;       WAIT_V(6); BAR; MMA(1, 1, At, B1); BAR;
;       LDB(B0, 1, 0); SCHED; LDA(At, 1, 0); STAGE_A(SA(0, 1), 1, t + 2);
;       WAIT_L(8); BAR; WAIT_L(0); MMA(0, 0, At, B0); BAR; SCHED;
;       LDB(B1, 1, 1); STAGE_B(SB(1, 0), 0, t + 3);
;       BAR; WAIT_L(0); MMA(0, 1, At, B1); BAR;
;       LDA(At, 1, 1); STAGE_A(SA(1, 0), 0, t + 3);
;       BAR; WAIT_L(0); MMA(1, 0, At, B0); BAR; SCHED;
;       STAGE_B(SB(1, 1), 1, t + 3);
;       WAIT_V(6); BAR; MMA(1, 1, At, B1); BAR;
;     }
	s_setprio 0
	ds_read_b128 v[138:141], v205 offset:32768
	ds_read_b128 v[142:145], v205 offset:33792
	ds_read_b128 v[146:149], v205 offset:34816
	ds_read_b128 v[150:153], v205 offset:35840
	ds_read_b128 v[208:211], v205 offset:49152
	ds_read_b128 v[212:215], v205 offset:50176
	ds_read_b128 v[216:219], v205 offset:51200
	ds_read_b128 v[220:223], v205 offset:52224
	ds_read_b128 v[154:157], v204 offset:32768
	ds_read_b128 v[158:161], v204 offset:33792
	ds_read_b128 v[178:181], v204 offset:34816
	ds_read_b128 v[182:185], v204 offset:35840
	ds_read_b128 v[186:189], v204 offset:36864
	ds_read_b128 v[190:193], v204 offset:37888
	ds_read_b128 v[194:197], v204 offset:38912
	ds_read_b128 v[198:201], v204 offset:39936
	s_mov_b32 m0, s77
	s_nop 0
	global_load_lds_dwordx4 v230, s[98:99]
	s_mov_b32 m0, s78
	s_nop 0
	global_load_lds_dwordx4 v231, s[98:99]
	s_waitcnt vmcnt(8)
	s_waitcnt lgkmcnt(0)
	s_setprio 1
	s_barrier
	v_mfma_f32_16x16x32_bf16 v[2:5], v[154:157], v[138:141], v[2:5]
	v_mfma_f32_16x16x32_bf16 v[6:9], v[154:157], v[146:149], v[6:9]
	v_mfma_f32_16x16x32_bf16 v[10:13], v[178:181], v[138:141], v[10:13]
	v_mfma_f32_16x16x32_bf16 v[18:21], v[178:181], v[146:149], v[18:21]
	v_mfma_f32_16x16x32_bf16 v[30:33], v[186:189], v[138:141], v[30:33]
	v_mfma_f32_16x16x32_bf16 v[42:45], v[186:189], v[146:149], v[42:45]
	v_mfma_f32_16x16x32_bf16 v[54:57], v[194:197], v[138:141], v[54:57]
	v_mfma_f32_16x16x32_bf16 v[66:69], v[194:197], v[146:149], v[66:69]
	v_mfma_f32_16x16x32_bf16 v[2:5], v[158:161], v[142:145], v[2:5]
	v_mfma_f32_16x16x32_bf16 v[6:9], v[158:161], v[150:153], v[6:9]
	v_mfma_f32_16x16x32_bf16 v[10:13], v[182:185], v[142:145], v[10:13]
	v_mfma_f32_16x16x32_bf16 v[18:21], v[182:185], v[150:153], v[18:21]
	v_mfma_f32_16x16x32_bf16 v[30:33], v[190:193], v[142:145], v[30:33]
	v_mfma_f32_16x16x32_bf16 v[42:45], v[190:193], v[150:153], v[42:45]
	v_mfma_f32_16x16x32_bf16 v[54:57], v[198:201], v[142:145], v[54:57]
	v_mfma_f32_16x16x32_bf16 v[66:69], v[198:201], v[150:153], v[66:69]
	v_mfma_f32_16x16x32_bf16 v[14:17], v[154:157], v[208:211], v[14:17]
	v_mfma_f32_16x16x32_bf16 v[22:25], v[154:157], v[216:219], v[22:25]
	v_mfma_f32_16x16x32_bf16 v[34:37], v[178:181], v[208:211], v[34:37]
	v_mfma_f32_16x16x32_bf16 v[46:49], v[178:181], v[216:219], v[46:49]
	v_mfma_f32_16x16x32_bf16 v[58:61], v[186:189], v[208:211], v[58:61]
	v_mfma_f32_16x16x32_bf16 v[70:73], v[186:189], v[216:219], v[70:73]
	v_mfma_f32_16x16x32_bf16 v[78:81], v[194:197], v[208:211], v[78:81]
	v_mfma_f32_16x16x32_bf16 v[86:89], v[194:197], v[216:219], v[86:89]
	v_mfma_f32_16x16x32_bf16 v[14:17], v[158:161], v[212:215], v[14:17]
	v_mfma_f32_16x16x32_bf16 v[22:25], v[158:161], v[220:223], v[22:25]
	v_mfma_f32_16x16x32_bf16 v[34:37], v[182:185], v[212:215], v[34:37]
	v_mfma_f32_16x16x32_bf16 v[46:49], v[182:185], v[220:223], v[46:49]
	v_mfma_f32_16x16x32_bf16 v[58:61], v[190:193], v[212:215], v[58:61]
	v_mfma_f32_16x16x32_bf16 v[70:73], v[190:193], v[220:223], v[70:73]
	v_mfma_f32_16x16x32_bf16 v[78:81], v[198:201], v[212:215], v[78:81]
	v_mfma_f32_16x16x32_bf16 v[86:89], v[198:201], v[220:223], v[86:89]
	s_barrier
	s_setprio 0
	ds_read_b128 v[154:157], v204 offset:49152
	ds_read_b128 v[158:161], v204 offset:50176
	ds_read_b128 v[178:181], v204 offset:51200
	ds_read_b128 v[182:185], v204 offset:52224
	ds_read_b128 v[186:189], v204 offset:53248
	ds_read_b128 v[190:193], v204 offset:54272
	ds_read_b128 v[194:197], v204 offset:55296
	ds_read_b128 v[198:201], v204 offset:56320
	s_mov_b32 m0, s35
	s_nop 0
	global_load_lds_dwordx4 v232, s[100:101]
	s_mov_b32 m0, s53
	s_nop 0
	global_load_lds_dwordx4 v233, s[100:101]
	s_mov_b32 m0, s56
	s_nop 0
	global_load_lds_dwordx4 v234, s[98:99]
	s_mov_b32 m0, s57
	s_nop 0
	global_load_lds_dwordx4 v235, s[98:99]
	s_mov_b32 m0, s54
	s_nop 0
	global_load_lds_dwordx4 v236, s[100:101]
	s_mov_b32 m0, s55
	s_nop 0
	global_load_lds_dwordx4 v237, s[100:101]
	s_add_i32 s58, s58, 2
	s_add_u32 s10, s10, 0x100
	s_addc_u32 s11, s11, 0
	s_add_u32 s98, s98, 0x100
	s_addc_u32 s99, s99, 0
	s_add_u32 s100, s100, 0x100
	s_addc_u32 s101, s101, 0
	s_cmp_gt_u32 s58, 27
	s_waitcnt vmcnt(8)
	s_waitcnt lgkmcnt(0)
	s_setprio 1
	s_barrier
	v_mfma_f32_16x16x32_bf16 v[26:29], v[154:157], v[138:141], v[26:29]
	v_mfma_f32_16x16x32_bf16 v[38:41], v[154:157], v[146:149], v[38:41]
	v_mfma_f32_16x16x32_bf16 v[50:53], v[178:181], v[138:141], v[50:53]
	v_mfma_f32_16x16x32_bf16 v[62:65], v[178:181], v[146:149], v[62:65]
	v_mfma_f32_16x16x32_bf16 v[74:77], v[186:189], v[138:141], v[74:77]
	v_mfma_f32_16x16x32_bf16 v[82:85], v[186:189], v[146:149], v[82:85]
	v_mfma_f32_16x16x32_bf16 v[90:93], v[194:197], v[138:141], v[90:93]
	v_mfma_f32_16x16x32_bf16 v[94:97], v[194:197], v[146:149], v[94:97]
	v_mfma_f32_16x16x32_bf16 v[26:29], v[158:161], v[142:145], v[26:29]
	v_mfma_f32_16x16x32_bf16 v[38:41], v[158:161], v[150:153], v[38:41]
	v_mfma_f32_16x16x32_bf16 v[50:53], v[182:185], v[142:145], v[50:53]
	v_mfma_f32_16x16x32_bf16 v[62:65], v[182:185], v[150:153], v[62:65]
	v_mfma_f32_16x16x32_bf16 v[74:77], v[190:193], v[142:145], v[74:77]
	v_mfma_f32_16x16x32_bf16 v[82:85], v[190:193], v[150:153], v[82:85]
	v_mfma_f32_16x16x32_bf16 v[90:93], v[198:201], v[142:145], v[90:93]
	v_mfma_f32_16x16x32_bf16 v[94:97], v[198:201], v[150:153], v[94:97]
	v_mfma_f32_16x16x32_bf16 v[98:101], v[154:157], v[208:211], v[98:101]
	v_mfma_f32_16x16x32_bf16 v[102:105], v[154:157], v[216:219], v[102:105]
	v_mfma_f32_16x16x32_bf16 v[106:109], v[178:181], v[208:211], v[106:109]
	v_mfma_f32_16x16x32_bf16 v[110:113], v[178:181], v[216:219], v[110:113]
	v_mfma_f32_16x16x32_bf16 v[114:117], v[186:189], v[208:211], v[114:117]
	v_mfma_f32_16x16x32_bf16 v[118:121], v[186:189], v[216:219], v[118:121]
	v_mfma_f32_16x16x32_bf16 v[122:125], v[194:197], v[208:211], v[122:125]
	v_mfma_f32_16x16x32_bf16 v[126:129], v[194:197], v[216:219], v[126:129]
	v_mfma_f32_16x16x32_bf16 v[98:101], v[158:161], v[212:215], v[98:101]
	v_mfma_f32_16x16x32_bf16 v[102:105], v[158:161], v[220:223], v[102:105]
	v_mfma_f32_16x16x32_bf16 v[106:109], v[182:185], v[212:215], v[106:109]
	v_mfma_f32_16x16x32_bf16 v[110:113], v[182:185], v[220:223], v[110:113]
	v_mfma_f32_16x16x32_bf16 v[114:117], v[190:193], v[212:215], v[114:117]
	v_mfma_f32_16x16x32_bf16 v[118:121], v[190:193], v[220:223], v[118:121]
	v_mfma_f32_16x16x32_bf16 v[122:125], v[198:201], v[212:215], v[122:125]
	v_mfma_f32_16x16x32_bf16 v[126:129], v[198:201], v[220:223], v[126:129]
	s_barrier
; #define LDA(dst, b, h)                                                                                     \
;   _Pragma("unroll") for (int m = 0; m < 4; ++m) _Pragma("unroll") for (int k = 0; k < 2; ++k) dst[m][k] = \
;       *reinterpret_cast<const bf16x8*>(shmc + aL + (((b) * 2 + (h)) * 16384 + (m * 2 + k) * 1024))
; #define LDB(dst, b, h)                                                                                     \
;   _Pragma("unroll") for (int n = 0; n < 2; ++n) _Pragma("unroll") for (int k = 0; k < 2; ++k) dst[n][k] = \
;       *reinterpret_cast<const bf16x8*>(shmc + bL + (((b) * 2 + (h)) * 16384 + (n * 2 + k) * 1024))
; #define OPAQ asm volatile("" : "+v"(aL), "+v"(bL))
; #define WAIT_V(n) asm volatile("s_waitcnt vmcnt(" #n ")" ::: "memory")
; #define WAIT_L(n) asm volatile("s_waitcnt lgkmcnt(" #n ")" ::: "memory")
; #define BAR __builtin_amdgcn_s_barrier()
; template <int EPI>
; __device__ __forceinline__ void phase_gemm(const Params& p, const GemmDesc& d, char* shmc) {
;     ...
;     }
;     {
;       OPAQ;
;       LDB(B0, 0, 0); LDA(At, 0, 0); STAGE_A(SA(1, 1), 1, nt - 1);
;       BAR; WAIT_L(0); MMA(0, 0, At, B0); BAR;
;       LDB(B1, 0, 1); BAR; WAIT_L(0); MMA(0, 1, At, B1); BAR;
;       LDA(At, 0, 1); WAIT_V(4); BAR; WAIT_L(0); MMA(1, 0, At, B0); MMA(1, 1, At, B1); BAR;
;     }
	s_cbranch_scc0 .LBB0_1153
	s_setprio 0
	s_add_u32 s8, s8, 0x80f80
	s_addc_u32 s9, s9, 0
	v_add_u32_e32 v162, 0, v205
	v_add_u32_e32 v175, 0, v204
	s_mov_b32 m0, s59
	ds_read_b128 v[130:133], v162
	ds_read_b128 v[134:137], v162 offset:1024
	ds_read_b128 v[138:141], v162 offset:2048
	ds_read_b128 v[142:145], v162 offset:3072
	ds_read_b128 v[146:149], v175
	ds_read_b128 v[150:153], v175 offset:1024
	ds_read_b128 v[154:157], v175 offset:2048
	ds_read_b128 v[158:161], v175 offset:3072
	ds_read_b128 v[178:181], v175 offset:4096
	ds_read_b128 v[182:185], v175 offset:5120
	ds_read_b128 v[186:189], v175 offset:6144
	ds_read_b128 v[190:193], v175 offset:7168
	global_load_lds_dwordx4 v174, s[8:9]
	s_mov_b32 m0, s68
	s_nop 0
	global_load_lds_dwordx4 v176, s[8:9]
	s_waitcnt vmcnt(8)
	s_barrier
	s_waitcnt lgkmcnt(0)
	s_setprio 1
	s_waitcnt lgkmcnt(0)
	v_mfma_f32_16x16x32_bf16 v[2:5], v[146:149], v[130:133], v[2:5]
	v_mfma_f32_16x16x32_bf16 v[6:9], v[146:149], v[138:141], v[6:9]
	v_mfma_f32_16x16x32_bf16 v[10:13], v[154:157], v[130:133], v[10:13]
	v_mfma_f32_16x16x32_bf16 v[18:21], v[154:157], v[138:141], v[18:21]
	v_mfma_f32_16x16x32_bf16 v[66:69], v[186:189], v[138:141], v[66:69]
	v_mfma_f32_16x16x32_bf16 v[2:5], v[150:153], v[134:137], v[2:5]
	v_mfma_f32_16x16x32_bf16 v[6:9], v[150:153], v[142:145], v[6:9]
	v_mfma_f32_16x16x32_bf16 v[10:13], v[158:161], v[134:137], v[10:13]
	v_mfma_f32_16x16x32_bf16 v[18:21], v[158:161], v[142:145], v[18:21]
	v_mfma_f32_16x16x32_bf16 v[30:33], v[178:181], v[130:133], v[30:33]
	v_mfma_f32_16x16x32_bf16 v[42:45], v[178:181], v[138:141], v[42:45]
	v_mfma_f32_16x16x32_bf16 v[54:57], v[186:189], v[130:133], v[54:57]
	v_mfma_f32_16x16x32_bf16 v[66:69], v[190:193], v[142:145], v[66:69]
	v_mfma_f32_16x16x32_bf16 v[30:33], v[182:185], v[134:137], v[30:33]
	v_mfma_f32_16x16x32_bf16 v[42:45], v[182:185], v[142:145], v[42:45]
	v_mfma_f32_16x16x32_bf16 v[54:57], v[190:193], v[134:137], v[54:57]
	s_setprio 0
	s_barrier
	ds_read_b128 v[194:197], v162 offset:16384
	ds_read_b128 v[198:201], v162 offset:17408
	ds_read_b128 v[208:211], v162 offset:18432
	ds_read_b128 v[212:215], v162 offset:19456
	s_barrier
	s_waitcnt lgkmcnt(0)
	s_setprio 1
	s_waitcnt lgkmcnt(0)
	v_mfma_f32_16x16x32_bf16 v[14:17], v[146:149], v[194:197], v[14:17]
	v_mfma_f32_16x16x32_bf16 v[22:25], v[146:149], v[208:211], v[22:25]
	v_mfma_f32_16x16x32_bf16 v[58:61], v[178:181], v[194:197], v[58:61]
	v_mfma_f32_16x16x32_bf16 v[14:17], v[150:153], v[198:201], v[14:17]
	v_mfma_f32_16x16x32_bf16 v[22:25], v[150:153], v[212:215], v[22:25]
	v_mfma_f32_16x16x32_bf16 v[150:153], v[182:185], v[198:201], v[58:61]
	v_mfma_f32_16x16x32_bf16 v[58:61], v[178:181], v[208:211], v[70:73]
	v_mfma_f32_16x16x32_bf16 v[34:37], v[154:157], v[194:197], v[34:37]
	v_mfma_f32_16x16x32_bf16 v[46:49], v[154:157], v[208:211], v[46:49]
	v_mfma_f32_16x16x32_bf16 v[154:157], v[182:185], v[212:215], v[58:61]
	v_mfma_f32_16x16x32_bf16 v[58:61], v[186:189], v[194:197], v[78:81]
	v_mfma_f32_16x16x32_bf16 v[78:81], v[190:193], v[198:201], v[58:61]
	v_mfma_f32_16x16x32_bf16 v[58:61], v[186:189], v[208:211], v[86:89]
	v_mfma_f32_16x16x32_bf16 v[86:89], v[190:193], v[212:215], v[58:61]
	v_mfma_f32_16x16x32_bf16 v[34:37], v[158:161], v[198:201], v[34:37]
	v_mfma_f32_16x16x32_bf16 v[46:49], v[158:161], v[212:215], v[46:49]
	s_setprio 0
	s_barrier
	s_nop 2
	ds_read_b128 v[58:61], v175 offset:16384
	ds_read_b128 v[70:73], v175 offset:17408
	ds_read_b128 v[146:149], v175 offset:18432
	ds_read_b128 v[158:161], v175 offset:19456
	ds_read_b128 v[178:181], v175 offset:20480
	ds_read_b128 v[182:185], v175 offset:21504
	ds_read_b128 v[186:189], v175 offset:22528
	ds_read_b128 v[190:193], v175 offset:23552
	s_waitcnt vmcnt(4)
	s_barrier
	s_waitcnt lgkmcnt(0)
	s_setprio 1
	s_waitcnt lgkmcnt(0)
	v_mfma_f32_16x16x32_bf16 v[74:77], v[178:181], v[130:133], v[74:77]
	v_mfma_f32_16x16x32_bf16 v[216:219], v[182:185], v[134:137], v[74:77]
	v_mfma_f32_16x16x32_bf16 v[74:77], v[178:181], v[138:141], v[82:85]
	v_mfma_f32_16x16x32_bf16 v[26:29], v[58:61], v[130:133], v[26:29]
	v_mfma_f32_16x16x32_bf16 v[82:85], v[182:185], v[142:145], v[74:77]
	v_mfma_f32_16x16x32_bf16 v[74:77], v[186:189], v[130:133], v[90:93]
	v_mfma_f32_16x16x32_bf16 v[26:29], v[70:73], v[134:137], v[26:29]
	v_mfma_f32_16x16x32_bf16 v[38:41], v[58:61], v[138:141], v[38:41]
	v_mfma_f32_16x16x32_bf16 v[50:53], v[146:149], v[130:133], v[50:53]
	v_mfma_f32_16x16x32_bf16 v[62:65], v[146:149], v[138:141], v[62:65]
	v_mfma_f32_16x16x32_bf16 v[90:93], v[190:193], v[134:137], v[74:77]
	v_mfma_f32_16x16x32_bf16 v[74:77], v[186:189], v[138:141], v[94:97]
	v_mfma_f32_16x16x32_bf16 v[38:41], v[70:73], v[142:145], v[38:41]
	v_mfma_f32_16x16x32_bf16 v[50:53], v[158:161], v[134:137], v[50:53]
	v_mfma_f32_16x16x32_bf16 v[62:65], v[158:161], v[142:145], v[62:65]
	v_mfma_f32_16x16x32_bf16 v[220:223], v[190:193], v[142:145], v[74:77]
	s_setprio 0
	s_setprio 1
	v_mfma_f32_16x16x32_bf16 v[74:77], v[58:61], v[194:197], v[98:101]
	v_mfma_f32_16x16x32_bf16 v[58:61], v[58:61], v[208:211], v[102:105]
	v_mfma_f32_16x16x32_bf16 v[228:231], v[70:73], v[212:215], v[58:61]
	v_mfma_f32_16x16x32_bf16 v[58:61], v[146:149], v[194:197], v[106:109]
	v_mfma_f32_16x16x32_bf16 v[232:235], v[158:161], v[198:201], v[58:61]
	v_mfma_f32_16x16x32_bf16 v[58:61], v[146:149], v[208:211], v[110:113]
	v_mfma_f32_16x16x32_bf16 v[236:239], v[158:161], v[212:215], v[58:61]
	v_mfma_f32_16x16x32_bf16 v[58:61], v[178:181], v[194:197], v[114:117]
	v_mfma_f32_16x16x32_bf16 v[240:243], v[182:185], v[198:201], v[58:61]
	v_mfma_f32_16x16x32_bf16 v[58:61], v[178:181], v[208:211], v[118:121]
	v_mfma_f32_16x16x32_bf16 v[178:181], v[182:185], v[212:215], v[58:61]
	v_mfma_f32_16x16x32_bf16 v[58:61], v[186:189], v[194:197], v[122:125]
	v_mfma_f32_16x16x32_bf16 v[182:185], v[190:193], v[198:201], v[58:61]
	v_mfma_f32_16x16x32_bf16 v[58:61], v[186:189], v[208:211], v[126:129]
	v_mfma_f32_16x16x32_bf16 v[224:227], v[70:73], v[198:201], v[74:77]
	v_mfma_f32_16x16x32_bf16 v[186:189], v[190:193], v[212:215], v[58:61]
	s_setprio 0
	s_barrier
; #define LDA(dst, b, h)                                                                                     \
;   _Pragma("unroll") for (int m = 0; m < 4; ++m) _Pragma("unroll") for (int k = 0; k < 2; ++k) dst[m][k] = \
;       *reinterpret_cast<const bf16x8*>(shmc + aL + (((b) * 2 + (h)) * 16384 + (m * 2 + k) * 1024))
; #define LDB(dst, b, h)                                                                                     \
;   _Pragma("unroll") for (int n = 0; n < 2; ++n) _Pragma("unroll") for (int k = 0; k < 2; ++k) dst[n][k] = \
;       *reinterpret_cast<const bf16x8*>(shmc + bL + (((b) * 2 + (h)) * 16384 + (n * 2 + k) * 1024))
; #define WAIT_V(n) asm volatile("s_waitcnt vmcnt(" #n ")" ::: "memory")
; #define WAIT_L(n) asm volatile("s_waitcnt lgkmcnt(" #n ")" ::: "memory")
; #define BAR __builtin_amdgcn_s_barrier()
; template <int EPI>
; __device__ __forceinline__ void phase_gemm(const Params& p, const GemmDesc& d, char* shmc) {
;     ...
;     {
;       LDB(B0, 1, 0); LDA(At, 1, 0); WAIT_V(2); BAR; WAIT_L(0); MMA(0, 0, At, B0); BAR;
;       LDB(B1, 1, 1); WAIT_V(0); BAR; WAIT_L(0); MMA(0, 1, At, B1); BAR;
;       LDA(At, 1, 1); BAR; WAIT_L(0); MMA(1, 0, At, B0); MMA(1, 1, At, B1); BAR;
;     }
;     if (wr == 0) BAR;
	ds_read_b128 v[98:101], v162 offset:32768
	ds_read_b128 v[106:109], v162 offset:33792
	ds_read_b128 v[190:193], v162 offset:34816
	ds_read_b128 v[194:197], v162 offset:35840
	ds_read_b128 v[58:61], v175 offset:32768
	ds_read_b128 v[70:73], v175 offset:33792
	ds_read_b128 v[114:117], v175 offset:34816
	ds_read_b128 v[122:125], v175 offset:35840
	ds_read_b128 v[130:133], v175 offset:36864
	ds_read_b128 v[138:141], v175 offset:37888
	ds_read_b128 v[198:201], v175 offset:38912
	ds_read_b128 v[208:211], v175 offset:39936
	s_waitcnt vmcnt(2)
	s_barrier
	s_waitcnt lgkmcnt(0)
	s_setprio 1
	s_waitcnt lgkmcnt(0)
	v_mfma_f32_16x16x32_bf16 v[2:5], v[58:61], v[98:101], v[2:5]
	v_mfma_f32_16x16x32_bf16 v[158:161], v[70:73], v[106:109], v[2:5]
	v_mfma_f32_16x16x32_bf16 v[2:5], v[58:61], v[190:193], v[6:9]
	v_mfma_f32_16x16x32_bf16 v[146:149], v[70:73], v[194:197], v[2:5]
	v_mfma_f32_16x16x32_bf16 v[2:5], v[114:117], v[98:101], v[10:13]
	v_mfma_f32_16x16x32_bf16 v[142:145], v[122:125], v[106:109], v[2:5]
	v_mfma_f32_16x16x32_bf16 v[2:5], v[114:117], v[190:193], v[18:21]
	v_mfma_f32_16x16x32_bf16 v[134:137], v[122:125], v[194:197], v[2:5]
	v_mfma_f32_16x16x32_bf16 v[2:5], v[130:133], v[98:101], v[30:33]
	v_mfma_f32_16x16x32_bf16 v[126:129], v[138:141], v[106:109], v[2:5]
	v_mfma_f32_16x16x32_bf16 v[2:5], v[130:133], v[190:193], v[42:45]
	v_mfma_f32_16x16x32_bf16 v[118:121], v[138:141], v[194:197], v[2:5]
	v_mfma_f32_16x16x32_bf16 v[2:5], v[198:201], v[98:101], v[54:57]
	v_mfma_f32_16x16x32_bf16 v[110:113], v[208:211], v[106:109], v[2:5]
	v_mfma_f32_16x16x32_bf16 v[2:5], v[198:201], v[190:193], v[66:69]
	v_mfma_f32_16x16x32_bf16 v[102:105], v[208:211], v[194:197], v[2:5]
	s_setprio 0
	s_barrier
	ds_read_b128 v[30:33], v162 offset:49152
	ds_read_b128 v[42:45], v162 offset:50176
	ds_read_b128 v[54:57], v162 offset:51200
	ds_read_b128 v[212:215], v162 offset:52224
	s_waitcnt vmcnt(0)
	s_barrier
	s_waitcnt lgkmcnt(0)
	s_setprio 1
	s_waitcnt lgkmcnt(0)
	v_mfma_f32_16x16x32_bf16 v[2:5], v[58:61], v[30:33], v[14:17]
	v_mfma_f32_16x16x32_bf16 v[94:97], v[70:73], v[42:45], v[2:5]
	v_mfma_f32_16x16x32_bf16 v[2:5], v[58:61], v[54:57], v[22:25]
	v_mfma_f32_16x16x32_bf16 v[58:61], v[70:73], v[212:215], v[2:5]
	v_mfma_f32_16x16x32_bf16 v[2:5], v[114:117], v[30:33], v[34:37]
	v_mfma_f32_16x16x32_bf16 v[74:77], v[122:125], v[42:45], v[2:5]
	v_mfma_f32_16x16x32_bf16 v[2:5], v[114:117], v[54:57], v[46:49]
	v_mfma_f32_16x16x32_bf16 v[10:13], v[122:125], v[212:215], v[2:5]
	v_mfma_f32_16x16x32_bf16 v[2:5], v[130:133], v[30:33], v[150:153]
	v_mfma_f32_16x16x32_bf16 v[70:73], v[138:141], v[42:45], v[2:5]
	v_mfma_f32_16x16x32_bf16 v[2:5], v[130:133], v[54:57], v[154:157]
	v_mfma_f32_16x16x32_bf16 v[6:9], v[138:141], v[212:215], v[2:5]
	v_mfma_f32_16x16x32_bf16 v[2:5], v[198:201], v[30:33], v[78:81]
	v_mfma_f32_16x16x32_bf16 v[66:69], v[208:211], v[42:45], v[2:5]
	v_mfma_f32_16x16x32_bf16 v[2:5], v[198:201], v[54:57], v[86:89]
	v_mfma_f32_16x16x32_bf16 v[2:5], v[208:211], v[212:215], v[2:5]
	s_setprio 0
	s_barrier
	ds_read_b128 v[14:17], v175 offset:49152
	ds_read_b128 v[18:21], v175 offset:50176
	ds_read_b128 v[22:25], v175 offset:51200
	ds_read_b128 v[34:37], v175 offset:52224
	ds_read_b128 v[46:49], v175 offset:53248
	ds_read_b128 v[78:81], v175 offset:54272
	ds_read_b128 v[198:201], v175 offset:55296
	ds_read_b128 v[208:211], v175 offset:56320
	s_barrier
	s_waitcnt lgkmcnt(0)
	s_setprio 1
	s_waitcnt lgkmcnt(0)
	v_mfma_f32_16x16x32_bf16 v[26:29], v[14:17], v[98:101], v[26:29]
	v_mfma_f32_16x16x32_bf16 v[154:157], v[18:21], v[106:109], v[26:29]
	v_mfma_f32_16x16x32_bf16 v[26:29], v[14:17], v[190:193], v[38:41]
	v_mfma_f32_16x16x32_bf16 v[150:153], v[18:21], v[194:197], v[26:29]
	v_mfma_f32_16x16x32_bf16 v[26:29], v[22:25], v[98:101], v[50:53]
	v_mfma_f32_16x16x32_bf16 v[138:141], v[34:37], v[106:109], v[26:29]
	v_mfma_f32_16x16x32_bf16 v[26:29], v[22:25], v[190:193], v[62:65]
	v_mfma_f32_16x16x32_bf16 v[130:133], v[34:37], v[194:197], v[26:29]
	v_mfma_f32_16x16x32_bf16 v[26:29], v[46:49], v[98:101], v[216:219]
	v_mfma_f32_16x16x32_bf16 v[122:125], v[78:81], v[106:109], v[26:29]
	v_mfma_f32_16x16x32_bf16 v[26:29], v[46:49], v[190:193], v[82:85]
	v_mfma_f32_16x16x32_bf16 v[114:117], v[78:81], v[194:197], v[26:29]
	v_mfma_f32_16x16x32_bf16 v[26:29], v[198:201], v[98:101], v[90:93]
	v_mfma_f32_16x16x32_bf16 v[106:109], v[208:211], v[106:109], v[26:29]
	v_mfma_f32_16x16x32_bf16 v[26:29], v[198:201], v[190:193], v[220:223]
	v_mfma_f32_16x16x32_bf16 v[98:101], v[208:211], v[194:197], v[26:29]
	s_setprio 0
	s_setprio 1
	v_mfma_f32_16x16x32_bf16 v[26:29], v[14:17], v[30:33], v[224:227]
	v_mfma_f32_16x16x32_bf16 v[14:17], v[14:17], v[54:57], v[228:231]
	v_mfma_f32_16x16x32_bf16 v[90:93], v[18:21], v[42:45], v[26:29]
	v_mfma_f32_16x16x32_bf16 v[26:29], v[18:21], v[212:215], v[14:17]
	v_mfma_f32_16x16x32_bf16 v[14:17], v[22:25], v[30:33], v[232:235]
	v_mfma_f32_16x16x32_bf16 v[86:89], v[34:37], v[42:45], v[14:17]
	v_mfma_f32_16x16x32_bf16 v[14:17], v[22:25], v[54:57], v[236:239]
	v_mfma_f32_16x16x32_bf16 v[22:25], v[34:37], v[212:215], v[14:17]
	v_mfma_f32_16x16x32_bf16 v[14:17], v[46:49], v[30:33], v[240:243]
	v_mfma_f32_16x16x32_bf16 v[82:85], v[78:81], v[42:45], v[14:17]
	v_mfma_f32_16x16x32_bf16 v[14:17], v[46:49], v[54:57], v[178:181]
	v_mfma_f32_16x16x32_bf16 v[18:21], v[78:81], v[212:215], v[14:17]
	v_mfma_f32_16x16x32_bf16 v[14:17], v[198:201], v[30:33], v[182:185]
	v_mfma_f32_16x16x32_bf16 v[78:81], v[208:211], v[42:45], v[14:17]
	v_mfma_f32_16x16x32_bf16 v[14:17], v[198:201], v[54:57], v[186:189]
	v_mfma_f32_16x16x32_bf16 v[14:17], v[208:211], v[212:215], v[14:17]
	s_setprio 0
	s_barrier
	s_and_saveexec_b64 s[8:9], s[6:7]
	s_cbranch_execz .LBB0_1156
	s_barrier

; #define LDA(dst, b, h)                                                                                     \
;   _Pragma("unroll") for (int m = 0; m < 4; ++m) _Pragma("unroll") for (int k = 0; k < 2; ++k) dst[m][k] = \
;       *reinterpret_cast<const bf16x8*>(shmc + aL + (((b) * 2 + (h)) * 16384 + (m * 2 + k) * 1024))
; #define LDB(dst, b, h)                                                                                     \
;   _Pragma("unroll") for (int n = 0; n < 2; ++n) _Pragma("unroll") for (int k = 0; k < 2; ++k) dst[n][k] = \
;       *reinterpret_cast<const bf16x8*>(shmc + bL + (((b) * 2 + (h)) * 16384 + (n * 2 + k) * 1024))
; #define OPAQ asm volatile("" : "+v"(aL), "+v"(bL))
; #define WAIT_V(n) asm volatile("s_waitcnt vmcnt(" #n ")" ::: "memory")
; #define WAIT_L(n) asm volatile("s_waitcnt lgkmcnt(" #n ")" ::: "memory")
; #define BAR __builtin_amdgcn_s_barrier()
; #define SCHED __builtin_amdgcn_sched_barrier(0)
; template <int EPI>
; __device__ __forceinline__ void phase_gemm(const Params& p, const GemmDesc& d, char* shmc) {
;     ...
;     for (int t = 0; t < nt - 2; t += 2) {
;       OPAQ;
;       LDB(B0, 0, 0); SCHED; LDA(At, 0, 0); STAGE_A(SA(1, 1), 1, t + 1);
;       WAIT_L(8); BAR; WAIT_L(0); MMA(0, 0, At, B0); BAR; SCHED;
;       LDB(B1, 0, 1); STAGE_B(SB(0, 0), 0, t + 2);
;       BAR; WAIT_L(0); MMA(0, 1, At, B1); BAR;
;       LDA(At, 0, 1); STAGE_A(SA(0, 0), 0, t + 2);
;       BAR; WAIT_L(0); MMA(1, 0, At, B0); BAR; SCHED;
;       STAGE_B(SB(0, 1), 1, t + 2);
;       WAIT_V(6); BAR; MMA(1, 1, At, B1); BAR;
;       LDB(B0, 1, 0); SCHED; LDA(At, 1, 0); STAGE_A(SA(0, 1), 1, t + 2);
;       WAIT_L(8); BAR; WAIT_L(0); MMA(0, 0, At, B0); BAR; SCHED;
;       LDB(B1, 1, 1); STAGE_B(SB(1, 0), 0, t + 3);
;       BAR; WAIT_L(0); MMA(0, 1, At, B1); BAR;
;       LDA(At, 1, 1); STAGE_A(SA(1, 0), 0, t + 3);
;       BAR; WAIT_L(0); MMA(1, 0, At, B0); BAR; SCHED;
;       STAGE_B(SB(1, 1), 1, t + 3);
;       WAIT_V(6); BAR; MMA(1, 1, At, B1); BAR;
;     }
.LBB0_1312:
	s_nop 0
	s_setprio 0
	ds_read_b128 v[156:159], v153
	ds_read_b128 v[160:163], v153 offset:1024
	ds_read_b128 v[164:167], v153 offset:2048
	ds_read_b128 v[168:171], v153 offset:3072
	ds_read_b128 v[204:207], v153 offset:16384
	ds_read_b128 v[208:211], v153 offset:17408
	ds_read_b128 v[212:215], v153 offset:18432
	ds_read_b128 v[216:219], v153 offset:19456
	ds_read_b128 v[172:175], v152
	ds_read_b128 v[176:179], v152 offset:1024
	ds_read_b128 v[180:183], v152 offset:2048
	ds_read_b128 v[184:187], v152 offset:3072
	ds_read_b128 v[188:191], v152 offset:4096
	ds_read_b128 v[192:195], v152 offset:5120
	ds_read_b128 v[196:199], v152 offset:6144
	ds_read_b128 v[200:203], v152 offset:7168
	s_mov_b32 m0, s59
	s_nop 0
	global_load_lds_dwordx4 v220, s[98:99]
	s_mov_b32 m0, s60
	s_nop 0
	global_load_lds_dwordx4 v221, s[98:99]
	s_waitcnt vmcnt(8)
	s_waitcnt lgkmcnt(0)
	s_setprio 1
	s_barrier
	v_mfma_f32_16x16x32_bf16 v[126:129], v[156:159], v[172:175], v[126:129]
	v_mfma_f32_16x16x32_bf16 v[122:125], v[164:167], v[172:175], v[122:125]
	v_mfma_f32_16x16x32_bf16 v[118:121], v[156:159], v[180:183], v[118:121]
	v_mfma_f32_16x16x32_bf16 v[114:117], v[164:167], v[180:183], v[114:117]
	v_mfma_f32_16x16x32_bf16 v[110:113], v[156:159], v[188:191], v[110:113]
	v_mfma_f32_16x16x32_bf16 v[106:109], v[164:167], v[188:191], v[106:109]
	v_mfma_f32_16x16x32_bf16 v[102:105], v[156:159], v[196:199], v[102:105]
	v_mfma_f32_16x16x32_bf16 v[98:101], v[164:167], v[196:199], v[98:101]
	v_mfma_f32_16x16x32_bf16 v[126:129], v[160:163], v[176:179], v[126:129]
	v_mfma_f32_16x16x32_bf16 v[122:125], v[168:171], v[176:179], v[122:125]
	v_mfma_f32_16x16x32_bf16 v[118:121], v[160:163], v[184:187], v[118:121]
	v_mfma_f32_16x16x32_bf16 v[114:117], v[168:171], v[184:187], v[114:117]
	v_mfma_f32_16x16x32_bf16 v[110:113], v[160:163], v[192:195], v[110:113]
	v_mfma_f32_16x16x32_bf16 v[106:109], v[168:171], v[192:195], v[106:109]
	v_mfma_f32_16x16x32_bf16 v[102:105], v[160:163], v[200:203], v[102:105]
	v_mfma_f32_16x16x32_bf16 v[98:101], v[168:171], v[200:203], v[98:101]
	v_mfma_f32_16x16x32_bf16 v[86:89], v[204:207], v[172:175], v[86:89]
	v_mfma_f32_16x16x32_bf16 v[70:73], v[212:215], v[172:175], v[70:73]
	v_mfma_f32_16x16x32_bf16 v[54:57], v[204:207], v[180:183], v[54:57]
	v_mfma_f32_16x16x32_bf16 v[50:53], v[212:215], v[180:183], v[50:53]
	v_mfma_f32_16x16x32_bf16 v[46:49], v[204:207], v[188:191], v[46:49]
	v_mfma_f32_16x16x32_bf16 v[42:45], v[212:215], v[188:191], v[42:45]
	v_mfma_f32_16x16x32_bf16 v[38:41], v[204:207], v[196:199], v[38:41]
	v_mfma_f32_16x16x32_bf16 v[34:37], v[212:215], v[196:199], v[34:37]
	v_mfma_f32_16x16x32_bf16 v[86:89], v[208:211], v[176:179], v[86:89]
	v_mfma_f32_16x16x32_bf16 v[70:73], v[216:219], v[176:179], v[70:73]
	v_mfma_f32_16x16x32_bf16 v[54:57], v[208:211], v[184:187], v[54:57]
	v_mfma_f32_16x16x32_bf16 v[50:53], v[216:219], v[184:187], v[50:53]
	v_mfma_f32_16x16x32_bf16 v[46:49], v[208:211], v[192:195], v[46:49]
	v_mfma_f32_16x16x32_bf16 v[42:45], v[216:219], v[192:195], v[42:45]
	v_mfma_f32_16x16x32_bf16 v[38:41], v[208:211], v[200:203], v[38:41]
	v_mfma_f32_16x16x32_bf16 v[34:37], v[216:219], v[200:203], v[34:37]
	s_barrier
	s_setprio 0
	ds_read_b128 v[172:175], v152 offset:16384
	ds_read_b128 v[176:179], v152 offset:17408
	ds_read_b128 v[180:183], v152 offset:18432
	ds_read_b128 v[184:187], v152 offset:19456
	ds_read_b128 v[188:191], v152 offset:20480
	ds_read_b128 v[192:195], v152 offset:21504
	ds_read_b128 v[196:199], v152 offset:22528
	ds_read_b128 v[200:203], v152 offset:23552
	s_mov_b32 m0, s34
	s_nop 0
	global_load_lds_dwordx4 v222, s[100:101]
	s_mov_b32 m0, s35
	s_nop 0
	global_load_lds_dwordx4 v223, s[100:101]
	s_mov_b32 m0, s33
	s_nop 0
	global_load_lds_dwordx4 v224, s[98:99]
	s_mov_b32 m0, s46
	s_nop 0
	global_load_lds_dwordx4 v225, s[98:99]
	s_mov_b32 m0, s47
	s_nop 0
	global_load_lds_dwordx4 v226, s[100:101]
	s_mov_b32 m0, s48
	s_nop 0
	global_load_lds_dwordx4 v227, s[100:101]
	s_waitcnt vmcnt(8)
	s_waitcnt lgkmcnt(0)
	s_setprio 1
	s_barrier
	v_mfma_f32_16x16x32_bf16 v[30:33], v[156:159], v[172:175], v[30:33]
	v_mfma_f32_16x16x32_bf16 v[26:29], v[164:167], v[172:175], v[26:29]
	v_mfma_f32_16x16x32_bf16 v[22:25], v[156:159], v[180:183], v[22:25]
	v_mfma_f32_16x16x32_bf16 v[18:21], v[164:167], v[180:183], v[18:21]
	v_mfma_f32_16x16x32_bf16 v[14:17], v[156:159], v[188:191], v[14:17]
	v_mfma_f32_16x16x32_bf16 v[10:13], v[164:167], v[188:191], v[10:13]
	v_mfma_f32_16x16x32_bf16 v[6:9], v[156:159], v[196:199], v[6:9]
	v_mfma_f32_16x16x32_bf16 v[2:5], v[164:167], v[196:199], v[2:5]
	v_mfma_f32_16x16x32_bf16 v[30:33], v[160:163], v[176:179], v[30:33]
	v_mfma_f32_16x16x32_bf16 v[26:29], v[168:171], v[176:179], v[26:29]
	v_mfma_f32_16x16x32_bf16 v[22:25], v[160:163], v[184:187], v[22:25]
	v_mfma_f32_16x16x32_bf16 v[18:21], v[168:171], v[184:187], v[18:21]
	v_mfma_f32_16x16x32_bf16 v[14:17], v[160:163], v[192:195], v[14:17]
	v_mfma_f32_16x16x32_bf16 v[10:13], v[168:171], v[192:195], v[10:13]
	v_mfma_f32_16x16x32_bf16 v[6:9], v[160:163], v[200:203], v[6:9]
	v_mfma_f32_16x16x32_bf16 v[2:5], v[168:171], v[200:203], v[2:5]
	v_mfma_f32_16x16x32_bf16 v[58:61], v[204:207], v[172:175], v[58:61]
	v_mfma_f32_16x16x32_bf16 v[62:65], v[212:215], v[172:175], v[62:65]
	v_mfma_f32_16x16x32_bf16 v[66:69], v[204:207], v[180:183], v[66:69]
	v_mfma_f32_16x16x32_bf16 v[74:77], v[212:215], v[180:183], v[74:77]
	v_mfma_f32_16x16x32_bf16 v[78:81], v[204:207], v[188:191], v[78:81]
	v_mfma_f32_16x16x32_bf16 v[82:85], v[212:215], v[188:191], v[82:85]
	v_mfma_f32_16x16x32_bf16 v[90:93], v[204:207], v[196:199], v[90:93]
	v_mfma_f32_16x16x32_bf16 v[94:97], v[212:215], v[196:199], v[94:97]
	v_mfma_f32_16x16x32_bf16 v[58:61], v[208:211], v[176:179], v[58:61]
	v_mfma_f32_16x16x32_bf16 v[62:65], v[216:219], v[176:179], v[62:65]
	v_mfma_f32_16x16x32_bf16 v[66:69], v[208:211], v[184:187], v[66:69]
	v_mfma_f32_16x16x32_bf16 v[74:77], v[216:219], v[184:187], v[74:77]
	v_mfma_f32_16x16x32_bf16 v[78:81], v[208:211], v[192:195], v[78:81]
	v_mfma_f32_16x16x32_bf16 v[82:85], v[216:219], v[192:195], v[82:85]
	v_mfma_f32_16x16x32_bf16 v[90:93], v[208:211], v[200:203], v[90:93]
	v_mfma_f32_16x16x32_bf16 v[94:97], v[216:219], v[200:203], v[94:97]
	s_barrier
; #define LDA(dst, b, h)                                                                                     \
;   _Pragma("unroll") for (int m = 0; m < 4; ++m) _Pragma("unroll") for (int k = 0; k < 2; ++k) dst[m][k] = \
;       *reinterpret_cast<const bf16x8*>(shmc + aL + (((b) * 2 + (h)) * 16384 + (m * 2 + k) * 1024))
; #define LDB(dst, b, h)                                                                                     \
;   _Pragma("unroll") for (int n = 0; n < 2; ++n) _Pragma("unroll") for (int k = 0; k < 2; ++k) dst[n][k] = \
;       *reinterpret_cast<const bf16x8*>(shmc + bL + (((b) * 2 + (h)) * 16384 + (n * 2 + k) * 1024))
; #define OPAQ asm volatile("" : "+v"(aL), "+v"(bL))
; #define WAIT_V(n) asm volatile("s_waitcnt vmcnt(" #n ")" ::: "memory")
; #define WAIT_L(n) asm volatile("s_waitcnt lgkmcnt(" #n ")" ::: "memory")
; #define BAR __builtin_amdgcn_s_barrier()
; #define SCHED __builtin_amdgcn_sched_barrier(0)
; template <int EPI>
; __device__ __forceinline__ void phase_gemm(const Params& p, const GemmDesc& d, char* shmc) {
;     ...
;     for (int t = 0; t < nt - 2; t += 2) {
;       OPAQ;
;       LDB(B0, 0, 0); SCHED; LDA(At, 0, 0); STAGE_A(SA(1, 1), 1, t + 1);
;       WAIT_L(8); BAR; WAIT_L(0); MMA(0, 0, At, B0); BAR; SCHED;
;       LDB(B1, 0, 1); STAGE_B(SB(0, 0), 0, t + 2);
;       BAR; WAIT_L(0); MMA(0, 1, At, B1); BAR;
;       LDA(At, 0, 1); STAGE_A(SA(0, 0), 0, t + 2);
;       BAR; WAIT_L(0); MMA(1, 0, At, B0); BAR; SCHED;
;       STAGE_B(SB(0, 1), 1, t + 2);
;       WAIT_V(6); BAR; MMA(1, 1, At, B1); BAR;
;       LDB(B0, 1, 0); SCHED; LDA(At, 1, 0); STAGE_A(SA(0, 1), 1, t + 2);
;       WAIT_L(8); BAR; WAIT_L(0); MMA(0, 0, At, B0); BAR; SCHED;
;       LDB(B1, 1, 1); STAGE_B(SB(1, 0), 0, t + 3);
;       BAR; WAIT_L(0); MMA(0, 1, At, B1); BAR;
;       LDA(At, 1, 1); STAGE_A(SA(1, 0), 0, t + 3);
;       BAR; WAIT_L(0); MMA(1, 0, At, B0); BAR; SCHED;
;       STAGE_B(SB(1, 1), 1, t + 3);
;       WAIT_V(6); BAR; MMA(1, 1, At, B1); BAR;
;     }
	s_setprio 0
	ds_read_b128 v[156:159], v153 offset:32768
	ds_read_b128 v[160:163], v153 offset:33792
	ds_read_b128 v[164:167], v153 offset:34816
	ds_read_b128 v[168:171], v153 offset:35840
	ds_read_b128 v[204:207], v153 offset:49152
	ds_read_b128 v[208:211], v153 offset:50176
	ds_read_b128 v[212:215], v153 offset:51200
	ds_read_b128 v[216:219], v153 offset:52224
	ds_read_b128 v[172:175], v152 offset:32768
	ds_read_b128 v[176:179], v152 offset:33792
	ds_read_b128 v[180:183], v152 offset:34816
	ds_read_b128 v[184:187], v152 offset:35840
	ds_read_b128 v[188:191], v152 offset:36864
	ds_read_b128 v[192:195], v152 offset:37888
	ds_read_b128 v[196:199], v152 offset:38912
	ds_read_b128 v[200:203], v152 offset:39936
	s_mov_b32 m0, s49
	s_nop 0
	global_load_lds_dwordx4 v228, s[98:99]
	s_mov_b32 m0, s52
	s_nop 0
	global_load_lds_dwordx4 v229, s[98:99]
	s_waitcnt vmcnt(8)
	s_waitcnt lgkmcnt(0)
	s_setprio 1
	s_barrier
	v_mfma_f32_16x16x32_bf16 v[126:129], v[156:159], v[172:175], v[126:129]
	v_mfma_f32_16x16x32_bf16 v[122:125], v[164:167], v[172:175], v[122:125]
	v_mfma_f32_16x16x32_bf16 v[118:121], v[156:159], v[180:183], v[118:121]
	v_mfma_f32_16x16x32_bf16 v[114:117], v[164:167], v[180:183], v[114:117]
	v_mfma_f32_16x16x32_bf16 v[110:113], v[156:159], v[188:191], v[110:113]
	v_mfma_f32_16x16x32_bf16 v[106:109], v[164:167], v[188:191], v[106:109]
	v_mfma_f32_16x16x32_bf16 v[102:105], v[156:159], v[196:199], v[102:105]
	v_mfma_f32_16x16x32_bf16 v[98:101], v[164:167], v[196:199], v[98:101]
	v_mfma_f32_16x16x32_bf16 v[126:129], v[160:163], v[176:179], v[126:129]
	v_mfma_f32_16x16x32_bf16 v[122:125], v[168:171], v[176:179], v[122:125]
	v_mfma_f32_16x16x32_bf16 v[118:121], v[160:163], v[184:187], v[118:121]
	v_mfma_f32_16x16x32_bf16 v[114:117], v[168:171], v[184:187], v[114:117]
	v_mfma_f32_16x16x32_bf16 v[110:113], v[160:163], v[192:195], v[110:113]
	v_mfma_f32_16x16x32_bf16 v[106:109], v[168:171], v[192:195], v[106:109]
	v_mfma_f32_16x16x32_bf16 v[102:105], v[160:163], v[200:203], v[102:105]
	v_mfma_f32_16x16x32_bf16 v[98:101], v[168:171], v[200:203], v[98:101]
	v_mfma_f32_16x16x32_bf16 v[86:89], v[204:207], v[172:175], v[86:89]
	v_mfma_f32_16x16x32_bf16 v[70:73], v[212:215], v[172:175], v[70:73]
	v_mfma_f32_16x16x32_bf16 v[54:57], v[204:207], v[180:183], v[54:57]
	v_mfma_f32_16x16x32_bf16 v[50:53], v[212:215], v[180:183], v[50:53]
	v_mfma_f32_16x16x32_bf16 v[46:49], v[204:207], v[188:191], v[46:49]
	v_mfma_f32_16x16x32_bf16 v[42:45], v[212:215], v[188:191], v[42:45]
	v_mfma_f32_16x16x32_bf16 v[38:41], v[204:207], v[196:199], v[38:41]
	v_mfma_f32_16x16x32_bf16 v[34:37], v[212:215], v[196:199], v[34:37]
	v_mfma_f32_16x16x32_bf16 v[86:89], v[208:211], v[176:179], v[86:89]
	v_mfma_f32_16x16x32_bf16 v[70:73], v[216:219], v[176:179], v[70:73]
	v_mfma_f32_16x16x32_bf16 v[54:57], v[208:211], v[184:187], v[54:57]
	v_mfma_f32_16x16x32_bf16 v[50:53], v[216:219], v[184:187], v[50:53]
	v_mfma_f32_16x16x32_bf16 v[46:49], v[208:211], v[192:195], v[46:49]
	v_mfma_f32_16x16x32_bf16 v[42:45], v[216:219], v[192:195], v[42:45]
	v_mfma_f32_16x16x32_bf16 v[38:41], v[208:211], v[200:203], v[38:41]
	v_mfma_f32_16x16x32_bf16 v[34:37], v[216:219], v[200:203], v[34:37]
	s_barrier
	s_setprio 0
	ds_read_b128 v[172:175], v152 offset:49152
	ds_read_b128 v[176:179], v152 offset:50176
	ds_read_b128 v[180:183], v152 offset:51200
	ds_read_b128 v[184:187], v152 offset:52224
	ds_read_b128 v[188:191], v152 offset:53248
	ds_read_b128 v[192:195], v152 offset:54272
	ds_read_b128 v[196:199], v152 offset:55296
	ds_read_b128 v[200:203], v152 offset:56320
	s_mov_b32 m0, s53
	s_nop 0
	global_load_lds_dwordx4 v232, s[100:101]
	s_mov_b32 m0, s54
	s_nop 0
	global_load_lds_dwordx4 v233, s[100:101]
	s_mov_b32 m0, s55
	s_nop 0
	global_load_lds_dwordx4 v234, s[98:99]
	s_mov_b32 m0, s56
	s_nop 0
	global_load_lds_dwordx4 v235, s[98:99]
	s_mov_b32 m0, s57
	s_nop 0
	global_load_lds_dwordx4 v236, s[100:101]
	s_mov_b32 m0, s58
	s_nop 0
	global_load_lds_dwordx4 v237, s[100:101]
	s_add_i32 s42, s42, 2
	s_add_u32 s40, s40, 0x100
	s_addc_u32 s41, s41, 0
	s_add_u32 s98, s98, 0x100
	s_addc_u32 s99, s99, 0
	s_add_u32 s100, s100, 0x100
	s_addc_u32 s101, s101, 0
	s_cmpk_gt_u32 s42, 0x53
	s_waitcnt vmcnt(8)
	s_waitcnt lgkmcnt(0)
	s_setprio 1
	s_barrier
	v_mfma_f32_16x16x32_bf16 v[30:33], v[156:159], v[172:175], v[30:33]
	v_mfma_f32_16x16x32_bf16 v[26:29], v[164:167], v[172:175], v[26:29]
	v_mfma_f32_16x16x32_bf16 v[22:25], v[156:159], v[180:183], v[22:25]
	v_mfma_f32_16x16x32_bf16 v[18:21], v[164:167], v[180:183], v[18:21]
	v_mfma_f32_16x16x32_bf16 v[14:17], v[156:159], v[188:191], v[14:17]
	v_mfma_f32_16x16x32_bf16 v[10:13], v[164:167], v[188:191], v[10:13]
	v_mfma_f32_16x16x32_bf16 v[6:9], v[156:159], v[196:199], v[6:9]
	v_mfma_f32_16x16x32_bf16 v[2:5], v[164:167], v[196:199], v[2:5]
	v_mfma_f32_16x16x32_bf16 v[30:33], v[160:163], v[176:179], v[30:33]
	v_mfma_f32_16x16x32_bf16 v[26:29], v[168:171], v[176:179], v[26:29]
	v_mfma_f32_16x16x32_bf16 v[22:25], v[160:163], v[184:187], v[22:25]
	v_mfma_f32_16x16x32_bf16 v[18:21], v[168:171], v[184:187], v[18:21]
	v_mfma_f32_16x16x32_bf16 v[14:17], v[160:163], v[192:195], v[14:17]
	v_mfma_f32_16x16x32_bf16 v[10:13], v[168:171], v[192:195], v[10:13]
	v_mfma_f32_16x16x32_bf16 v[6:9], v[160:163], v[200:203], v[6:9]
	v_mfma_f32_16x16x32_bf16 v[2:5], v[168:171], v[200:203], v[2:5]
	v_mfma_f32_16x16x32_bf16 v[58:61], v[204:207], v[172:175], v[58:61]
	v_mfma_f32_16x16x32_bf16 v[62:65], v[212:215], v[172:175], v[62:65]
	v_mfma_f32_16x16x32_bf16 v[66:69], v[204:207], v[180:183], v[66:69]
	v_mfma_f32_16x16x32_bf16 v[74:77], v[212:215], v[180:183], v[74:77]
	v_mfma_f32_16x16x32_bf16 v[78:81], v[204:207], v[188:191], v[78:81]
	v_mfma_f32_16x16x32_bf16 v[82:85], v[212:215], v[188:191], v[82:85]
	v_mfma_f32_16x16x32_bf16 v[90:93], v[204:207], v[196:199], v[90:93]
	v_mfma_f32_16x16x32_bf16 v[94:97], v[212:215], v[196:199], v[94:97]
	v_mfma_f32_16x16x32_bf16 v[58:61], v[208:211], v[176:179], v[58:61]
	v_mfma_f32_16x16x32_bf16 v[62:65], v[216:219], v[176:179], v[62:65]
	v_mfma_f32_16x16x32_bf16 v[66:69], v[208:211], v[184:187], v[66:69]
	v_mfma_f32_16x16x32_bf16 v[74:77], v[216:219], v[184:187], v[74:77]
	v_mfma_f32_16x16x32_bf16 v[78:81], v[208:211], v[192:195], v[78:81]
	v_mfma_f32_16x16x32_bf16 v[82:85], v[216:219], v[192:195], v[82:85]
	v_mfma_f32_16x16x32_bf16 v[90:93], v[208:211], v[200:203], v[90:93]
	v_mfma_f32_16x16x32_bf16 v[94:97], v[216:219], v[200:203], v[94:97]
	s_barrier
; #define LDA(dst, b, h)                                                                                     \
;   _Pragma("unroll") for (int m = 0; m < 4; ++m) _Pragma("unroll") for (int k = 0; k < 2; ++k) dst[m][k] = \
;       *reinterpret_cast<const bf16x8*>(shmc + aL + (((b) * 2 + (h)) * 16384 + (m * 2 + k) * 1024))
; #define LDB(dst, b, h)                                                                                     \
;   _Pragma("unroll") for (int n = 0; n < 2; ++n) _Pragma("unroll") for (int k = 0; k < 2; ++k) dst[n][k] = \
;       *reinterpret_cast<const bf16x8*>(shmc + bL + (((b) * 2 + (h)) * 16384 + (n * 2 + k) * 1024))
; #define OPAQ asm volatile("" : "+v"(aL), "+v"(bL))
; #define WAIT_V(n) asm volatile("s_waitcnt vmcnt(" #n ")" ::: "memory")
; #define WAIT_L(n) asm volatile("s_waitcnt lgkmcnt(" #n ")" ::: "memory")
; #define BAR __builtin_amdgcn_s_barrier()
; template <int EPI>
; __device__ __forceinline__ void phase_gemm(const Params& p, const GemmDesc& d, char* shmc) {
;     ...
;     }
;     {
;       OPAQ;
;       LDB(B0, 0, 0); LDA(At, 0, 0); STAGE_A(SA(1, 1), 1, nt - 1);
;       BAR; WAIT_L(0); MMA(0, 0, At, B0); BAR;
;       LDB(B1, 0, 1); BAR; WAIT_L(0); MMA(0, 1, At, B1); BAR;
;       LDA(At, 0, 1); WAIT_V(4); BAR; WAIT_L(0); MMA(1, 0, At, B0); MMA(1, 1, At, B1); BAR;
;     }
	s_cbranch_scc0 .LBB0_1312
	s_setprio 0
	s_add_u32 s38, s38, 0x162b80
	s_addc_u32 s39, s39, 0
	v_add_u32_e32 v130, 0, v153
	v_add_u32_e32 v141, 0, v152
	s_mov_b32 m0, s59
	ds_read_b128 v[144:147], v130
	ds_read_b128 v[148:151], v130 offset:1024
	ds_read_b128 v[156:159], v130 offset:2048
	ds_read_b128 v[160:163], v130 offset:3072
	ds_read_b128 v[164:167], v141
	ds_read_b128 v[168:171], v141 offset:1024
	ds_read_b128 v[172:175], v141 offset:2048
	ds_read_b128 v[176:179], v141 offset:3072
	ds_read_b128 v[180:183], v141 offset:4096
	ds_read_b128 v[184:187], v141 offset:5120
	ds_read_b128 v[188:191], v141 offset:6144
	ds_read_b128 v[192:195], v141 offset:7168
	global_load_lds_dwordx4 v140, s[38:39]
	s_mov_b32 m0, s60
	s_nop 0
	global_load_lds_dwordx4 v142, s[38:39]
	s_waitcnt vmcnt(8)
	s_barrier
	s_waitcnt lgkmcnt(0)
	s_setprio 1
	s_waitcnt lgkmcnt(0)
	v_mfma_f32_16x16x32_bf16 v[126:129], v[144:147], v[164:167], v[126:129]
	v_mfma_f32_16x16x32_bf16 v[122:125], v[156:159], v[164:167], v[122:125]
	v_mfma_f32_16x16x32_bf16 v[114:117], v[156:159], v[172:175], v[114:117]
	v_mfma_f32_16x16x32_bf16 v[110:113], v[144:147], v[180:183], v[110:113]
	v_mfma_f32_16x16x32_bf16 v[102:105], v[144:147], v[188:191], v[102:105]
	v_mfma_f32_16x16x32_bf16 v[126:129], v[148:151], v[168:171], v[126:129]
	v_mfma_f32_16x16x32_bf16 v[122:125], v[160:163], v[168:171], v[122:125]
	v_mfma_f32_16x16x32_bf16 v[118:121], v[144:147], v[172:175], v[118:121]
	v_mfma_f32_16x16x32_bf16 v[114:117], v[160:163], v[176:179], v[114:117]
	v_mfma_f32_16x16x32_bf16 v[110:113], v[148:151], v[184:187], v[110:113]
	v_mfma_f32_16x16x32_bf16 v[106:109], v[156:159], v[180:183], v[106:109]
	v_mfma_f32_16x16x32_bf16 v[102:105], v[148:151], v[192:195], v[102:105]
	v_mfma_f32_16x16x32_bf16 v[98:101], v[156:159], v[188:191], v[98:101]
	v_mfma_f32_16x16x32_bf16 v[196:199], v[148:151], v[176:179], v[118:121]
	v_mfma_f32_16x16x32_bf16 v[200:203], v[160:163], v[184:187], v[106:109]
	v_mfma_f32_16x16x32_bf16 v[204:207], v[160:163], v[192:195], v[98:101]
	s_setprio 0
	s_barrier
	s_nop 2
	ds_read_b128 v[98:101], v130 offset:16384
	ds_read_b128 v[106:109], v130 offset:17408
	ds_read_b128 v[118:121], v130 offset:18432
	ds_read_b128 v[208:211], v130 offset:19456
	s_barrier
	s_waitcnt lgkmcnt(0)
	s_setprio 1
	s_waitcnt lgkmcnt(0)
	v_mfma_f32_16x16x32_bf16 v[86:89], v[98:101], v[164:167], v[86:89]
	v_mfma_f32_16x16x32_bf16 v[70:73], v[118:121], v[164:167], v[70:73]
	v_mfma_f32_16x16x32_bf16 v[54:57], v[98:101], v[172:175], v[54:57]
	v_mfma_f32_16x16x32_bf16 v[50:53], v[118:121], v[172:175], v[50:53]
	v_mfma_f32_16x16x32_bf16 v[46:49], v[98:101], v[180:183], v[46:49]
	v_mfma_f32_16x16x32_bf16 v[42:45], v[118:121], v[180:183], v[42:45]
	v_mfma_f32_16x16x32_bf16 v[38:41], v[98:101], v[188:191], v[38:41]
	v_mfma_f32_16x16x32_bf16 v[34:37], v[118:121], v[188:191], v[34:37]
	v_mfma_f32_16x16x32_bf16 v[86:89], v[106:109], v[168:171], v[86:89]
	v_mfma_f32_16x16x32_bf16 v[70:73], v[208:211], v[168:171], v[70:73]
	v_mfma_f32_16x16x32_bf16 v[54:57], v[106:109], v[176:179], v[54:57]
	v_mfma_f32_16x16x32_bf16 v[50:53], v[208:211], v[176:179], v[50:53]
	v_mfma_f32_16x16x32_bf16 v[46:49], v[106:109], v[184:187], v[46:49]
	v_mfma_f32_16x16x32_bf16 v[42:45], v[208:211], v[184:187], v[42:45]
	v_mfma_f32_16x16x32_bf16 v[38:41], v[106:109], v[192:195], v[38:41]
	v_mfma_f32_16x16x32_bf16 v[34:37], v[208:211], v[192:195], v[34:37]
	s_setprio 0
	s_barrier
	ds_read_b128 v[164:167], v141 offset:16384
	ds_read_b128 v[168:171], v141 offset:17408
	ds_read_b128 v[172:175], v141 offset:18432
	ds_read_b128 v[176:179], v141 offset:19456
	ds_read_b128 v[180:183], v141 offset:20480
	ds_read_b128 v[184:187], v141 offset:21504
	ds_read_b128 v[188:191], v141 offset:22528
	ds_read_b128 v[192:195], v141 offset:23552
	s_waitcnt vmcnt(4)
	s_barrier
	s_waitcnt lgkmcnt(0)
	s_setprio 1
	s_waitcnt lgkmcnt(0)
	v_mfma_f32_16x16x32_bf16 v[30:33], v[144:147], v[164:167], v[30:33]
	v_mfma_f32_16x16x32_bf16 v[26:29], v[156:159], v[164:167], v[26:29]
	v_mfma_f32_16x16x32_bf16 v[22:25], v[144:147], v[172:175], v[22:25]
	v_mfma_f32_16x16x32_bf16 v[18:21], v[156:159], v[172:175], v[18:21]
	v_mfma_f32_16x16x32_bf16 v[14:17], v[144:147], v[180:183], v[14:17]
	v_mfma_f32_16x16x32_bf16 v[10:13], v[156:159], v[180:183], v[10:13]
	v_mfma_f32_16x16x32_bf16 v[6:9], v[144:147], v[188:191], v[6:9]
	v_mfma_f32_16x16x32_bf16 v[2:5], v[156:159], v[188:191], v[2:5]
	v_mfma_f32_16x16x32_bf16 v[30:33], v[148:151], v[168:171], v[30:33]
	v_mfma_f32_16x16x32_bf16 v[26:29], v[160:163], v[168:171], v[26:29]
	v_mfma_f32_16x16x32_bf16 v[22:25], v[148:151], v[176:179], v[22:25]
	v_mfma_f32_16x16x32_bf16 v[18:21], v[160:163], v[176:179], v[18:21]
	v_mfma_f32_16x16x32_bf16 v[14:17], v[148:151], v[184:187], v[14:17]
	v_mfma_f32_16x16x32_bf16 v[10:13], v[160:163], v[184:187], v[10:13]
	v_mfma_f32_16x16x32_bf16 v[6:9], v[148:151], v[192:195], v[6:9]
	v_mfma_f32_16x16x32_bf16 v[2:5], v[160:163], v[192:195], v[2:5]
	s_setprio 0
	s_setprio 1
	v_mfma_f32_16x16x32_bf16 v[62:65], v[118:121], v[164:167], v[62:65]
	v_mfma_f32_16x16x32_bf16 v[144:147], v[208:211], v[168:171], v[62:65]
	v_mfma_f32_16x16x32_bf16 v[62:65], v[98:101], v[172:175], v[66:69]
	v_mfma_f32_16x16x32_bf16 v[148:151], v[106:109], v[176:179], v[62:65]
	v_mfma_f32_16x16x32_bf16 v[62:65], v[118:121], v[172:175], v[74:77]
	v_mfma_f32_16x16x32_bf16 v[156:159], v[208:211], v[176:179], v[62:65]
	v_mfma_f32_16x16x32_bf16 v[62:65], v[98:101], v[180:183], v[78:81]
	v_mfma_f32_16x16x32_bf16 v[160:163], v[106:109], v[184:187], v[62:65]
	v_mfma_f32_16x16x32_bf16 v[62:65], v[118:121], v[180:183], v[82:85]
	v_mfma_f32_16x16x32_bf16 v[58:61], v[98:101], v[164:167], v[58:61]
	v_mfma_f32_16x16x32_bf16 v[164:167], v[208:211], v[184:187], v[62:65]
	v_mfma_f32_16x16x32_bf16 v[62:65], v[98:101], v[188:191], v[90:93]
	v_mfma_f32_16x16x32_bf16 v[58:61], v[106:109], v[168:171], v[58:61]
	v_mfma_f32_16x16x32_bf16 v[168:171], v[106:109], v[192:195], v[62:65]
	v_mfma_f32_16x16x32_bf16 v[62:65], v[118:121], v[188:191], v[94:97]
	v_mfma_f32_16x16x32_bf16 v[172:175], v[208:211], v[192:195], v[62:65]
	s_setprio 0
	s_barrier
; #define LDA(dst, b, h)                                                                                     \
;   _Pragma("unroll") for (int m = 0; m < 4; ++m) _Pragma("unroll") for (int k = 0; k < 2; ++k) dst[m][k] = \
;       *reinterpret_cast<const bf16x8*>(shmc + aL + (((b) * 2 + (h)) * 16384 + (m * 2 + k) * 1024))
; #define LDB(dst, b, h)                                                                                     \
;   _Pragma("unroll") for (int n = 0; n < 2; ++n) _Pragma("unroll") for (int k = 0; k < 2; ++k) dst[n][k] = \
;       *reinterpret_cast<const bf16x8*>(shmc + bL + (((b) * 2 + (h)) * 16384 + (n * 2 + k) * 1024))
; #define WAIT_V(n) asm volatile("s_waitcnt vmcnt(" #n ")" ::: "memory")
; #define WAIT_L(n) asm volatile("s_waitcnt lgkmcnt(" #n ")" ::: "memory")
; #define BAR __builtin_amdgcn_s_barrier()
; template <int EPI>
; __device__ __forceinline__ void phase_gemm(const Params& p, const GemmDesc& d, char* shmc) {
;     ...
;     {
;       LDB(B0, 1, 0); LDA(At, 1, 0); WAIT_V(2); BAR; WAIT_L(0); MMA(0, 0, At, B0); BAR;
;       LDB(B1, 1, 1); WAIT_V(0); BAR; WAIT_L(0); MMA(0, 1, At, B1); BAR;
;       LDA(At, 1, 1); BAR; WAIT_L(0); MMA(1, 0, At, B0); MMA(1, 1, At, B1); BAR;
;     }
;     if (wr == 0) BAR;
	ds_read_b128 v[176:179], v130 offset:32768
	ds_read_b128 v[180:183], v130 offset:33792
	ds_read_b128 v[184:187], v130 offset:34816
	ds_read_b128 v[188:191], v130 offset:35840
	s_nop 0
	ds_read_b128 v[62:65], v141 offset:32768
	ds_read_b128 v[78:81], v141 offset:33792
	ds_read_b128 v[94:97], v141 offset:34816
	ds_read_b128 v[192:195], v141 offset:35840
	ds_read_b128 v[208:211], v141 offset:36864
	ds_read_b128 v[212:215], v141 offset:37888
	ds_read_b128 v[216:219], v141 offset:38912
	ds_read_b128 v[220:223], v141 offset:39936
	s_waitcnt vmcnt(2)
	s_barrier
	s_waitcnt lgkmcnt(0)
	s_setprio 1
	s_waitcnt lgkmcnt(0)
	v_mfma_f32_16x16x32_bf16 v[66:69], v[176:179], v[62:65], v[126:129]
	v_mfma_f32_16x16x32_bf16 v[126:129], v[180:183], v[78:81], v[66:69]
	v_mfma_f32_16x16x32_bf16 v[66:69], v[184:187], v[62:65], v[122:125]
	v_mfma_f32_16x16x32_bf16 v[118:121], v[188:191], v[78:81], v[66:69]
	v_mfma_f32_16x16x32_bf16 v[66:69], v[176:179], v[94:97], v[196:199]
	v_mfma_f32_16x16x32_bf16 v[106:109], v[180:183], v[192:195], v[66:69]
	v_mfma_f32_16x16x32_bf16 v[66:69], v[184:187], v[94:97], v[114:117]
	v_mfma_f32_16x16x32_bf16 v[98:101], v[188:191], v[192:195], v[66:69]
	v_mfma_f32_16x16x32_bf16 v[66:69], v[176:179], v[208:211], v[110:113]
	v_mfma_f32_16x16x32_bf16 v[90:93], v[180:183], v[212:215], v[66:69]
	v_mfma_f32_16x16x32_bf16 v[66:69], v[184:187], v[208:211], v[200:203]
	v_mfma_f32_16x16x32_bf16 v[82:85], v[188:191], v[212:215], v[66:69]
	v_mfma_f32_16x16x32_bf16 v[66:69], v[176:179], v[216:219], v[102:105]
	v_mfma_f32_16x16x32_bf16 v[74:77], v[180:183], v[220:223], v[66:69]
	v_mfma_f32_16x16x32_bf16 v[66:69], v[184:187], v[216:219], v[204:207]
	v_mfma_f32_16x16x32_bf16 v[66:69], v[188:191], v[220:223], v[66:69]
	s_setprio 0
	s_barrier
	ds_read_b128 v[196:199], v130 offset:49152
	ds_read_b128 v[200:203], v130 offset:50176
	ds_read_b128 v[204:207], v130 offset:51200
	ds_read_b128 v[224:227], v130 offset:52224
	s_waitcnt vmcnt(0)
	s_barrier
	s_waitcnt lgkmcnt(0)
	s_setprio 1
	s_waitcnt lgkmcnt(0)
	v_mfma_f32_16x16x32_bf16 v[86:89], v[196:199], v[62:65], v[86:89]
	v_mfma_f32_16x16x32_bf16 v[62:65], v[204:207], v[62:65], v[70:73]
	v_mfma_f32_16x16x32_bf16 v[54:57], v[196:199], v[94:97], v[54:57]
	v_mfma_f32_16x16x32_bf16 v[50:53], v[204:207], v[94:97], v[50:53]
	v_mfma_f32_16x16x32_bf16 v[46:49], v[196:199], v[208:211], v[46:49]
	v_mfma_f32_16x16x32_bf16 v[42:45], v[204:207], v[208:211], v[42:45]
	v_mfma_f32_16x16x32_bf16 v[38:41], v[196:199], v[216:219], v[38:41]
	v_mfma_f32_16x16x32_bf16 v[34:37], v[204:207], v[216:219], v[34:37]
	v_mfma_f32_16x16x32_bf16 v[122:125], v[200:203], v[78:81], v[86:89]
	v_mfma_f32_16x16x32_bf16 v[114:117], v[224:227], v[78:81], v[62:65]
	v_mfma_f32_16x16x32_bf16 v[110:113], v[200:203], v[192:195], v[54:57]
	v_mfma_f32_16x16x32_bf16 v[102:105], v[224:227], v[192:195], v[50:53]
	v_mfma_f32_16x16x32_bf16 v[94:97], v[200:203], v[212:215], v[46:49]
	v_mfma_f32_16x16x32_bf16 v[86:89], v[224:227], v[212:215], v[42:45]
	v_mfma_f32_16x16x32_bf16 v[78:81], v[200:203], v[220:223], v[38:41]
	v_mfma_f32_16x16x32_bf16 v[70:73], v[224:227], v[220:223], v[34:37]
	s_setprio 0
	s_barrier
	s_nop 0
	ds_read_b128 v[34:37], v141 offset:49152
	ds_read_b128 v[42:45], v141 offset:50176
	ds_read_b128 v[192:195], v141 offset:51200
	ds_read_b128 v[208:211], v141 offset:52224
	ds_read_b128 v[212:215], v141 offset:53248
	ds_read_b128 v[216:219], v141 offset:54272
	ds_read_b128 v[220:223], v141 offset:55296
	ds_read_b128 v[228:231], v141 offset:56320
	s_barrier
	s_waitcnt lgkmcnt(0)
	s_setprio 1
	s_waitcnt lgkmcnt(0)
	v_mfma_f32_16x16x32_bf16 v[30:33], v[176:179], v[34:37], v[30:33]
	v_mfma_f32_16x16x32_bf16 v[26:29], v[184:187], v[34:37], v[26:29]
	v_mfma_f32_16x16x32_bf16 v[22:25], v[176:179], v[192:195], v[22:25]
	v_mfma_f32_16x16x32_bf16 v[18:21], v[184:187], v[192:195], v[18:21]
	v_mfma_f32_16x16x32_bf16 v[14:17], v[176:179], v[212:215], v[14:17]
	v_mfma_f32_16x16x32_bf16 v[10:13], v[184:187], v[212:215], v[10:13]
	v_mfma_f32_16x16x32_bf16 v[6:9], v[176:179], v[220:223], v[6:9]
	v_mfma_f32_16x16x32_bf16 v[2:5], v[184:187], v[220:223], v[2:5]
	v_mfma_f32_16x16x32_bf16 v[62:65], v[180:183], v[42:45], v[30:33]
	v_mfma_f32_16x16x32_bf16 v[54:57], v[188:191], v[42:45], v[26:29]
	v_mfma_f32_16x16x32_bf16 v[46:49], v[180:183], v[208:211], v[22:25]
	v_mfma_f32_16x16x32_bf16 v[38:41], v[188:191], v[208:211], v[18:21]
	v_mfma_f32_16x16x32_bf16 v[30:33], v[180:183], v[216:219], v[14:17]
	v_mfma_f32_16x16x32_bf16 v[22:25], v[188:191], v[216:219], v[10:13]
	v_mfma_f32_16x16x32_bf16 v[14:17], v[180:183], v[228:231], v[6:9]
	v_mfma_f32_16x16x32_bf16 v[6:9], v[188:191], v[228:231], v[2:5]
	s_setprio 0
	s_setprio 1
	v_mfma_f32_16x16x32_bf16 v[2:5], v[196:199], v[34:37], v[58:61]
	v_mfma_f32_16x16x32_bf16 v[58:61], v[200:203], v[42:45], v[2:5]
	v_mfma_f32_16x16x32_bf16 v[2:5], v[204:207], v[34:37], v[144:147]
	v_mfma_f32_16x16x32_bf16 v[50:53], v[224:227], v[42:45], v[2:5]
	v_mfma_f32_16x16x32_bf16 v[2:5], v[196:199], v[192:195], v[148:151]
	v_mfma_f32_16x16x32_bf16 v[42:45], v[200:203], v[208:211], v[2:5]
	v_mfma_f32_16x16x32_bf16 v[2:5], v[204:207], v[192:195], v[156:159]
	v_mfma_f32_16x16x32_bf16 v[34:37], v[224:227], v[208:211], v[2:5]
	v_mfma_f32_16x16x32_bf16 v[2:5], v[196:199], v[212:215], v[160:163]
	v_mfma_f32_16x16x32_bf16 v[26:29], v[200:203], v[216:219], v[2:5]
	v_mfma_f32_16x16x32_bf16 v[2:5], v[204:207], v[212:215], v[164:167]
	v_mfma_f32_16x16x32_bf16 v[18:21], v[224:227], v[216:219], v[2:5]
	v_mfma_f32_16x16x32_bf16 v[2:5], v[196:199], v[220:223], v[168:171]
	v_mfma_f32_16x16x32_bf16 v[10:13], v[200:203], v[228:231], v[2:5]
	v_mfma_f32_16x16x32_bf16 v[2:5], v[204:207], v[220:223], v[172:175]
	v_mfma_f32_16x16x32_bf16 v[2:5], v[224:227], v[228:231], v[2:5]
	s_setprio 0
	s_barrier
	s_and_saveexec_b64 s[38:39], s[4:5]
	s_cbranch_execz .LBB0_1315
	s_barrier
